# K-loop: dup lgkmcnt wait and setprio 0/1 pair deleted; setprio moved outside the MFMA segment's barriers
# speedup vs baseline: 1.0057x; 1.0057x over previous
.LBB0_556:
	ds_read_b128 v[0:3], v211
	ds_read_b128 v[4:7], v211 offset:1024
	ds_read_b128 v[8:11], v211 offset:2048
	ds_read_b128 v[12:15], v211 offset:3072
	ds_read_b128 v[144:147], v212
	ds_read_b128 v[170:173], v212 offset:1024
	ds_read_b128 v[174:177], v212 offset:2048
	ds_read_b128 v[178:181], v212 offset:3072
	s_add_u32 s8, s6, 0xfff80080
	s_addc_u32 s9, s7, -1
	s_cmp_eq_u32 s61, 28
	s_cselect_b32 s11, s55, s9
	s_cselect_b32 s10, s54, s8
	s_cselect_b32 s9, s57, s60
	s_cselect_b32 s8, s56, s5
	v_lshl_add_u64 v[230:231], s[6:7], 0, v[162:163]
	s_add_i32 m0, s17, 0xc000
	ds_read_b128 v[182:185], v213
	ds_read_b128 v[186:189], v213 offset:1024
	ds_read_b128 v[190:193], v213 offset:2048
	ds_read_b128 v[194:197], v213 offset:3072
	ds_read_b128 v[198:201], v213 offset:4096
	ds_read_b128 v[218:221], v213 offset:5120
	ds_read_b128 v[222:225], v213 offset:6144
	ds_read_b128 v[226:229], v213 offset:7168
	global_load_lds_dwordx4 v[230:231], off
	v_lshl_add_u64 v[230:231], s[6:7], 0, v[160:161]
	s_add_i32 m0, s17, 0xe000
	s_nop 0
	global_load_lds_dwordx4 v[230:231], off
	s_waitcnt vmcnt(8)
	s_waitcnt lgkmcnt(0)
	s_setprio 1
	s_barrier
	v_mfma_f32_16x16x32_bf16 v[92:95], v[0:3], v[182:185], v[92:95]
	v_mfma_f32_16x16x32_bf16 v[88:91], v[8:11], v[182:185], v[88:91]
	v_mfma_f32_16x16x32_bf16 v[116:119], v[0:3], v[190:193], v[116:119]
	v_mfma_f32_16x16x32_bf16 v[108:111], v[8:11], v[190:193], v[108:111]
	v_mfma_f32_16x16x32_bf16 v[124:127], v[0:3], v[198:201], v[124:127]
	v_mfma_f32_16x16x32_bf16 v[120:123], v[8:11], v[198:201], v[120:123]
	v_mfma_f32_16x16x32_bf16 v[100:103], v[0:3], v[222:225], v[100:103]
	v_mfma_f32_16x16x32_bf16 v[96:99], v[8:11], v[222:225], v[96:99]
	v_mfma_f32_16x16x32_bf16 v[92:95], v[4:7], v[186:189], v[92:95]
	v_mfma_f32_16x16x32_bf16 v[88:91], v[12:15], v[186:189], v[88:91]
	v_mfma_f32_16x16x32_bf16 v[116:119], v[4:7], v[194:197], v[116:119]
	v_mfma_f32_16x16x32_bf16 v[108:111], v[12:15], v[194:197], v[108:111]
	v_mfma_f32_16x16x32_bf16 v[124:127], v[4:7], v[218:221], v[124:127]
	v_mfma_f32_16x16x32_bf16 v[120:123], v[12:15], v[218:221], v[120:123]
	v_mfma_f32_16x16x32_bf16 v[100:103], v[4:7], v[226:229], v[100:103]
	v_mfma_f32_16x16x32_bf16 v[96:99], v[12:15], v[226:229], v[96:99]
	v_mfma_f32_16x16x32_bf16 v[140:143], v[144:147], v[182:185], v[140:143]
	v_mfma_f32_16x16x32_bf16 v[136:139], v[174:177], v[182:185], v[136:139]
	v_mfma_f32_16x16x32_bf16 v[132:135], v[144:147], v[190:193], v[132:135]
	v_mfma_f32_16x16x32_bf16 v[128:131], v[174:177], v[190:193], v[128:131]
	v_mfma_f32_16x16x32_bf16 v[112:115], v[144:147], v[198:201], v[112:115]
	v_mfma_f32_16x16x32_bf16 v[104:107], v[174:177], v[198:201], v[104:107]
	v_mfma_f32_16x16x32_bf16 v[84:87], v[144:147], v[222:225], v[84:87]
	v_mfma_f32_16x16x32_bf16 v[80:83], v[174:177], v[222:225], v[80:83]
	v_mfma_f32_16x16x32_bf16 v[140:143], v[170:173], v[186:189], v[140:143]
	v_mfma_f32_16x16x32_bf16 v[136:139], v[178:181], v[186:189], v[136:139]
	v_mfma_f32_16x16x32_bf16 v[132:135], v[170:173], v[194:197], v[132:135]
	v_mfma_f32_16x16x32_bf16 v[128:131], v[178:181], v[194:197], v[128:131]
	v_mfma_f32_16x16x32_bf16 v[112:115], v[170:173], v[218:221], v[112:115]
	v_mfma_f32_16x16x32_bf16 v[104:107], v[178:181], v[218:221], v[104:107]
	v_mfma_f32_16x16x32_bf16 v[84:87], v[170:173], v[226:229], v[84:87]
	v_mfma_f32_16x16x32_bf16 v[80:83], v[178:181], v[226:229], v[80:83]
	s_barrier
	s_setprio 0
	s_add_i32 s62, s77, s23
	v_lshl_add_u64 v[230:231], s[8:9], 0, v[150:151]
	s_mov_b32 m0, s62
	ds_read_b128 v[182:185], v213 offset:16384
	ds_read_b128 v[186:189], v213 offset:17408
	ds_read_b128 v[190:193], v213 offset:18432
	ds_read_b128 v[194:197], v213 offset:19456
	ds_read_b128 v[198:201], v213 offset:20480
	ds_read_b128 v[218:221], v213 offset:21504
	ds_read_b128 v[222:225], v213 offset:22528
	ds_read_b128 v[226:229], v213 offset:23552
	global_load_lds_dwordx4 v[230:231], off
	s_add_i32 m0, s62, 0x2000
	s_add_u32 s62, s8, 0x80000
	v_lshl_add_u64 v[232:233], s[8:9], 0, v[154:155]
	s_addc_u32 s63, s9, 0
	s_add_i32 s92, s78, s23
	global_load_lds_dwordx4 v[232:233], off
	v_lshl_add_u64 v[234:235], s[62:63], 0, v[150:151]
	s_mov_b32 m0, s92
	v_lshl_add_u64 v[236:237], s[10:11], 0, v[152:153]
	global_load_lds_dwordx4 v[234:235], off
	v_lshl_add_u64 v[234:235], s[62:63], 0, v[154:155]
	s_add_i32 m0, s92, 0x2000
	s_nop 0
	global_load_lds_dwordx4 v[234:235], off
	v_lshl_add_u64 v[234:235], s[10:11], 0, v[148:149]
	s_mov_b32 m0, s17
	s_nop 0
	global_load_lds_dwordx4 v[234:235], off
	s_mov_b32 m0, s53
	s_nop 0
	global_load_lds_dwordx4 v[236:237], off
	s_waitcnt vmcnt(8)
	s_waitcnt lgkmcnt(0)
	s_setprio 1
	s_barrier
	v_mfma_f32_16x16x32_bf16 v[76:79], v[0:3], v[182:185], v[76:79]
	v_mfma_f32_16x16x32_bf16 v[72:75], v[8:11], v[182:185], v[72:75]
	v_mfma_f32_16x16x32_bf16 v[60:63], v[0:3], v[190:193], v[60:63]
	v_mfma_f32_16x16x32_bf16 v[56:59], v[8:11], v[190:193], v[56:59]
	v_mfma_f32_16x16x32_bf16 v[44:47], v[0:3], v[198:201], v[44:47]
	v_mfma_f32_16x16x32_bf16 v[40:43], v[8:11], v[198:201], v[40:43]
	v_mfma_f32_16x16x32_bf16 v[0:3], v[0:3], v[222:225], v[28:31]
	v_mfma_f32_16x16x32_bf16 v[76:79], v[4:7], v[186:189], v[76:79]
	v_mfma_f32_16x16x32_bf16 v[72:75], v[12:15], v[186:189], v[72:75]
	v_mfma_f32_16x16x32_bf16 v[60:63], v[4:7], v[194:197], v[60:63]
	v_mfma_f32_16x16x32_bf16 v[56:59], v[12:15], v[194:197], v[56:59]
	v_mfma_f32_16x16x32_bf16 v[44:47], v[4:7], v[218:221], v[44:47]
	v_mfma_f32_16x16x32_bf16 v[40:43], v[12:15], v[218:221], v[40:43]
	v_mfma_f32_16x16x32_bf16 v[0:3], v[4:7], v[226:229], v[0:3]
	v_mfma_f32_16x16x32_bf16 v[4:7], v[8:11], v[222:225], v[20:23]
	v_mfma_f32_16x16x32_bf16 v[4:7], v[12:15], v[226:229], v[4:7]
	v_mfma_f32_16x16x32_bf16 v[20:23], v[144:147], v[190:193], v[52:55]
	v_mfma_f32_16x16x32_bf16 v[52:55], v[170:173], v[194:197], v[20:23]
	v_mfma_f32_16x16x32_bf16 v[20:23], v[174:177], v[190:193], v[48:51]
	v_mfma_f32_16x16x32_bf16 v[48:51], v[178:181], v[194:197], v[20:23]
	v_mfma_f32_16x16x32_bf16 v[20:23], v[144:147], v[198:201], v[36:39]
	v_mfma_f32_16x16x32_bf16 v[36:39], v[170:173], v[218:221], v[20:23]
	v_mfma_f32_16x16x32_bf16 v[20:23], v[174:177], v[198:201], v[32:35]
	v_mfma_f32_16x16x32_bf16 v[32:35], v[178:181], v[218:221], v[20:23]
	v_mfma_f32_16x16x32_bf16 v[20:23], v[144:147], v[222:225], v[24:27]
	v_mfma_f32_16x16x32_bf16 v[16:19], v[174:177], v[222:225], v[16:19]
	v_mfma_f32_16x16x32_bf16 v[8:11], v[144:147], v[182:185], v[68:71]
	v_mfma_f32_16x16x32_bf16 v[12:15], v[174:177], v[182:185], v[64:67]
	v_mfma_f32_16x16x32_bf16 v[24:27], v[170:173], v[226:229], v[20:23]
	v_mfma_f32_16x16x32_bf16 v[16:19], v[178:181], v[226:229], v[16:19]
	v_mfma_f32_16x16x32_bf16 v[8:11], v[170:173], v[186:189], v[8:11]
	v_mfma_f32_16x16x32_bf16 v[12:15], v[178:181], v[186:189], v[12:15]
	s_barrier
	s_setprio 0
	ds_read_b128 v[20:23], v214
	ds_read_b128 v[28:31], v214 offset:1024
	ds_read_b128 v[64:67], v214 offset:2048
	ds_read_b128 v[68:71], v214 offset:3072
	ds_read_b128 v[144:147], v215
	ds_read_b128 v[170:173], v215 offset:1024
	ds_read_b128 v[174:177], v215 offset:2048
	ds_read_b128 v[178:181], v215 offset:3072
	s_add_u32 s10, s10, 0x80000
	s_addc_u32 s11, s11, 0
	s_mov_b32 m0, s64
	v_lshl_add_u64 v[238:239], s[10:11], 0, v[148:149]
	ds_read_b128 v[182:185], v213 offset:32768
	ds_read_b128 v[186:189], v213 offset:33792
	ds_read_b128 v[190:193], v213 offset:34816
	ds_read_b128 v[194:197], v213 offset:35840
	ds_read_b128 v[198:201], v213 offset:36864
	ds_read_b128 v[218:221], v213 offset:37888
	ds_read_b128 v[222:225], v213 offset:38912
	ds_read_b128 v[226:229], v213 offset:39936
	global_load_lds_dwordx4 v[238:239], off
	v_lshl_add_u64 v[238:239], s[10:11], 0, v[152:153]
	s_mov_b32 m0, s65
	s_nop 0
	global_load_lds_dwordx4 v[238:239], off
	s_waitcnt vmcnt(8)
	s_waitcnt lgkmcnt(0)
	s_setprio 1
	s_barrier
	v_mfma_f32_16x16x32_bf16 v[92:95], v[20:23], v[182:185], v[92:95]
	v_mfma_f32_16x16x32_bf16 v[88:91], v[64:67], v[182:185], v[88:91]
	v_mfma_f32_16x16x32_bf16 v[116:119], v[20:23], v[190:193], v[116:119]
	v_mfma_f32_16x16x32_bf16 v[108:111], v[64:67], v[190:193], v[108:111]
	v_mfma_f32_16x16x32_bf16 v[124:127], v[20:23], v[198:201], v[124:127]
	v_mfma_f32_16x16x32_bf16 v[120:123], v[64:67], v[198:201], v[120:123]
	v_mfma_f32_16x16x32_bf16 v[100:103], v[20:23], v[222:225], v[100:103]
	v_mfma_f32_16x16x32_bf16 v[96:99], v[64:67], v[222:225], v[96:99]
	v_mfma_f32_16x16x32_bf16 v[92:95], v[28:31], v[186:189], v[92:95]
	v_mfma_f32_16x16x32_bf16 v[88:91], v[68:71], v[186:189], v[88:91]
	v_mfma_f32_16x16x32_bf16 v[116:119], v[28:31], v[194:197], v[116:119]
	v_mfma_f32_16x16x32_bf16 v[108:111], v[68:71], v[194:197], v[108:111]
	v_mfma_f32_16x16x32_bf16 v[124:127], v[28:31], v[218:221], v[124:127]
	v_mfma_f32_16x16x32_bf16 v[120:123], v[68:71], v[218:221], v[120:123]
	v_mfma_f32_16x16x32_bf16 v[100:103], v[28:31], v[226:229], v[100:103]
	v_mfma_f32_16x16x32_bf16 v[96:99], v[68:71], v[226:229], v[96:99]
	v_mfma_f32_16x16x32_bf16 v[140:143], v[144:147], v[182:185], v[140:143]
	v_mfma_f32_16x16x32_bf16 v[136:139], v[174:177], v[182:185], v[136:139]
	v_mfma_f32_16x16x32_bf16 v[132:135], v[144:147], v[190:193], v[132:135]
	v_mfma_f32_16x16x32_bf16 v[128:131], v[174:177], v[190:193], v[128:131]
	v_mfma_f32_16x16x32_bf16 v[112:115], v[144:147], v[198:201], v[112:115]
	v_mfma_f32_16x16x32_bf16 v[104:107], v[174:177], v[198:201], v[104:107]
	v_mfma_f32_16x16x32_bf16 v[84:87], v[144:147], v[222:225], v[84:87]
	v_mfma_f32_16x16x32_bf16 v[80:83], v[174:177], v[222:225], v[80:83]
	v_mfma_f32_16x16x32_bf16 v[140:143], v[170:173], v[186:189], v[140:143]
	v_mfma_f32_16x16x32_bf16 v[136:139], v[178:181], v[186:189], v[136:139]
	v_mfma_f32_16x16x32_bf16 v[132:135], v[170:173], v[194:197], v[132:135]
	v_mfma_f32_16x16x32_bf16 v[128:131], v[178:181], v[194:197], v[128:131]
	v_mfma_f32_16x16x32_bf16 v[112:115], v[170:173], v[218:221], v[112:115]
	v_mfma_f32_16x16x32_bf16 v[104:107], v[178:181], v[218:221], v[104:107]
	v_mfma_f32_16x16x32_bf16 v[84:87], v[170:173], v[226:229], v[84:87]
	v_mfma_f32_16x16x32_bf16 v[80:83], v[178:181], v[226:229], v[80:83]
	s_barrier
	s_setprio 0
	s_add_i32 s10, s80, s23
	v_lshl_add_u64 v[230:231], v[230:231], 0, s[20:21]
	s_mov_b32 m0, s10
	ds_read_b128 v[182:185], v213 offset:49152
	ds_read_b128 v[186:189], v213 offset:50176
	ds_read_b128 v[190:193], v213 offset:51200
	ds_read_b128 v[194:197], v213 offset:52224
	ds_read_b128 v[198:201], v213 offset:53248
	ds_read_b128 v[218:221], v213 offset:54272
	ds_read_b128 v[222:225], v213 offset:55296
	ds_read_b128 v[226:229], v213 offset:56320
	global_load_lds_dwordx4 v[230:231], off
	s_add_i32 m0, s10, 0x2000
	s_add_u32 s8, s8, 0x80080
	v_lshl_add_u64 v[230:231], v[232:233], 0, s[20:21]
	s_addc_u32 s9, s9, 0
	s_add_i32 s10, s81, s23
	global_load_lds_dwordx4 v[230:231], off
	v_lshl_add_u64 v[230:231], s[8:9], 0, v[150:151]
	s_mov_b32 m0, s10
	s_nop 0
	global_load_lds_dwordx4 v[230:231], off
	v_lshl_add_u64 v[230:231], s[8:9], 0, v[154:155]
	s_add_i32 m0, s10, 0x2000
	s_nop 0
	global_load_lds_dwordx4 v[230:231], off
	v_lshl_add_u64 v[230:231], v[234:235], 0, s[20:21]
	s_mov_b32 m0, s66
	s_nop 0
	global_load_lds_dwordx4 v[230:231], off
	v_lshl_add_u64 v[230:231], v[236:237], 0, s[20:21]
	s_mov_b32 m0, s67
	s_nop 0
	global_load_lds_dwordx4 v[230:231], off
	s_waitcnt vmcnt(8)
	s_waitcnt lgkmcnt(0)
	s_setprio 1
	s_barrier
	v_mfma_f32_16x16x32_bf16 v[76:79], v[20:23], v[182:185], v[76:79]
	v_mfma_f32_16x16x32_bf16 v[60:63], v[20:23], v[190:193], v[60:63]
	v_mfma_f32_16x16x32_bf16 v[44:47], v[20:23], v[198:201], v[44:47]
	v_mfma_f32_16x16x32_bf16 v[0:3], v[20:23], v[222:225], v[0:3]
	v_mfma_f32_16x16x32_bf16 v[76:79], v[28:31], v[186:189], v[76:79]
	v_mfma_f32_16x16x32_bf16 v[72:75], v[64:67], v[182:185], v[72:75]
	v_mfma_f32_16x16x32_bf16 v[60:63], v[28:31], v[194:197], v[60:63]
	v_mfma_f32_16x16x32_bf16 v[56:59], v[64:67], v[190:193], v[56:59]
	v_mfma_f32_16x16x32_bf16 v[44:47], v[28:31], v[218:221], v[44:47]
	v_mfma_f32_16x16x32_bf16 v[40:43], v[64:67], v[198:201], v[40:43]
	v_mfma_f32_16x16x32_bf16 v[28:31], v[28:31], v[226:229], v[0:3]
	v_mfma_f32_16x16x32_bf16 v[0:3], v[64:67], v[222:225], v[4:7]
	v_mfma_f32_16x16x32_bf16 v[72:75], v[68:71], v[186:189], v[72:75]
	v_mfma_f32_16x16x32_bf16 v[56:59], v[68:71], v[194:197], v[56:59]
	v_mfma_f32_16x16x32_bf16 v[40:43], v[68:71], v[218:221], v[40:43]
	v_mfma_f32_16x16x32_bf16 v[20:23], v[68:71], v[226:229], v[0:3]
	v_mfma_f32_16x16x32_bf16 v[0:3], v[144:147], v[182:185], v[8:11]
	v_mfma_f32_16x16x32_bf16 v[68:71], v[170:173], v[186:189], v[0:3]
	v_mfma_f32_16x16x32_bf16 v[0:3], v[174:177], v[182:185], v[12:15]
	v_mfma_f32_16x16x32_bf16 v[64:67], v[178:181], v[186:189], v[0:3]
	v_mfma_f32_16x16x32_bf16 v[0:3], v[144:147], v[190:193], v[52:55]
	v_mfma_f32_16x16x32_bf16 v[52:55], v[170:173], v[194:197], v[0:3]
	v_mfma_f32_16x16x32_bf16 v[0:3], v[174:177], v[190:193], v[48:51]
	v_mfma_f32_16x16x32_bf16 v[48:51], v[178:181], v[194:197], v[0:3]
	v_mfma_f32_16x16x32_bf16 v[0:3], v[144:147], v[198:201], v[36:39]
	v_mfma_f32_16x16x32_bf16 v[36:39], v[170:173], v[218:221], v[0:3]
	v_mfma_f32_16x16x32_bf16 v[0:3], v[174:177], v[198:201], v[32:35]
	v_mfma_f32_16x16x32_bf16 v[32:35], v[178:181], v[218:221], v[0:3]
	v_mfma_f32_16x16x32_bf16 v[0:3], v[144:147], v[222:225], v[24:27]
	v_mfma_f32_16x16x32_bf16 v[24:27], v[170:173], v[226:229], v[0:3]
	v_mfma_f32_16x16x32_bf16 v[0:3], v[174:177], v[222:225], v[16:19]
	v_mfma_f32_16x16x32_bf16 v[16:19], v[178:181], v[226:229], v[0:3]
	s_barrier
	s_setprio 0
	s_add_i32 s61, s61, 2
	s_add_u32 s5, s5, 0x100
	s_addc_u32 s60, s60, 0
	s_add_u32 s6, s6, 0x100
	s_addc_u32 s7, s7, 0
	s_cmp_gt_u32 s61, 29
	s_cbranch_scc0 .LBB0_556
	s_and_b64 vcc, exec, s[34:35]
	s_cbranch_vccz .LBB0_559
	s_barrier

.LBB0_1778:
	s_or_b32 s42, s31, 1
	s_lshl_b64 s[92:93], s[42:43], 7
	s_add_i32 s42, s31, 2
	s_lshl_b64 vcc, s[42:43], 7
	s_add_u32 s40, s62, vcc_lo
	s_addc_u32 s41, s63, vcc_hi
	s_and_b64 s[72:73], s[70:71], exec
	s_cselect_b32 s73, s41, s57
	s_cselect_b32 s72, s40, s56
	s_add_u32 s40, s64, vcc_lo
	s_addc_u32 s41, s65, vcc_hi
	s_add_i32 s55, 0, 0x10000
	s_and_b64 s[70:71], s[70:71], exec
	s_cselect_b32 s71, s41, s59
	s_cselect_b32 s70, s40, s58
	s_add_i32 s40, 0, 0x14000
	v_add_u32_e32 v140, s55, v169
	v_add_u32_e32 v182, s40, v169
	ds_read_b128 v[128:131], v140
	ds_read_b128 v[132:135], v140 offset:1024
	ds_read_b128 v[136:139], v140 offset:2048
	ds_read_b128 v[140:143], v140 offset:3072
	ds_read_b128 v[160:163], v182
	ds_read_b128 v[174:177], v182 offset:1024
	ds_read_b128 v[178:181], v182 offset:2048
	ds_read_b128 v[182:185], v182 offset:3072
	s_add_u32 s41, s62, s92
	s_addc_u32 s61, s63, s93
	s_add_u32 s92, s41, 0x80000
	s_addc_u32 s93, s61, 0
	v_lshl_add_u64 v[202:203], s[92:93], 0, v[152:153]
	s_add_i32 m0, s7, 0xc000
	ds_read_b128 v[186:189], v173
	ds_read_b128 v[190:193], v173 offset:1024
	ds_read_b128 v[194:197], v173 offset:2048
	ds_read_b128 v[198:201], v173 offset:3072
	ds_read_b128 v[206:209], v173 offset:4096
	ds_read_b128 v[210:213], v173 offset:5120
	ds_read_b128 v[214:217], v173 offset:6144
	ds_read_b128 v[218:221], v173 offset:7168
	global_load_lds_dwordx4 v[202:203], off
	v_lshl_add_u64 v[202:203], s[92:93], 0, v[154:155]
	s_add_i32 m0, s7, 0xe000
	s_nop 0
	global_load_lds_dwordx4 v[202:203], off
	s_waitcnt vmcnt(8)
	s_waitcnt lgkmcnt(0)
	s_setprio 1
	s_barrier
	v_mfma_f32_16x16x32_bf16 v[124:127], v[128:131], v[186:189], v[124:127]
	v_mfma_f32_16x16x32_bf16 v[120:123], v[136:139], v[186:189], v[120:123]
	v_mfma_f32_16x16x32_bf16 v[108:111], v[128:131], v[194:197], v[108:111]
	v_mfma_f32_16x16x32_bf16 v[104:107], v[136:139], v[194:197], v[104:107]
	v_mfma_f32_16x16x32_bf16 v[92:95], v[128:131], v[206:209], v[92:95]
	v_mfma_f32_16x16x32_bf16 v[88:91], v[136:139], v[206:209], v[88:91]
	v_mfma_f32_16x16x32_bf16 v[76:79], v[128:131], v[214:217], v[76:79]
	v_mfma_f32_16x16x32_bf16 v[72:75], v[136:139], v[214:217], v[72:75]
	v_mfma_f32_16x16x32_bf16 v[124:127], v[132:135], v[190:193], v[124:127]
	v_mfma_f32_16x16x32_bf16 v[120:123], v[140:143], v[190:193], v[120:123]
	v_mfma_f32_16x16x32_bf16 v[108:111], v[132:135], v[198:201], v[108:111]
	v_mfma_f32_16x16x32_bf16 v[104:107], v[140:143], v[198:201], v[104:107]
	v_mfma_f32_16x16x32_bf16 v[92:95], v[132:135], v[210:213], v[92:95]
	v_mfma_f32_16x16x32_bf16 v[88:91], v[140:143], v[210:213], v[88:91]
	v_mfma_f32_16x16x32_bf16 v[76:79], v[132:135], v[218:221], v[76:79]
	v_mfma_f32_16x16x32_bf16 v[72:75], v[140:143], v[218:221], v[72:75]
	v_mfma_f32_16x16x32_bf16 v[116:119], v[160:163], v[186:189], v[116:119]
	v_mfma_f32_16x16x32_bf16 v[112:115], v[178:181], v[186:189], v[112:115]
	v_mfma_f32_16x16x32_bf16 v[100:103], v[160:163], v[194:197], v[100:103]
	v_mfma_f32_16x16x32_bf16 v[96:99], v[178:181], v[194:197], v[96:99]
	v_mfma_f32_16x16x32_bf16 v[84:87], v[160:163], v[206:209], v[84:87]
	v_mfma_f32_16x16x32_bf16 v[80:83], v[178:181], v[206:209], v[80:83]
	v_mfma_f32_16x16x32_bf16 v[68:71], v[160:163], v[214:217], v[68:71]
	v_mfma_f32_16x16x32_bf16 v[64:67], v[178:181], v[214:217], v[64:67]
	v_mfma_f32_16x16x32_bf16 v[116:119], v[174:177], v[190:193], v[116:119]
	v_mfma_f32_16x16x32_bf16 v[112:115], v[182:185], v[190:193], v[112:115]
	v_mfma_f32_16x16x32_bf16 v[100:103], v[174:177], v[198:201], v[100:103]
	v_mfma_f32_16x16x32_bf16 v[96:99], v[182:185], v[198:201], v[96:99]
	v_mfma_f32_16x16x32_bf16 v[84:87], v[174:177], v[210:213], v[84:87]
	v_mfma_f32_16x16x32_bf16 v[80:83], v[182:185], v[210:213], v[80:83]
	v_mfma_f32_16x16x32_bf16 v[68:71], v[174:177], v[218:221], v[68:71]
	v_mfma_f32_16x16x32_bf16 v[64:67], v[182:185], v[218:221], v[64:67]
	s_barrier
	s_setprio 0
	s_add_i32 s41, s55, s6
	v_lshl_add_u64 v[202:203], s[70:71], 0, v[144:145]
	s_mov_b32 m0, s41
	ds_read_b128 v[186:189], v173 offset:16384
	ds_read_b128 v[190:193], v173 offset:17408
	ds_read_b128 v[194:197], v173 offset:18432
	ds_read_b128 v[198:201], v173 offset:19456
	ds_read_b128 v[206:209], v173 offset:20480
	ds_read_b128 v[210:213], v173 offset:21504
	ds_read_b128 v[214:217], v173 offset:22528
	ds_read_b128 v[218:221], v173 offset:23552
	global_load_lds_dwordx4 v[202:203], off
	s_add_i32 m0, s41, 0x2000
	s_add_u32 s92, s70, 0x80000
	v_lshl_add_u64 v[222:223], s[70:71], 0, v[156:157]
	s_addc_u32 s93, s71, 0
	s_add_i32 s40, s40, s6
	global_load_lds_dwordx4 v[222:223], off
	v_lshl_add_u64 v[224:225], s[92:93], 0, v[144:145]
	s_mov_b32 m0, s40
	v_lshl_add_u64 v[226:227], s[72:73], 0, v[154:155]
	global_load_lds_dwordx4 v[224:225], off
	v_lshl_add_u64 v[224:225], s[92:93], 0, v[156:157]
	s_add_i32 m0, s40, 0x2000
	s_nop 0
	global_load_lds_dwordx4 v[224:225], off
	v_lshl_add_u64 v[224:225], s[72:73], 0, v[152:153]
	s_mov_b32 m0, s7
	s_nop 0
	global_load_lds_dwordx4 v[224:225], off
	s_mov_b32 m0, s8
	s_nop 0
	global_load_lds_dwordx4 v[226:227], off
	s_waitcnt vmcnt(8)
	s_waitcnt lgkmcnt(0)
	s_setprio 1
	s_barrier
	v_mfma_f32_16x16x32_bf16 v[60:63], v[128:131], v[186:189], v[60:63]
	v_mfma_f32_16x16x32_bf16 v[56:59], v[136:139], v[186:189], v[56:59]
	v_mfma_f32_16x16x32_bf16 v[44:47], v[128:131], v[194:197], v[44:47]
	v_mfma_f32_16x16x32_bf16 v[40:43], v[136:139], v[194:197], v[40:43]
	v_mfma_f32_16x16x32_bf16 v[24:27], v[128:131], v[206:209], v[24:27]
	v_mfma_f32_16x16x32_bf16 v[16:19], v[136:139], v[206:209], v[16:19]
	v_mfma_f32_16x16x32_bf16 v[4:7], v[128:131], v[214:217], v[4:7]
	v_mfma_f32_16x16x32_bf16 v[0:3], v[136:139], v[214:217], v[0:3]
	v_mfma_f32_16x16x32_bf16 v[60:63], v[132:135], v[190:193], v[60:63]
	v_mfma_f32_16x16x32_bf16 v[56:59], v[140:143], v[190:193], v[56:59]
	v_mfma_f32_16x16x32_bf16 v[44:47], v[132:135], v[198:201], v[44:47]
	v_mfma_f32_16x16x32_bf16 v[40:43], v[140:143], v[198:201], v[40:43]
	v_mfma_f32_16x16x32_bf16 v[24:27], v[132:135], v[210:213], v[24:27]
	v_mfma_f32_16x16x32_bf16 v[16:19], v[140:143], v[210:213], v[16:19]
	v_mfma_f32_16x16x32_bf16 v[4:7], v[132:135], v[218:221], v[4:7]
	v_mfma_f32_16x16x32_bf16 v[0:3], v[140:143], v[218:221], v[0:3]
	v_mfma_f32_16x16x32_bf16 v[52:55], v[160:163], v[186:189], v[52:55]
	v_mfma_f32_16x16x32_bf16 v[48:51], v[178:181], v[186:189], v[48:51]
	v_mfma_f32_16x16x32_bf16 v[28:31], v[160:163], v[194:197], v[28:31]
	v_mfma_f32_16x16x32_bf16 v[20:23], v[178:181], v[194:197], v[20:23]
	v_mfma_f32_16x16x32_bf16 v[32:35], v[160:163], v[206:209], v[32:35]
	v_mfma_f32_16x16x32_bf16 v[36:39], v[178:181], v[206:209], v[36:39]
	v_mfma_f32_16x16x32_bf16 v[8:11], v[160:163], v[214:217], v[8:11]
	v_mfma_f32_16x16x32_bf16 v[12:15], v[178:181], v[214:217], v[12:15]
	v_mfma_f32_16x16x32_bf16 v[52:55], v[174:177], v[190:193], v[52:55]
	v_mfma_f32_16x16x32_bf16 v[48:51], v[182:185], v[190:193], v[48:51]
	v_mfma_f32_16x16x32_bf16 v[28:31], v[174:177], v[198:201], v[28:31]
	v_mfma_f32_16x16x32_bf16 v[20:23], v[182:185], v[198:201], v[20:23]
	v_mfma_f32_16x16x32_bf16 v[32:35], v[174:177], v[210:213], v[32:35]
	v_mfma_f32_16x16x32_bf16 v[36:39], v[182:185], v[210:213], v[36:39]
	v_mfma_f32_16x16x32_bf16 v[8:11], v[174:177], v[218:221], v[8:11]
	v_mfma_f32_16x16x32_bf16 v[12:15], v[182:185], v[218:221], v[12:15]
	s_barrier
	s_setprio 0
	s_add_i32 s40, 0, 0x18000
	s_add_i32 s41, 0, 0x1c000
	v_add_u32_e32 v140, s40, v169
	v_add_u32_e32 v182, s41, v169
	ds_read_b128 v[128:131], v140
	ds_read_b128 v[132:135], v140 offset:1024
	ds_read_b128 v[136:139], v140 offset:2048
	ds_read_b128 v[140:143], v140 offset:3072
	ds_read_b128 v[160:163], v182
	ds_read_b128 v[174:177], v182 offset:1024
	ds_read_b128 v[178:181], v182 offset:2048
	ds_read_b128 v[182:185], v182 offset:3072
	s_add_u32 s72, s72, 0x80000
	s_addc_u32 s73, s73, 0
	s_mov_b32 m0, s9
	v_lshl_add_u64 v[228:229], s[72:73], 0, v[152:153]
	ds_read_b128 v[186:189], v173 offset:32768
	ds_read_b128 v[190:193], v173 offset:33792
	ds_read_b128 v[194:197], v173 offset:34816
	ds_read_b128 v[198:201], v173 offset:35840
	ds_read_b128 v[206:209], v173 offset:36864
	ds_read_b128 v[210:213], v173 offset:37888
	ds_read_b128 v[214:217], v173 offset:38912
	ds_read_b128 v[218:221], v173 offset:39936
	global_load_lds_dwordx4 v[228:229], off
	v_lshl_add_u64 v[228:229], s[72:73], 0, v[154:155]
	s_mov_b32 m0, s10
	s_nop 0
	global_load_lds_dwordx4 v[228:229], off
	s_waitcnt vmcnt(8)
	s_waitcnt lgkmcnt(0)
	s_setprio 1
	s_barrier
	v_mfma_f32_16x16x32_bf16 v[124:127], v[128:131], v[186:189], v[124:127]
	v_mfma_f32_16x16x32_bf16 v[120:123], v[136:139], v[186:189], v[120:123]
	v_mfma_f32_16x16x32_bf16 v[108:111], v[128:131], v[194:197], v[108:111]
	v_mfma_f32_16x16x32_bf16 v[104:107], v[136:139], v[194:197], v[104:107]
	v_mfma_f32_16x16x32_bf16 v[92:95], v[128:131], v[206:209], v[92:95]
	v_mfma_f32_16x16x32_bf16 v[88:91], v[136:139], v[206:209], v[88:91]
	v_mfma_f32_16x16x32_bf16 v[76:79], v[128:131], v[214:217], v[76:79]
	v_mfma_f32_16x16x32_bf16 v[72:75], v[136:139], v[214:217], v[72:75]
	v_mfma_f32_16x16x32_bf16 v[124:127], v[132:135], v[190:193], v[124:127]
	v_mfma_f32_16x16x32_bf16 v[120:123], v[140:143], v[190:193], v[120:123]
	v_mfma_f32_16x16x32_bf16 v[108:111], v[132:135], v[198:201], v[108:111]
	v_mfma_f32_16x16x32_bf16 v[104:107], v[140:143], v[198:201], v[104:107]
	v_mfma_f32_16x16x32_bf16 v[92:95], v[132:135], v[210:213], v[92:95]
	v_mfma_f32_16x16x32_bf16 v[88:91], v[140:143], v[210:213], v[88:91]
	v_mfma_f32_16x16x32_bf16 v[76:79], v[132:135], v[218:221], v[76:79]
	v_mfma_f32_16x16x32_bf16 v[72:75], v[140:143], v[218:221], v[72:75]
	v_mfma_f32_16x16x32_bf16 v[116:119], v[160:163], v[186:189], v[116:119]
	v_mfma_f32_16x16x32_bf16 v[112:115], v[178:181], v[186:189], v[112:115]
	v_mfma_f32_16x16x32_bf16 v[100:103], v[160:163], v[194:197], v[100:103]
	v_mfma_f32_16x16x32_bf16 v[96:99], v[178:181], v[194:197], v[96:99]
	v_mfma_f32_16x16x32_bf16 v[84:87], v[160:163], v[206:209], v[84:87]
	v_mfma_f32_16x16x32_bf16 v[80:83], v[178:181], v[206:209], v[80:83]
	v_mfma_f32_16x16x32_bf16 v[68:71], v[160:163], v[214:217], v[68:71]
	v_mfma_f32_16x16x32_bf16 v[64:67], v[178:181], v[214:217], v[64:67]
	v_mfma_f32_16x16x32_bf16 v[116:119], v[174:177], v[190:193], v[116:119]
	v_mfma_f32_16x16x32_bf16 v[112:115], v[182:185], v[190:193], v[112:115]
	v_mfma_f32_16x16x32_bf16 v[100:103], v[174:177], v[198:201], v[100:103]
	v_mfma_f32_16x16x32_bf16 v[96:99], v[182:185], v[198:201], v[96:99]
	v_mfma_f32_16x16x32_bf16 v[84:87], v[174:177], v[210:213], v[84:87]
	v_mfma_f32_16x16x32_bf16 v[80:83], v[182:185], v[210:213], v[80:83]
	v_mfma_f32_16x16x32_bf16 v[68:71], v[174:177], v[218:221], v[68:71]
	v_mfma_f32_16x16x32_bf16 v[64:67], v[182:185], v[218:221], v[64:67]
	s_barrier
	s_setprio 0
	s_add_i32 s40, s40, s6
	v_lshl_add_u64 v[202:203], v[202:203], 0, s[44:45]
	s_mov_b32 m0, s40
	ds_read_b128 v[186:189], v173 offset:49152
	ds_read_b128 v[190:193], v173 offset:50176
	ds_read_b128 v[194:197], v173 offset:51200
	ds_read_b128 v[198:201], v173 offset:52224
	ds_read_b128 v[206:209], v173 offset:53248
	ds_read_b128 v[210:213], v173 offset:54272
	ds_read_b128 v[214:217], v173 offset:55296
	ds_read_b128 v[218:221], v173 offset:56320
	global_load_lds_dwordx4 v[202:203], off
	s_add_i32 m0, s40, 0x2000
	s_add_u32 s70, s70, 0x80080
	v_lshl_add_u64 v[202:203], v[222:223], 0, s[44:45]
	s_addc_u32 s71, s71, 0
	s_add_i32 s40, s41, s6
	global_load_lds_dwordx4 v[202:203], off
	v_lshl_add_u64 v[202:203], s[70:71], 0, v[144:145]
	s_mov_b32 m0, s40
	s_nop 0
	global_load_lds_dwordx4 v[202:203], off
	v_lshl_add_u64 v[202:203], s[70:71], 0, v[156:157]
	s_add_i32 m0, s40, 0x2000
	s_nop 0
	global_load_lds_dwordx4 v[202:203], off
	v_lshl_add_u64 v[202:203], v[224:225], 0, s[44:45]
	s_mov_b32 m0, s11
	s_nop 0
	global_load_lds_dwordx4 v[202:203], off
	v_lshl_add_u64 v[202:203], v[226:227], 0, s[44:45]
	s_mov_b32 m0, s12
	s_nop 0
	global_load_lds_dwordx4 v[202:203], off
	s_waitcnt vmcnt(8)
	s_waitcnt lgkmcnt(0)
	s_setprio 1
	s_barrier
	v_mfma_f32_16x16x32_bf16 v[60:63], v[128:131], v[186:189], v[60:63]
	v_mfma_f32_16x16x32_bf16 v[56:59], v[136:139], v[186:189], v[56:59]
	v_mfma_f32_16x16x32_bf16 v[44:47], v[128:131], v[194:197], v[44:47]
	v_mfma_f32_16x16x32_bf16 v[40:43], v[136:139], v[194:197], v[40:43]
	v_mfma_f32_16x16x32_bf16 v[24:27], v[128:131], v[206:209], v[24:27]
	v_mfma_f32_16x16x32_bf16 v[16:19], v[136:139], v[206:209], v[16:19]
	v_mfma_f32_16x16x32_bf16 v[4:7], v[128:131], v[214:217], v[4:7]
	v_mfma_f32_16x16x32_bf16 v[0:3], v[136:139], v[214:217], v[0:3]
	v_mfma_f32_16x16x32_bf16 v[60:63], v[132:135], v[190:193], v[60:63]
	v_mfma_f32_16x16x32_bf16 v[56:59], v[140:143], v[190:193], v[56:59]
	v_mfma_f32_16x16x32_bf16 v[44:47], v[132:135], v[198:201], v[44:47]
	v_mfma_f32_16x16x32_bf16 v[40:43], v[140:143], v[198:201], v[40:43]
	v_mfma_f32_16x16x32_bf16 v[24:27], v[132:135], v[210:213], v[24:27]
	v_mfma_f32_16x16x32_bf16 v[16:19], v[140:143], v[210:213], v[16:19]
	v_mfma_f32_16x16x32_bf16 v[4:7], v[132:135], v[218:221], v[4:7]
	v_mfma_f32_16x16x32_bf16 v[0:3], v[140:143], v[218:221], v[0:3]
	v_mfma_f32_16x16x32_bf16 v[52:55], v[160:163], v[186:189], v[52:55]
	v_mfma_f32_16x16x32_bf16 v[48:51], v[178:181], v[186:189], v[48:51]
	v_mfma_f32_16x16x32_bf16 v[28:31], v[160:163], v[194:197], v[28:31]
	v_mfma_f32_16x16x32_bf16 v[20:23], v[178:181], v[194:197], v[20:23]
	v_mfma_f32_16x16x32_bf16 v[32:35], v[160:163], v[206:209], v[32:35]
	v_mfma_f32_16x16x32_bf16 v[36:39], v[178:181], v[206:209], v[36:39]
	v_mfma_f32_16x16x32_bf16 v[8:11], v[160:163], v[214:217], v[8:11]
	v_mfma_f32_16x16x32_bf16 v[12:15], v[178:181], v[214:217], v[12:15]
	v_mfma_f32_16x16x32_bf16 v[52:55], v[174:177], v[190:193], v[52:55]
	v_mfma_f32_16x16x32_bf16 v[48:51], v[182:185], v[190:193], v[48:51]
	v_mfma_f32_16x16x32_bf16 v[28:31], v[174:177], v[198:201], v[28:31]
	v_mfma_f32_16x16x32_bf16 v[20:23], v[182:185], v[198:201], v[20:23]
	v_mfma_f32_16x16x32_bf16 v[32:35], v[174:177], v[210:213], v[32:35]
	v_mfma_f32_16x16x32_bf16 v[36:39], v[182:185], v[210:213], v[36:39]
	v_mfma_f32_16x16x32_bf16 v[8:11], v[174:177], v[218:221], v[8:11]
	v_mfma_f32_16x16x32_bf16 v[12:15], v[182:185], v[218:221], v[12:15]
	s_barrier
	s_setprio 0
	s_cmp_gt_u32 s31, 29
	s_cbranch_scc1 .LBB0_1780
	s_mov_b32 s31, s42
	s_branch .LBB0_1766

.LBB0_1933:
	s_add_i32 s77, s26, 2
	s_add_u32 s92, s22, 0x80
	s_addc_u32 s27, s23, 0
	s_add_i32 s40, 0, 0x10000
	s_cmp_eq_u32 s73, s26
	s_cselect_b32 s27, s36, s27
	s_cselect_b32 s26, s37, s92
	s_cselect_b32 s93, s42, vcc_hi
	s_cselect_b32 s92, s61, vcc_lo
	s_add_i32 s41, 0, 0x14000
	v_add_u32_e32 v158, s40, v168
	v_add_u32_e32 v162, s41, v168
	ds_read_b128 v[128:131], v158
	ds_read_b128 v[132:135], v158 offset:1024
	ds_read_b128 v[154:157], v158 offset:2048
	ds_read_b128 v[158:161], v158 offset:3072
	ds_read_b128 v[172:175], v162
	ds_read_b128 v[176:179], v162 offset:1024
	ds_read_b128 v[180:183], v162 offset:2048
	ds_read_b128 v[184:187], v162 offset:3072
	v_lshl_add_u64 v[162:163], s[22:23], 0, v[152:153]
	s_add_i32 m0, s12, 0xc000
	ds_read_b128 v[188:191], v171
	ds_read_b128 v[192:195], v171 offset:1024
	ds_read_b128 v[196:199], v171 offset:2048
	ds_read_b128 v[200:203], v171 offset:3072
	ds_read_b128 v[206:209], v171 offset:4096
	ds_read_b128 v[210:213], v171 offset:5120
	ds_read_b128 v[214:217], v171 offset:6144
	ds_read_b128 v[218:221], v171 offset:7168
	global_load_lds_dwordx4 v[162:163], off
	v_lshl_add_u64 v[162:163], s[22:23], 0, v[142:143]
	s_add_i32 m0, s12, 0xe000
	s_nop 0
	global_load_lds_dwordx4 v[162:163], off
	s_waitcnt vmcnt(8)
	s_waitcnt lgkmcnt(0)
	s_setprio 1
	s_barrier
	v_mfma_f32_16x16x32_bf16 v[124:127], v[128:131], v[188:191], v[124:127]
	v_mfma_f32_16x16x32_bf16 v[120:123], v[154:157], v[188:191], v[120:123]
	v_mfma_f32_16x16x32_bf16 v[108:111], v[128:131], v[196:199], v[108:111]
	v_mfma_f32_16x16x32_bf16 v[104:107], v[154:157], v[196:199], v[104:107]
	v_mfma_f32_16x16x32_bf16 v[92:95], v[128:131], v[206:209], v[92:95]
	v_mfma_f32_16x16x32_bf16 v[88:91], v[154:157], v[206:209], v[88:91]
	v_mfma_f32_16x16x32_bf16 v[76:79], v[128:131], v[214:217], v[76:79]
	v_mfma_f32_16x16x32_bf16 v[72:75], v[154:157], v[214:217], v[72:75]
	v_mfma_f32_16x16x32_bf16 v[124:127], v[132:135], v[192:195], v[124:127]
	v_mfma_f32_16x16x32_bf16 v[120:123], v[158:161], v[192:195], v[120:123]
	v_mfma_f32_16x16x32_bf16 v[108:111], v[132:135], v[200:203], v[108:111]
	v_mfma_f32_16x16x32_bf16 v[104:107], v[158:161], v[200:203], v[104:107]
	v_mfma_f32_16x16x32_bf16 v[92:95], v[132:135], v[210:213], v[92:95]
	v_mfma_f32_16x16x32_bf16 v[88:91], v[158:161], v[210:213], v[88:91]
	v_mfma_f32_16x16x32_bf16 v[76:79], v[132:135], v[218:221], v[76:79]
	v_mfma_f32_16x16x32_bf16 v[72:75], v[158:161], v[218:221], v[72:75]
	v_mfma_f32_16x16x32_bf16 v[116:119], v[172:175], v[188:191], v[116:119]
	v_mfma_f32_16x16x32_bf16 v[112:115], v[180:183], v[188:191], v[112:115]
	v_mfma_f32_16x16x32_bf16 v[100:103], v[172:175], v[196:199], v[100:103]
	v_mfma_f32_16x16x32_bf16 v[96:99], v[180:183], v[196:199], v[96:99]
	v_mfma_f32_16x16x32_bf16 v[84:87], v[172:175], v[206:209], v[84:87]
	v_mfma_f32_16x16x32_bf16 v[80:83], v[180:183], v[206:209], v[80:83]
	v_mfma_f32_16x16x32_bf16 v[68:71], v[172:175], v[214:217], v[68:71]
	v_mfma_f32_16x16x32_bf16 v[64:67], v[180:183], v[214:217], v[64:67]
	v_mfma_f32_16x16x32_bf16 v[116:119], v[176:179], v[192:195], v[116:119]
	v_mfma_f32_16x16x32_bf16 v[112:115], v[184:187], v[192:195], v[112:115]
	v_mfma_f32_16x16x32_bf16 v[100:103], v[176:179], v[200:203], v[100:103]
	v_mfma_f32_16x16x32_bf16 v[96:99], v[184:187], v[200:203], v[96:99]
	v_mfma_f32_16x16x32_bf16 v[84:87], v[176:179], v[210:213], v[84:87]
	v_mfma_f32_16x16x32_bf16 v[80:83], v[184:187], v[210:213], v[80:83]
	v_mfma_f32_16x16x32_bf16 v[68:71], v[176:179], v[218:221], v[68:71]
	v_mfma_f32_16x16x32_bf16 v[64:67], v[184:187], v[218:221], v[64:67]
	s_barrier
	s_setprio 0
	s_add_i32 s40, s40, s11
	v_lshl_add_u64 v[162:163], s[92:93], 0, v[144:145]
	s_mov_b32 m0, s40
	ds_read_b128 v[188:191], v171 offset:16384
	ds_read_b128 v[192:195], v171 offset:17408
	ds_read_b128 v[196:199], v171 offset:18432
	ds_read_b128 v[200:203], v171 offset:19456
	ds_read_b128 v[206:209], v171 offset:20480
	ds_read_b128 v[210:213], v171 offset:21504
	ds_read_b128 v[214:217], v171 offset:22528
	ds_read_b128 v[218:221], v171 offset:23552
	global_load_lds_dwordx4 v[162:163], off
	s_add_i32 m0, s40, 0x2000
	v_lshl_add_u64 v[222:223], s[92:93], 0, v[140:141]
	s_add_u32 s92, s92, s48
	s_addc_u32 s93, s93, 0
	s_add_i32 s40, s41, s11
	global_load_lds_dwordx4 v[222:223], off
	v_lshl_add_u64 v[224:225], s[92:93], 0, v[144:145]
	s_mov_b32 m0, s40
	v_lshl_add_u64 v[226:227], s[92:93], 0, v[140:141]
	global_load_lds_dwordx4 v[224:225], off
	s_add_i32 m0, s40, 0x2000
	v_lshl_add_u64 v[228:229], s[26:27], 0, v[136:137]
	global_load_lds_dwordx4 v[226:227], off
	s_mov_b32 m0, s12
	v_lshl_add_u64 v[230:231], s[26:27], 0, v[138:139]
	global_load_lds_dwordx4 v[228:229], off
	s_mov_b32 m0, s13
	s_nop 0
	global_load_lds_dwordx4 v[230:231], off
	s_waitcnt vmcnt(8)
	s_waitcnt lgkmcnt(0)
	s_setprio 1
	s_barrier
	v_mfma_f32_16x16x32_bf16 v[60:63], v[128:131], v[188:191], v[60:63]
	v_mfma_f32_16x16x32_bf16 v[56:59], v[154:157], v[188:191], v[56:59]
	v_mfma_f32_16x16x32_bf16 v[44:47], v[128:131], v[196:199], v[44:47]
	v_mfma_f32_16x16x32_bf16 v[40:43], v[154:157], v[196:199], v[40:43]
	v_mfma_f32_16x16x32_bf16 v[28:31], v[128:131], v[206:209], v[28:31]
	v_mfma_f32_16x16x32_bf16 v[24:27], v[154:157], v[206:209], v[24:27]
	v_mfma_f32_16x16x32_bf16 v[12:15], v[128:131], v[214:217], v[12:15]
	v_mfma_f32_16x16x32_bf16 v[8:11], v[154:157], v[214:217], v[8:11]
	v_mfma_f32_16x16x32_bf16 v[60:63], v[132:135], v[192:195], v[60:63]
	v_mfma_f32_16x16x32_bf16 v[56:59], v[158:161], v[192:195], v[56:59]
	v_mfma_f32_16x16x32_bf16 v[44:47], v[132:135], v[200:203], v[44:47]
	v_mfma_f32_16x16x32_bf16 v[40:43], v[158:161], v[200:203], v[40:43]
	v_mfma_f32_16x16x32_bf16 v[28:31], v[132:135], v[210:213], v[28:31]
	v_mfma_f32_16x16x32_bf16 v[24:27], v[158:161], v[210:213], v[24:27]
	v_mfma_f32_16x16x32_bf16 v[12:15], v[132:135], v[218:221], v[12:15]
	v_mfma_f32_16x16x32_bf16 v[8:11], v[158:161], v[218:221], v[8:11]
	v_mfma_f32_16x16x32_bf16 v[52:55], v[172:175], v[188:191], v[52:55]
	v_mfma_f32_16x16x32_bf16 v[48:51], v[180:183], v[188:191], v[48:51]
	v_mfma_f32_16x16x32_bf16 v[36:39], v[172:175], v[196:199], v[36:39]
	v_mfma_f32_16x16x32_bf16 v[32:35], v[180:183], v[196:199], v[32:35]
	v_mfma_f32_16x16x32_bf16 v[20:23], v[172:175], v[206:209], v[20:23]
	v_mfma_f32_16x16x32_bf16 v[16:19], v[180:183], v[206:209], v[16:19]
	v_mfma_f32_16x16x32_bf16 v[4:7], v[172:175], v[214:217], v[4:7]
	v_mfma_f32_16x16x32_bf16 v[0:3], v[180:183], v[214:217], v[0:3]
	v_mfma_f32_16x16x32_bf16 v[52:55], v[176:179], v[192:195], v[52:55]
	v_mfma_f32_16x16x32_bf16 v[48:51], v[184:187], v[192:195], v[48:51]
	v_mfma_f32_16x16x32_bf16 v[36:39], v[176:179], v[200:203], v[36:39]
	v_mfma_f32_16x16x32_bf16 v[32:35], v[184:187], v[200:203], v[32:35]
	v_mfma_f32_16x16x32_bf16 v[20:23], v[176:179], v[210:213], v[20:23]
	v_mfma_f32_16x16x32_bf16 v[16:19], v[184:187], v[210:213], v[16:19]
	v_mfma_f32_16x16x32_bf16 v[4:7], v[176:179], v[218:221], v[4:7]
	v_mfma_f32_16x16x32_bf16 v[0:3], v[184:187], v[218:221], v[0:3]
	s_barrier
	s_setprio 0
	s_add_i32 s40, 0, 0x18000
	s_add_i32 s41, 0, 0x1c000
	v_add_u32_e32 v158, s40, v168
	v_add_u32_e32 v184, s41, v168
	ds_read_b128 v[128:131], v158
	ds_read_b128 v[132:135], v158 offset:1024
	ds_read_b128 v[154:157], v158 offset:2048
	ds_read_b128 v[158:161], v158 offset:3072
	ds_read_b128 v[172:175], v184
	ds_read_b128 v[176:179], v184 offset:1024
	ds_read_b128 v[180:183], v184 offset:2048
	ds_read_b128 v[184:187], v184 offset:3072
	s_add_u32 s26, s26, s48
	s_addc_u32 s27, s27, 0
	s_mov_b32 m0, s28
	v_lshl_add_u64 v[232:233], s[26:27], 0, v[136:137]
	ds_read_b128 v[188:191], v171 offset:32768
	ds_read_b128 v[192:195], v171 offset:33792
	ds_read_b128 v[196:199], v171 offset:34816
	ds_read_b128 v[200:203], v171 offset:35840
	ds_read_b128 v[206:209], v171 offset:36864
	ds_read_b128 v[210:213], v171 offset:37888
	ds_read_b128 v[214:217], v171 offset:38912
	ds_read_b128 v[218:221], v171 offset:39936
	global_load_lds_dwordx4 v[232:233], off
	v_lshl_add_u64 v[232:233], s[26:27], 0, v[138:139]
	s_mov_b32 m0, s29
	s_nop 0
	global_load_lds_dwordx4 v[232:233], off
	s_waitcnt vmcnt(8)
	s_waitcnt lgkmcnt(0)
	s_setprio 1
	s_barrier
	v_mfma_f32_16x16x32_bf16 v[124:127], v[128:131], v[188:191], v[124:127]
	v_mfma_f32_16x16x32_bf16 v[120:123], v[154:157], v[188:191], v[120:123]
	v_mfma_f32_16x16x32_bf16 v[108:111], v[128:131], v[196:199], v[108:111]
	v_mfma_f32_16x16x32_bf16 v[104:107], v[154:157], v[196:199], v[104:107]
	v_mfma_f32_16x16x32_bf16 v[92:95], v[128:131], v[206:209], v[92:95]
	v_mfma_f32_16x16x32_bf16 v[88:91], v[154:157], v[206:209], v[88:91]
	v_mfma_f32_16x16x32_bf16 v[76:79], v[128:131], v[214:217], v[76:79]
	v_mfma_f32_16x16x32_bf16 v[72:75], v[154:157], v[214:217], v[72:75]
	v_mfma_f32_16x16x32_bf16 v[124:127], v[132:135], v[192:195], v[124:127]
	v_mfma_f32_16x16x32_bf16 v[120:123], v[158:161], v[192:195], v[120:123]
	v_mfma_f32_16x16x32_bf16 v[108:111], v[132:135], v[200:203], v[108:111]
	v_mfma_f32_16x16x32_bf16 v[104:107], v[158:161], v[200:203], v[104:107]
	v_mfma_f32_16x16x32_bf16 v[92:95], v[132:135], v[210:213], v[92:95]
	v_mfma_f32_16x16x32_bf16 v[88:91], v[158:161], v[210:213], v[88:91]
	v_mfma_f32_16x16x32_bf16 v[76:79], v[132:135], v[218:221], v[76:79]
	v_mfma_f32_16x16x32_bf16 v[72:75], v[158:161], v[218:221], v[72:75]
	v_mfma_f32_16x16x32_bf16 v[116:119], v[172:175], v[188:191], v[116:119]
	v_mfma_f32_16x16x32_bf16 v[112:115], v[180:183], v[188:191], v[112:115]
	v_mfma_f32_16x16x32_bf16 v[100:103], v[172:175], v[196:199], v[100:103]
	v_mfma_f32_16x16x32_bf16 v[96:99], v[180:183], v[196:199], v[96:99]
	v_mfma_f32_16x16x32_bf16 v[84:87], v[172:175], v[206:209], v[84:87]
	v_mfma_f32_16x16x32_bf16 v[80:83], v[180:183], v[206:209], v[80:83]
	v_mfma_f32_16x16x32_bf16 v[68:71], v[172:175], v[214:217], v[68:71]
	v_mfma_f32_16x16x32_bf16 v[64:67], v[180:183], v[214:217], v[64:67]
	v_mfma_f32_16x16x32_bf16 v[116:119], v[176:179], v[192:195], v[116:119]
	v_mfma_f32_16x16x32_bf16 v[112:115], v[184:187], v[192:195], v[112:115]
	v_mfma_f32_16x16x32_bf16 v[100:103], v[176:179], v[200:203], v[100:103]
	v_mfma_f32_16x16x32_bf16 v[96:99], v[184:187], v[200:203], v[96:99]
	v_mfma_f32_16x16x32_bf16 v[84:87], v[176:179], v[210:213], v[84:87]
	v_mfma_f32_16x16x32_bf16 v[80:83], v[184:187], v[210:213], v[80:83]
	v_mfma_f32_16x16x32_bf16 v[68:71], v[176:179], v[218:221], v[68:71]
	v_mfma_f32_16x16x32_bf16 v[64:67], v[184:187], v[218:221], v[64:67]
	s_barrier
	s_setprio 0
	s_add_i32 s26, s40, s11
	v_lshl_add_u64 v[162:163], v[162:163], 0, s[44:45]
	s_mov_b32 m0, s26
	ds_read_b128 v[188:191], v171 offset:49152
	ds_read_b128 v[192:195], v171 offset:50176
	ds_read_b128 v[196:199], v171 offset:51200
	ds_read_b128 v[200:203], v171 offset:52224
	ds_read_b128 v[206:209], v171 offset:53248
	ds_read_b128 v[210:213], v171 offset:54272
	ds_read_b128 v[214:217], v171 offset:55296
	ds_read_b128 v[218:221], v171 offset:56320
	global_load_lds_dwordx4 v[162:163], off
	v_lshl_add_u64 v[162:163], v[222:223], 0, s[44:45]
	s_add_i32 m0, s26, 0x2000
	s_add_i32 s26, s41, s11
	global_load_lds_dwordx4 v[162:163], off
	v_lshl_add_u64 v[162:163], v[224:225], 0, s[44:45]
	s_mov_b32 m0, s26
	s_nop 0
	global_load_lds_dwordx4 v[162:163], off
	v_lshl_add_u64 v[162:163], v[226:227], 0, s[44:45]
	s_add_i32 m0, s26, 0x2000
	s_nop 0
	global_load_lds_dwordx4 v[162:163], off
	v_lshl_add_u64 v[162:163], v[228:229], 0, s[44:45]
	s_mov_b32 m0, s68
	s_nop 0
	global_load_lds_dwordx4 v[162:163], off
	v_lshl_add_u64 v[162:163], v[230:231], 0, s[44:45]
	s_mov_b32 m0, s69
	s_nop 0
	global_load_lds_dwordx4 v[162:163], off
	s_waitcnt vmcnt(8)
	s_waitcnt lgkmcnt(0)
	s_setprio 1
	s_barrier
	v_mfma_f32_16x16x32_bf16 v[60:63], v[128:131], v[188:191], v[60:63]
	v_mfma_f32_16x16x32_bf16 v[56:59], v[154:157], v[188:191], v[56:59]
	v_mfma_f32_16x16x32_bf16 v[44:47], v[128:131], v[196:199], v[44:47]
	v_mfma_f32_16x16x32_bf16 v[40:43], v[154:157], v[196:199], v[40:43]
	v_mfma_f32_16x16x32_bf16 v[28:31], v[128:131], v[206:209], v[28:31]
	v_mfma_f32_16x16x32_bf16 v[24:27], v[154:157], v[206:209], v[24:27]
	v_mfma_f32_16x16x32_bf16 v[12:15], v[128:131], v[214:217], v[12:15]
	v_mfma_f32_16x16x32_bf16 v[8:11], v[154:157], v[214:217], v[8:11]
	v_mfma_f32_16x16x32_bf16 v[60:63], v[132:135], v[192:195], v[60:63]
	v_mfma_f32_16x16x32_bf16 v[56:59], v[158:161], v[192:195], v[56:59]
	v_mfma_f32_16x16x32_bf16 v[44:47], v[132:135], v[200:203], v[44:47]
	v_mfma_f32_16x16x32_bf16 v[40:43], v[158:161], v[200:203], v[40:43]
	v_mfma_f32_16x16x32_bf16 v[28:31], v[132:135], v[210:213], v[28:31]
	v_mfma_f32_16x16x32_bf16 v[24:27], v[158:161], v[210:213], v[24:27]
	v_mfma_f32_16x16x32_bf16 v[12:15], v[132:135], v[218:221], v[12:15]
	v_mfma_f32_16x16x32_bf16 v[8:11], v[158:161], v[218:221], v[8:11]
	v_mfma_f32_16x16x32_bf16 v[52:55], v[172:175], v[188:191], v[52:55]
	v_mfma_f32_16x16x32_bf16 v[48:51], v[180:183], v[188:191], v[48:51]
	v_mfma_f32_16x16x32_bf16 v[36:39], v[172:175], v[196:199], v[36:39]
	v_mfma_f32_16x16x32_bf16 v[32:35], v[180:183], v[196:199], v[32:35]
	v_mfma_f32_16x16x32_bf16 v[20:23], v[172:175], v[206:209], v[20:23]
	v_mfma_f32_16x16x32_bf16 v[16:19], v[180:183], v[206:209], v[16:19]
	v_mfma_f32_16x16x32_bf16 v[4:7], v[172:175], v[214:217], v[4:7]
	v_mfma_f32_16x16x32_bf16 v[0:3], v[180:183], v[214:217], v[0:3]
	v_mfma_f32_16x16x32_bf16 v[52:55], v[176:179], v[192:195], v[52:55]
	v_mfma_f32_16x16x32_bf16 v[48:51], v[184:187], v[192:195], v[48:51]
	v_mfma_f32_16x16x32_bf16 v[36:39], v[176:179], v[200:203], v[36:39]
	v_mfma_f32_16x16x32_bf16 v[32:35], v[184:187], v[200:203], v[32:35]
	v_mfma_f32_16x16x32_bf16 v[20:23], v[176:179], v[210:213], v[20:23]
	v_mfma_f32_16x16x32_bf16 v[16:19], v[184:187], v[210:213], v[16:19]
	v_mfma_f32_16x16x32_bf16 v[4:7], v[176:179], v[218:221], v[4:7]
	v_mfma_f32_16x16x32_bf16 v[0:3], v[184:187], v[218:221], v[0:3]
	s_barrier
	s_setprio 0
	s_add_u32 vcc_lo, vcc_lo, 0x100
	s_addc_u32 vcc_hi, vcc_hi, 0
	s_add_u32 s22, s22, 0x100
	s_addc_u32 s23, s23, 0
	s_cmp_ge_i32 s77, s1
	s_mov_b32 s26, s77
	s_cbranch_scc0 .LBB0_1933
	s_and_b64 vcc, exec, s[52:53]
	s_cbranch_vccz .LBB0_1936

.LBB0_2145:
	s_or_b32 s50, s23, 1
	s_lshl_b64 s[88:89], s[50:51], 7
	s_add_i32 s50, s23, 2
	s_lshl_b64 s[90:91], s[50:51], 7
	v_add_u32_e32 v116, s74, v197
	v_add_u32_e32 v174, s75, v197
	s_add_u32 s43, s26, s90
	ds_read_b128 v[104:107], v116
	ds_read_b128 v[108:111], v116 offset:1024
	ds_read_b128 v[112:115], v116 offset:2048
	ds_read_b128 v[116:119], v116 offset:3072
	ds_read_b128 v[144:147], v174
	ds_read_b128 v[166:169], v174 offset:1024
	ds_read_b128 v[170:173], v174 offset:2048
	ds_read_b128 v[174:177], v174 offset:3072
	s_addc_u32 s87, s27, s91
	s_and_b64 s[72:73], s[70:71], exec
	s_cselect_b32 s73, s87, s63
	s_cselect_b32 s72, s43, s62
	s_add_u32 s43, s40, s90
	s_addc_u32 s87, s41, s91
	s_and_b64 s[70:71], s[70:71], exec
	s_cselect_b32 s71, s87, s65
	s_cselect_b32 s70, s43, s64
	s_add_u32 s43, s26, s88
	s_addc_u32 s87, s27, s89
	s_add_u32 s88, s43, 0x80000
	s_addc_u32 s89, s87, 0
	v_lshl_add_u64 v[218:219], s[88:89], 0, v[148:149]
	s_add_i32 m0, s7, 0xc000
	ds_read_b128 v[178:181], v156
	ds_read_b128 v[182:185], v156 offset:1024
	ds_read_b128 v[186:189], v156 offset:2048
	ds_read_b128 v[190:193], v156 offset:3072
	ds_read_b128 v[200:203], v156 offset:4096
	ds_read_b128 v[206:209], v156 offset:5120
	ds_read_b128 v[210:213], v156 offset:6144
	ds_read_b128 v[214:217], v156 offset:7168
	global_load_lds_dwordx4 v[218:219], off
	v_lshl_add_u64 v[218:219], s[88:89], 0, v[152:153]
	s_add_i32 m0, s7, 0xe000
	s_nop 0
	global_load_lds_dwordx4 v[218:219], off
	s_waitcnt vmcnt(8)
	s_waitcnt lgkmcnt(0)
	s_setprio 1
	s_barrier
	v_mfma_f32_16x16x32_bf16 v[140:143], v[104:107], v[178:181], v[140:143]
	v_mfma_f32_16x16x32_bf16 v[136:139], v[112:115], v[178:181], v[136:139]
	v_mfma_f32_16x16x32_bf16 v[124:127], v[104:107], v[186:189], v[124:127]
	v_mfma_f32_16x16x32_bf16 v[120:123], v[112:115], v[186:189], v[120:123]
	v_mfma_f32_16x16x32_bf16 v[92:95], v[104:107], v[200:203], v[92:95]
	v_mfma_f32_16x16x32_bf16 v[88:91], v[112:115], v[200:203], v[88:91]
	v_mfma_f32_16x16x32_bf16 v[76:79], v[104:107], v[210:213], v[76:79]
	v_mfma_f32_16x16x32_bf16 v[72:75], v[112:115], v[210:213], v[72:75]
	v_mfma_f32_16x16x32_bf16 v[140:143], v[108:111], v[182:185], v[140:143]
	v_mfma_f32_16x16x32_bf16 v[136:139], v[116:119], v[182:185], v[136:139]
	v_mfma_f32_16x16x32_bf16 v[124:127], v[108:111], v[190:193], v[124:127]
	v_mfma_f32_16x16x32_bf16 v[120:123], v[116:119], v[190:193], v[120:123]
	v_mfma_f32_16x16x32_bf16 v[92:95], v[108:111], v[206:209], v[92:95]
	v_mfma_f32_16x16x32_bf16 v[88:91], v[116:119], v[206:209], v[88:91]
	v_mfma_f32_16x16x32_bf16 v[76:79], v[108:111], v[214:217], v[76:79]
	v_mfma_f32_16x16x32_bf16 v[72:75], v[116:119], v[214:217], v[72:75]
	v_mfma_f32_16x16x32_bf16 v[132:135], v[144:147], v[178:181], v[132:135]
	v_mfma_f32_16x16x32_bf16 v[128:131], v[170:173], v[178:181], v[128:131]
	v_mfma_f32_16x16x32_bf16 v[100:103], v[144:147], v[186:189], v[100:103]
	v_mfma_f32_16x16x32_bf16 v[96:99], v[170:173], v[186:189], v[96:99]
	v_mfma_f32_16x16x32_bf16 v[84:87], v[144:147], v[200:203], v[84:87]
	v_mfma_f32_16x16x32_bf16 v[80:83], v[170:173], v[200:203], v[80:83]
	v_mfma_f32_16x16x32_bf16 v[68:71], v[144:147], v[210:213], v[68:71]
	v_mfma_f32_16x16x32_bf16 v[64:67], v[170:173], v[210:213], v[64:67]
	v_mfma_f32_16x16x32_bf16 v[132:135], v[166:169], v[182:185], v[132:135]
	v_mfma_f32_16x16x32_bf16 v[128:131], v[174:177], v[182:185], v[128:131]
	v_mfma_f32_16x16x32_bf16 v[100:103], v[166:169], v[190:193], v[100:103]
	v_mfma_f32_16x16x32_bf16 v[96:99], v[174:177], v[190:193], v[96:99]
	v_mfma_f32_16x16x32_bf16 v[84:87], v[166:169], v[206:209], v[84:87]
	v_mfma_f32_16x16x32_bf16 v[80:83], v[174:177], v[206:209], v[80:83]
	v_mfma_f32_16x16x32_bf16 v[68:71], v[166:169], v[214:217], v[68:71]
	v_mfma_f32_16x16x32_bf16 v[64:67], v[174:177], v[214:217], v[64:67]
	s_barrier
	s_setprio 0
	s_add_i32 s43, s74, s6
	v_lshl_add_u64 v[218:219], s[70:71], 0, v[150:151]
	s_mov_b32 m0, s43
	ds_read_b128 v[178:181], v156 offset:16384
	ds_read_b128 v[182:185], v156 offset:17408
	ds_read_b128 v[186:189], v156 offset:18432
	ds_read_b128 v[190:193], v156 offset:19456
	ds_read_b128 v[200:203], v156 offset:20480
	ds_read_b128 v[206:209], v156 offset:21504
	ds_read_b128 v[210:213], v156 offset:22528
	ds_read_b128 v[214:217], v156 offset:23552
	global_load_lds_dwordx4 v[218:219], off
	s_add_i32 m0, s43, 0x2000
	s_add_u32 s88, s70, 0x80000
	v_lshl_add_u64 v[220:221], s[70:71], 0, v[154:155]
	s_addc_u32 s89, s71, 0
	s_add_i32 s43, s75, s6
	global_load_lds_dwordx4 v[220:221], off
	v_lshl_add_u64 v[222:223], s[88:89], 0, v[150:151]
	s_mov_b32 m0, s43
	v_lshl_add_u64 v[224:225], s[72:73], 0, v[152:153]
	global_load_lds_dwordx4 v[222:223], off
	v_lshl_add_u64 v[222:223], s[88:89], 0, v[154:155]
	s_add_i32 m0, s43, 0x2000
	s_nop 0
	global_load_lds_dwordx4 v[222:223], off
	v_lshl_add_u64 v[222:223], s[72:73], 0, v[148:149]
	s_mov_b32 m0, s7
	s_nop 0
	global_load_lds_dwordx4 v[222:223], off
	s_mov_b32 m0, s8
	s_nop 0
	global_load_lds_dwordx4 v[224:225], off
	s_waitcnt vmcnt(8)
	s_waitcnt lgkmcnt(0)
	s_setprio 1
	s_barrier
	v_mfma_f32_16x16x32_bf16 v[60:63], v[104:107], v[178:181], v[60:63]
	v_mfma_f32_16x16x32_bf16 v[56:59], v[112:115], v[178:181], v[56:59]
	v_mfma_f32_16x16x32_bf16 v[44:47], v[104:107], v[186:189], v[44:47]
	v_mfma_f32_16x16x32_bf16 v[40:43], v[112:115], v[186:189], v[40:43]
	v_mfma_f32_16x16x32_bf16 v[20:23], v[104:107], v[200:203], v[20:23]
	v_mfma_f32_16x16x32_bf16 v[16:19], v[112:115], v[200:203], v[16:19]
	v_mfma_f32_16x16x32_bf16 v[4:7], v[104:107], v[210:213], v[4:7]
	v_mfma_f32_16x16x32_bf16 v[0:3], v[112:115], v[210:213], v[0:3]
	v_mfma_f32_16x16x32_bf16 v[60:63], v[108:111], v[182:185], v[60:63]
	v_mfma_f32_16x16x32_bf16 v[56:59], v[116:119], v[182:185], v[56:59]
	v_mfma_f32_16x16x32_bf16 v[44:47], v[108:111], v[190:193], v[44:47]
	v_mfma_f32_16x16x32_bf16 v[40:43], v[116:119], v[190:193], v[40:43]
	v_mfma_f32_16x16x32_bf16 v[20:23], v[108:111], v[206:209], v[20:23]
	v_mfma_f32_16x16x32_bf16 v[16:19], v[116:119], v[206:209], v[16:19]
	v_mfma_f32_16x16x32_bf16 v[4:7], v[108:111], v[214:217], v[4:7]
	v_mfma_f32_16x16x32_bf16 v[0:3], v[116:119], v[214:217], v[0:3]
	v_mfma_f32_16x16x32_bf16 v[52:55], v[144:147], v[178:181], v[52:55]
	v_mfma_f32_16x16x32_bf16 v[48:51], v[170:173], v[178:181], v[48:51]
	v_mfma_f32_16x16x32_bf16 v[36:39], v[144:147], v[186:189], v[36:39]
	v_mfma_f32_16x16x32_bf16 v[32:35], v[170:173], v[186:189], v[32:35]
	v_mfma_f32_16x16x32_bf16 v[28:31], v[144:147], v[200:203], v[28:31]
	v_mfma_f32_16x16x32_bf16 v[24:27], v[170:173], v[200:203], v[24:27]
	v_mfma_f32_16x16x32_bf16 v[12:15], v[144:147], v[210:213], v[12:15]
	v_mfma_f32_16x16x32_bf16 v[8:11], v[170:173], v[210:213], v[8:11]
	v_mfma_f32_16x16x32_bf16 v[52:55], v[166:169], v[182:185], v[52:55]
	v_mfma_f32_16x16x32_bf16 v[48:51], v[174:177], v[182:185], v[48:51]
	v_mfma_f32_16x16x32_bf16 v[36:39], v[166:169], v[190:193], v[36:39]
	v_mfma_f32_16x16x32_bf16 v[32:35], v[174:177], v[190:193], v[32:35]
	v_mfma_f32_16x16x32_bf16 v[28:31], v[166:169], v[206:209], v[28:31]
	v_mfma_f32_16x16x32_bf16 v[24:27], v[174:177], v[206:209], v[24:27]
	v_mfma_f32_16x16x32_bf16 v[12:15], v[166:169], v[214:217], v[12:15]
	v_mfma_f32_16x16x32_bf16 v[8:11], v[174:177], v[214:217], v[8:11]
	s_barrier
	s_setprio 0
	v_add_u32_e32 v116, s76, v197
	v_add_u32_e32 v174, s77, v197
	ds_read_b128 v[104:107], v116
	ds_read_b128 v[108:111], v116 offset:1024
	ds_read_b128 v[112:115], v116 offset:2048
	ds_read_b128 v[116:119], v116 offset:3072
	ds_read_b128 v[144:147], v174
	ds_read_b128 v[166:169], v174 offset:1024
	ds_read_b128 v[170:173], v174 offset:2048
	ds_read_b128 v[174:177], v174 offset:3072
	s_add_u32 s72, s72, 0x80000
	s_addc_u32 s73, s73, 0
	s_mov_b32 m0, s9
	v_lshl_add_u64 v[226:227], s[72:73], 0, v[148:149]
	ds_read_b128 v[178:181], v156 offset:32768
	ds_read_b128 v[182:185], v156 offset:33792
	ds_read_b128 v[186:189], v156 offset:34816
	ds_read_b128 v[190:193], v156 offset:35840
	ds_read_b128 v[200:203], v156 offset:36864
	ds_read_b128 v[206:209], v156 offset:37888
	ds_read_b128 v[210:213], v156 offset:38912
	ds_read_b128 v[214:217], v156 offset:39936
	global_load_lds_dwordx4 v[226:227], off
	v_lshl_add_u64 v[226:227], s[72:73], 0, v[152:153]
	s_mov_b32 m0, s10
	s_nop 0
	global_load_lds_dwordx4 v[226:227], off
	s_waitcnt vmcnt(8)
	s_waitcnt lgkmcnt(0)
	s_setprio 1
	s_barrier
	v_mfma_f32_16x16x32_bf16 v[140:143], v[104:107], v[178:181], v[140:143]
	v_mfma_f32_16x16x32_bf16 v[136:139], v[112:115], v[178:181], v[136:139]
	v_mfma_f32_16x16x32_bf16 v[124:127], v[104:107], v[186:189], v[124:127]
	v_mfma_f32_16x16x32_bf16 v[120:123], v[112:115], v[186:189], v[120:123]
	v_mfma_f32_16x16x32_bf16 v[92:95], v[104:107], v[200:203], v[92:95]
	v_mfma_f32_16x16x32_bf16 v[88:91], v[112:115], v[200:203], v[88:91]
	v_mfma_f32_16x16x32_bf16 v[76:79], v[104:107], v[210:213], v[76:79]
	v_mfma_f32_16x16x32_bf16 v[72:75], v[112:115], v[210:213], v[72:75]
	v_mfma_f32_16x16x32_bf16 v[140:143], v[108:111], v[182:185], v[140:143]
	v_mfma_f32_16x16x32_bf16 v[136:139], v[116:119], v[182:185], v[136:139]
	v_mfma_f32_16x16x32_bf16 v[124:127], v[108:111], v[190:193], v[124:127]
	v_mfma_f32_16x16x32_bf16 v[120:123], v[116:119], v[190:193], v[120:123]
	v_mfma_f32_16x16x32_bf16 v[92:95], v[108:111], v[206:209], v[92:95]
	v_mfma_f32_16x16x32_bf16 v[88:91], v[116:119], v[206:209], v[88:91]
	v_mfma_f32_16x16x32_bf16 v[76:79], v[108:111], v[214:217], v[76:79]
	v_mfma_f32_16x16x32_bf16 v[72:75], v[116:119], v[214:217], v[72:75]
	v_mfma_f32_16x16x32_bf16 v[132:135], v[144:147], v[178:181], v[132:135]
	v_mfma_f32_16x16x32_bf16 v[128:131], v[170:173], v[178:181], v[128:131]
	v_mfma_f32_16x16x32_bf16 v[100:103], v[144:147], v[186:189], v[100:103]
	v_mfma_f32_16x16x32_bf16 v[96:99], v[170:173], v[186:189], v[96:99]
	v_mfma_f32_16x16x32_bf16 v[84:87], v[144:147], v[200:203], v[84:87]
	v_mfma_f32_16x16x32_bf16 v[80:83], v[170:173], v[200:203], v[80:83]
	v_mfma_f32_16x16x32_bf16 v[68:71], v[144:147], v[210:213], v[68:71]
	v_mfma_f32_16x16x32_bf16 v[64:67], v[170:173], v[210:213], v[64:67]
	v_mfma_f32_16x16x32_bf16 v[132:135], v[166:169], v[182:185], v[132:135]
	v_mfma_f32_16x16x32_bf16 v[128:131], v[174:177], v[182:185], v[128:131]
	v_mfma_f32_16x16x32_bf16 v[100:103], v[166:169], v[190:193], v[100:103]
	v_mfma_f32_16x16x32_bf16 v[96:99], v[174:177], v[190:193], v[96:99]
	v_mfma_f32_16x16x32_bf16 v[84:87], v[166:169], v[206:209], v[84:87]
	v_mfma_f32_16x16x32_bf16 v[80:83], v[174:177], v[206:209], v[80:83]
	v_mfma_f32_16x16x32_bf16 v[68:71], v[166:169], v[214:217], v[68:71]
	v_mfma_f32_16x16x32_bf16 v[64:67], v[174:177], v[214:217], v[64:67]
	s_barrier
	s_setprio 0
	s_add_i32 s43, s76, s6
	v_lshl_add_u64 v[218:219], v[218:219], 0, s[48:49]
	s_mov_b32 m0, s43
	ds_read_b128 v[178:181], v156 offset:49152
	ds_read_b128 v[182:185], v156 offset:50176
	ds_read_b128 v[186:189], v156 offset:51200
	ds_read_b128 v[190:193], v156 offset:52224
	ds_read_b128 v[200:203], v156 offset:53248
	ds_read_b128 v[206:209], v156 offset:54272
	ds_read_b128 v[210:213], v156 offset:55296
	ds_read_b128 v[214:217], v156 offset:56320
	global_load_lds_dwordx4 v[218:219], off
	s_add_i32 m0, s43, 0x2000
	s_add_u32 s70, s70, 0x80080
	v_lshl_add_u64 v[218:219], v[220:221], 0, s[48:49]
	s_addc_u32 s71, s71, 0
	s_add_i32 s43, s77, s6
	global_load_lds_dwordx4 v[218:219], off
	v_lshl_add_u64 v[218:219], s[70:71], 0, v[150:151]
	s_mov_b32 m0, s43
	s_nop 0
	global_load_lds_dwordx4 v[218:219], off
	v_lshl_add_u64 v[218:219], s[70:71], 0, v[154:155]
	s_add_i32 m0, s43, 0x2000
	s_nop 0
	global_load_lds_dwordx4 v[218:219], off
	v_lshl_add_u64 v[218:219], v[222:223], 0, s[48:49]
	s_mov_b32 m0, s11
	s_nop 0
	global_load_lds_dwordx4 v[218:219], off
	v_lshl_add_u64 v[218:219], v[224:225], 0, s[48:49]
	s_mov_b32 m0, s12
	s_nop 0
	global_load_lds_dwordx4 v[218:219], off
	s_waitcnt vmcnt(8)
	s_waitcnt lgkmcnt(0)
	s_setprio 1
	s_barrier
	v_mfma_f32_16x16x32_bf16 v[60:63], v[104:107], v[178:181], v[60:63]
	v_mfma_f32_16x16x32_bf16 v[56:59], v[112:115], v[178:181], v[56:59]
	v_mfma_f32_16x16x32_bf16 v[44:47], v[104:107], v[186:189], v[44:47]
	v_mfma_f32_16x16x32_bf16 v[40:43], v[112:115], v[186:189], v[40:43]
	v_mfma_f32_16x16x32_bf16 v[20:23], v[104:107], v[200:203], v[20:23]
	v_mfma_f32_16x16x32_bf16 v[16:19], v[112:115], v[200:203], v[16:19]
	v_mfma_f32_16x16x32_bf16 v[4:7], v[104:107], v[210:213], v[4:7]
	v_mfma_f32_16x16x32_bf16 v[0:3], v[112:115], v[210:213], v[0:3]
	v_mfma_f32_16x16x32_bf16 v[60:63], v[108:111], v[182:185], v[60:63]
	v_mfma_f32_16x16x32_bf16 v[56:59], v[116:119], v[182:185], v[56:59]
	v_mfma_f32_16x16x32_bf16 v[44:47], v[108:111], v[190:193], v[44:47]
	v_mfma_f32_16x16x32_bf16 v[40:43], v[116:119], v[190:193], v[40:43]
	v_mfma_f32_16x16x32_bf16 v[20:23], v[108:111], v[206:209], v[20:23]
	v_mfma_f32_16x16x32_bf16 v[16:19], v[116:119], v[206:209], v[16:19]
	v_mfma_f32_16x16x32_bf16 v[4:7], v[108:111], v[214:217], v[4:7]
	v_mfma_f32_16x16x32_bf16 v[0:3], v[116:119], v[214:217], v[0:3]
	v_mfma_f32_16x16x32_bf16 v[52:55], v[144:147], v[178:181], v[52:55]
	v_mfma_f32_16x16x32_bf16 v[48:51], v[170:173], v[178:181], v[48:51]
	v_mfma_f32_16x16x32_bf16 v[36:39], v[144:147], v[186:189], v[36:39]
	v_mfma_f32_16x16x32_bf16 v[32:35], v[170:173], v[186:189], v[32:35]
	v_mfma_f32_16x16x32_bf16 v[28:31], v[144:147], v[200:203], v[28:31]
	v_mfma_f32_16x16x32_bf16 v[24:27], v[170:173], v[200:203], v[24:27]
	v_mfma_f32_16x16x32_bf16 v[12:15], v[144:147], v[210:213], v[12:15]
	v_mfma_f32_16x16x32_bf16 v[8:11], v[170:173], v[210:213], v[8:11]
	v_mfma_f32_16x16x32_bf16 v[52:55], v[166:169], v[182:185], v[52:55]
	v_mfma_f32_16x16x32_bf16 v[48:51], v[174:177], v[182:185], v[48:51]
	v_mfma_f32_16x16x32_bf16 v[36:39], v[166:169], v[190:193], v[36:39]
	v_mfma_f32_16x16x32_bf16 v[32:35], v[174:177], v[190:193], v[32:35]
	v_mfma_f32_16x16x32_bf16 v[28:31], v[166:169], v[206:209], v[28:31]
	v_mfma_f32_16x16x32_bf16 v[24:27], v[174:177], v[206:209], v[24:27]
	v_mfma_f32_16x16x32_bf16 v[12:15], v[166:169], v[214:217], v[12:15]
	v_mfma_f32_16x16x32_bf16 v[8:11], v[174:177], v[214:217], v[8:11]
	s_barrier
	s_setprio 0
	s_cmp_gt_u32 s23, 29
	s_cbranch_scc1 .LBB0_2147
	s_mov_b32 s23, s50
	s_branch .LBB0_2133

.LBB0_3142:
	s_or_b32 s40, s31, 1
	s_lshl_b64 s[96:97], s[40:41], 7
	s_add_i32 s40, s31, 2
	s_lshl_b64 vcc, s[40:41], 7
	s_add_u32 s53, s60, vcc_lo
	s_addc_u32 s59, s61, vcc_hi
	s_and_b64 s[70:71], s[68:69], exec
	s_cselect_b32 s71, s59, s55
	s_cselect_b32 s70, s53, s54
	s_add_u32 s53, s62, vcc_lo
	s_addc_u32 s59, s63, vcc_hi
	s_add_i32 s65, 0, 0x10000
	s_and_b64 s[68:69], s[68:69], exec
	s_cselect_b32 s69, s59, s57
	s_cselect_b32 s68, s53, s56
	s_add_i32 s53, 0, 0x14000
	v_add_u32_e32 v140, s65, v169
	v_add_u32_e32 v182, s53, v169
	ds_read_b128 v[128:131], v140
	ds_read_b128 v[132:135], v140 offset:1024
	ds_read_b128 v[136:139], v140 offset:2048
	ds_read_b128 v[140:143], v140 offset:3072
	ds_read_b128 v[160:163], v182
	ds_read_b128 v[174:177], v182 offset:1024
	ds_read_b128 v[178:181], v182 offset:2048
	ds_read_b128 v[182:185], v182 offset:3072
	s_add_u32 s59, s60, s96
	s_addc_u32 s95, s61, s97
	s_add_u32 s96, s59, 0x80000
	s_addc_u32 s97, s95, 0
	v_lshl_add_u64 v[202:203], s[96:97], 0, v[152:153]
	s_add_i32 m0, s7, 0xc000
	ds_read_b128 v[186:189], v173
	ds_read_b128 v[190:193], v173 offset:1024
	ds_read_b128 v[194:197], v173 offset:2048
	ds_read_b128 v[198:201], v173 offset:3072
	ds_read_b128 v[206:209], v173 offset:4096
	ds_read_b128 v[210:213], v173 offset:5120
	ds_read_b128 v[214:217], v173 offset:6144
	ds_read_b128 v[218:221], v173 offset:7168
	global_load_lds_dwordx4 v[202:203], off
	v_lshl_add_u64 v[202:203], s[96:97], 0, v[154:155]
	s_add_i32 m0, s7, 0xe000
	s_nop 0
	global_load_lds_dwordx4 v[202:203], off
	s_waitcnt vmcnt(8)
	s_waitcnt lgkmcnt(0)
	s_setprio 1
	s_barrier
	v_mfma_f32_16x16x32_bf16 v[124:127], v[128:131], v[186:189], v[124:127]
	v_mfma_f32_16x16x32_bf16 v[120:123], v[136:139], v[186:189], v[120:123]
	v_mfma_f32_16x16x32_bf16 v[108:111], v[128:131], v[194:197], v[108:111]
	v_mfma_f32_16x16x32_bf16 v[104:107], v[136:139], v[194:197], v[104:107]
	v_mfma_f32_16x16x32_bf16 v[92:95], v[128:131], v[206:209], v[92:95]
	v_mfma_f32_16x16x32_bf16 v[88:91], v[136:139], v[206:209], v[88:91]
	v_mfma_f32_16x16x32_bf16 v[76:79], v[128:131], v[214:217], v[76:79]
	v_mfma_f32_16x16x32_bf16 v[72:75], v[136:139], v[214:217], v[72:75]
	v_mfma_f32_16x16x32_bf16 v[124:127], v[132:135], v[190:193], v[124:127]
	v_mfma_f32_16x16x32_bf16 v[120:123], v[140:143], v[190:193], v[120:123]
	v_mfma_f32_16x16x32_bf16 v[108:111], v[132:135], v[198:201], v[108:111]
	v_mfma_f32_16x16x32_bf16 v[104:107], v[140:143], v[198:201], v[104:107]
	v_mfma_f32_16x16x32_bf16 v[92:95], v[132:135], v[210:213], v[92:95]
	v_mfma_f32_16x16x32_bf16 v[88:91], v[140:143], v[210:213], v[88:91]
	v_mfma_f32_16x16x32_bf16 v[76:79], v[132:135], v[218:221], v[76:79]
	v_mfma_f32_16x16x32_bf16 v[72:75], v[140:143], v[218:221], v[72:75]
	v_mfma_f32_16x16x32_bf16 v[116:119], v[160:163], v[186:189], v[116:119]
	v_mfma_f32_16x16x32_bf16 v[112:115], v[178:181], v[186:189], v[112:115]
	v_mfma_f32_16x16x32_bf16 v[100:103], v[160:163], v[194:197], v[100:103]
	v_mfma_f32_16x16x32_bf16 v[96:99], v[178:181], v[194:197], v[96:99]
	v_mfma_f32_16x16x32_bf16 v[84:87], v[160:163], v[206:209], v[84:87]
	v_mfma_f32_16x16x32_bf16 v[80:83], v[178:181], v[206:209], v[80:83]
	v_mfma_f32_16x16x32_bf16 v[68:71], v[160:163], v[214:217], v[68:71]
	v_mfma_f32_16x16x32_bf16 v[64:67], v[178:181], v[214:217], v[64:67]
	v_mfma_f32_16x16x32_bf16 v[116:119], v[174:177], v[190:193], v[116:119]
	v_mfma_f32_16x16x32_bf16 v[112:115], v[182:185], v[190:193], v[112:115]
	v_mfma_f32_16x16x32_bf16 v[100:103], v[174:177], v[198:201], v[100:103]
	v_mfma_f32_16x16x32_bf16 v[96:99], v[182:185], v[198:201], v[96:99]
	v_mfma_f32_16x16x32_bf16 v[84:87], v[174:177], v[210:213], v[84:87]
	v_mfma_f32_16x16x32_bf16 v[80:83], v[182:185], v[210:213], v[80:83]
	v_mfma_f32_16x16x32_bf16 v[68:71], v[174:177], v[218:221], v[68:71]
	v_mfma_f32_16x16x32_bf16 v[64:67], v[182:185], v[218:221], v[64:67]
	s_barrier
	s_setprio 0
	s_add_i32 s59, s65, s6
	v_lshl_add_u64 v[202:203], s[68:69], 0, v[144:145]
	s_mov_b32 m0, s59
	ds_read_b128 v[186:189], v173 offset:16384
	ds_read_b128 v[190:193], v173 offset:17408
	ds_read_b128 v[194:197], v173 offset:18432
	ds_read_b128 v[198:201], v173 offset:19456
	ds_read_b128 v[206:209], v173 offset:20480
	ds_read_b128 v[210:213], v173 offset:21504
	ds_read_b128 v[214:217], v173 offset:22528
	ds_read_b128 v[218:221], v173 offset:23552
	global_load_lds_dwordx4 v[202:203], off
	s_add_i32 m0, s59, 0x2000
	s_add_u32 s96, s68, 0x80000
	v_lshl_add_u64 v[222:223], s[68:69], 0, v[156:157]
	s_addc_u32 s97, s69, 0
	s_add_i32 s53, s53, s6
	global_load_lds_dwordx4 v[222:223], off
	v_lshl_add_u64 v[224:225], s[96:97], 0, v[144:145]
	s_mov_b32 m0, s53
	v_lshl_add_u64 v[226:227], s[70:71], 0, v[154:155]
	global_load_lds_dwordx4 v[224:225], off
	v_lshl_add_u64 v[224:225], s[96:97], 0, v[156:157]
	s_add_i32 m0, s53, 0x2000
	s_nop 0
	global_load_lds_dwordx4 v[224:225], off
	v_lshl_add_u64 v[224:225], s[70:71], 0, v[152:153]
	s_mov_b32 m0, s7
	s_nop 0
	global_load_lds_dwordx4 v[224:225], off
	s_mov_b32 m0, s8
	s_nop 0
	global_load_lds_dwordx4 v[226:227], off
	s_waitcnt vmcnt(8)
	s_waitcnt lgkmcnt(0)
	s_setprio 1
	s_barrier
	v_mfma_f32_16x16x32_bf16 v[60:63], v[128:131], v[186:189], v[60:63]
	v_mfma_f32_16x16x32_bf16 v[56:59], v[136:139], v[186:189], v[56:59]
	v_mfma_f32_16x16x32_bf16 v[44:47], v[128:131], v[194:197], v[44:47]
	v_mfma_f32_16x16x32_bf16 v[40:43], v[136:139], v[194:197], v[40:43]
	v_mfma_f32_16x16x32_bf16 v[24:27], v[128:131], v[206:209], v[24:27]
	v_mfma_f32_16x16x32_bf16 v[16:19], v[136:139], v[206:209], v[16:19]
	v_mfma_f32_16x16x32_bf16 v[4:7], v[128:131], v[214:217], v[4:7]
	v_mfma_f32_16x16x32_bf16 v[0:3], v[136:139], v[214:217], v[0:3]
	v_mfma_f32_16x16x32_bf16 v[60:63], v[132:135], v[190:193], v[60:63]
	v_mfma_f32_16x16x32_bf16 v[56:59], v[140:143], v[190:193], v[56:59]
	v_mfma_f32_16x16x32_bf16 v[44:47], v[132:135], v[198:201], v[44:47]
	v_mfma_f32_16x16x32_bf16 v[40:43], v[140:143], v[198:201], v[40:43]
	v_mfma_f32_16x16x32_bf16 v[24:27], v[132:135], v[210:213], v[24:27]
	v_mfma_f32_16x16x32_bf16 v[16:19], v[140:143], v[210:213], v[16:19]
	v_mfma_f32_16x16x32_bf16 v[4:7], v[132:135], v[218:221], v[4:7]
	v_mfma_f32_16x16x32_bf16 v[0:3], v[140:143], v[218:221], v[0:3]
	v_mfma_f32_16x16x32_bf16 v[52:55], v[160:163], v[186:189], v[52:55]
	v_mfma_f32_16x16x32_bf16 v[48:51], v[178:181], v[186:189], v[48:51]
	v_mfma_f32_16x16x32_bf16 v[28:31], v[160:163], v[194:197], v[28:31]
	v_mfma_f32_16x16x32_bf16 v[20:23], v[178:181], v[194:197], v[20:23]
	v_mfma_f32_16x16x32_bf16 v[32:35], v[160:163], v[206:209], v[32:35]
	v_mfma_f32_16x16x32_bf16 v[36:39], v[178:181], v[206:209], v[36:39]
	v_mfma_f32_16x16x32_bf16 v[8:11], v[160:163], v[214:217], v[8:11]
	v_mfma_f32_16x16x32_bf16 v[12:15], v[178:181], v[214:217], v[12:15]
	v_mfma_f32_16x16x32_bf16 v[52:55], v[174:177], v[190:193], v[52:55]
	v_mfma_f32_16x16x32_bf16 v[48:51], v[182:185], v[190:193], v[48:51]
	v_mfma_f32_16x16x32_bf16 v[28:31], v[174:177], v[198:201], v[28:31]
	v_mfma_f32_16x16x32_bf16 v[20:23], v[182:185], v[198:201], v[20:23]
	v_mfma_f32_16x16x32_bf16 v[32:35], v[174:177], v[210:213], v[32:35]
	v_mfma_f32_16x16x32_bf16 v[36:39], v[182:185], v[210:213], v[36:39]
	v_mfma_f32_16x16x32_bf16 v[8:11], v[174:177], v[218:221], v[8:11]
	v_mfma_f32_16x16x32_bf16 v[12:15], v[182:185], v[218:221], v[12:15]
	s_barrier
	s_setprio 0
	s_add_i32 s53, 0, 0x18000
	s_add_i32 s59, 0, 0x1c000
	v_add_u32_e32 v140, s53, v169
	v_add_u32_e32 v182, s59, v169
	ds_read_b128 v[128:131], v140
	ds_read_b128 v[132:135], v140 offset:1024
	ds_read_b128 v[136:139], v140 offset:2048
	ds_read_b128 v[140:143], v140 offset:3072
	ds_read_b128 v[160:163], v182
	ds_read_b128 v[174:177], v182 offset:1024
	ds_read_b128 v[178:181], v182 offset:2048
	ds_read_b128 v[182:185], v182 offset:3072
	s_add_u32 s70, s70, 0x80000
	s_addc_u32 s71, s71, 0
	s_mov_b32 m0, s9
	v_lshl_add_u64 v[228:229], s[70:71], 0, v[152:153]
	ds_read_b128 v[186:189], v173 offset:32768
	ds_read_b128 v[190:193], v173 offset:33792
	ds_read_b128 v[194:197], v173 offset:34816
	ds_read_b128 v[198:201], v173 offset:35840
	ds_read_b128 v[206:209], v173 offset:36864
	ds_read_b128 v[210:213], v173 offset:37888
	ds_read_b128 v[214:217], v173 offset:38912
	ds_read_b128 v[218:221], v173 offset:39936
	global_load_lds_dwordx4 v[228:229], off
	v_lshl_add_u64 v[228:229], s[70:71], 0, v[154:155]
	s_mov_b32 m0, s10
	s_nop 0
	global_load_lds_dwordx4 v[228:229], off
	s_waitcnt vmcnt(8)
	s_waitcnt lgkmcnt(0)
	s_setprio 1
	s_barrier
	v_mfma_f32_16x16x32_bf16 v[124:127], v[128:131], v[186:189], v[124:127]
	v_mfma_f32_16x16x32_bf16 v[120:123], v[136:139], v[186:189], v[120:123]
	v_mfma_f32_16x16x32_bf16 v[108:111], v[128:131], v[194:197], v[108:111]
	v_mfma_f32_16x16x32_bf16 v[104:107], v[136:139], v[194:197], v[104:107]
	v_mfma_f32_16x16x32_bf16 v[92:95], v[128:131], v[206:209], v[92:95]
	v_mfma_f32_16x16x32_bf16 v[88:91], v[136:139], v[206:209], v[88:91]
	v_mfma_f32_16x16x32_bf16 v[76:79], v[128:131], v[214:217], v[76:79]
	v_mfma_f32_16x16x32_bf16 v[72:75], v[136:139], v[214:217], v[72:75]
	v_mfma_f32_16x16x32_bf16 v[124:127], v[132:135], v[190:193], v[124:127]
	v_mfma_f32_16x16x32_bf16 v[120:123], v[140:143], v[190:193], v[120:123]
	v_mfma_f32_16x16x32_bf16 v[108:111], v[132:135], v[198:201], v[108:111]
	v_mfma_f32_16x16x32_bf16 v[104:107], v[140:143], v[198:201], v[104:107]
	v_mfma_f32_16x16x32_bf16 v[92:95], v[132:135], v[210:213], v[92:95]
	v_mfma_f32_16x16x32_bf16 v[88:91], v[140:143], v[210:213], v[88:91]
	v_mfma_f32_16x16x32_bf16 v[76:79], v[132:135], v[218:221], v[76:79]
	v_mfma_f32_16x16x32_bf16 v[72:75], v[140:143], v[218:221], v[72:75]
	v_mfma_f32_16x16x32_bf16 v[116:119], v[160:163], v[186:189], v[116:119]
	v_mfma_f32_16x16x32_bf16 v[112:115], v[178:181], v[186:189], v[112:115]
	v_mfma_f32_16x16x32_bf16 v[100:103], v[160:163], v[194:197], v[100:103]
	v_mfma_f32_16x16x32_bf16 v[96:99], v[178:181], v[194:197], v[96:99]
	v_mfma_f32_16x16x32_bf16 v[84:87], v[160:163], v[206:209], v[84:87]
	v_mfma_f32_16x16x32_bf16 v[80:83], v[178:181], v[206:209], v[80:83]
	v_mfma_f32_16x16x32_bf16 v[68:71], v[160:163], v[214:217], v[68:71]
	v_mfma_f32_16x16x32_bf16 v[64:67], v[178:181], v[214:217], v[64:67]
	v_mfma_f32_16x16x32_bf16 v[116:119], v[174:177], v[190:193], v[116:119]
	v_mfma_f32_16x16x32_bf16 v[112:115], v[182:185], v[190:193], v[112:115]
	v_mfma_f32_16x16x32_bf16 v[100:103], v[174:177], v[198:201], v[100:103]
	v_mfma_f32_16x16x32_bf16 v[96:99], v[182:185], v[198:201], v[96:99]
	v_mfma_f32_16x16x32_bf16 v[84:87], v[174:177], v[210:213], v[84:87]
	v_mfma_f32_16x16x32_bf16 v[80:83], v[182:185], v[210:213], v[80:83]
	v_mfma_f32_16x16x32_bf16 v[68:71], v[174:177], v[218:221], v[68:71]
	v_mfma_f32_16x16x32_bf16 v[64:67], v[182:185], v[218:221], v[64:67]
	s_barrier
	s_setprio 0
	s_add_i32 s53, s53, s6
	v_lshl_add_u64 v[202:203], v[202:203], 0, s[42:43]
	s_mov_b32 m0, s53
	ds_read_b128 v[186:189], v173 offset:49152
	ds_read_b128 v[190:193], v173 offset:50176
	ds_read_b128 v[194:197], v173 offset:51200
	ds_read_b128 v[198:201], v173 offset:52224
	ds_read_b128 v[206:209], v173 offset:53248
	ds_read_b128 v[210:213], v173 offset:54272
	ds_read_b128 v[214:217], v173 offset:55296
	ds_read_b128 v[218:221], v173 offset:56320
	global_load_lds_dwordx4 v[202:203], off
	s_add_i32 m0, s53, 0x2000
	s_add_u32 s68, s68, 0x80080
	v_lshl_add_u64 v[202:203], v[222:223], 0, s[42:43]
	s_addc_u32 s69, s69, 0
	s_add_i32 s53, s59, s6
	global_load_lds_dwordx4 v[202:203], off
	v_lshl_add_u64 v[202:203], s[68:69], 0, v[144:145]
	s_mov_b32 m0, s53
	s_nop 0
	global_load_lds_dwordx4 v[202:203], off
	v_lshl_add_u64 v[202:203], s[68:69], 0, v[156:157]
	s_add_i32 m0, s53, 0x2000
	s_nop 0
	global_load_lds_dwordx4 v[202:203], off
	v_lshl_add_u64 v[202:203], v[224:225], 0, s[42:43]
	s_mov_b32 m0, s11
	s_nop 0
	global_load_lds_dwordx4 v[202:203], off
	v_lshl_add_u64 v[202:203], v[226:227], 0, s[42:43]
	s_mov_b32 m0, s12
	s_nop 0
	global_load_lds_dwordx4 v[202:203], off
	s_waitcnt vmcnt(8)
	s_waitcnt lgkmcnt(0)
	s_setprio 1
	s_barrier
	v_mfma_f32_16x16x32_bf16 v[60:63], v[128:131], v[186:189], v[60:63]
	v_mfma_f32_16x16x32_bf16 v[56:59], v[136:139], v[186:189], v[56:59]
	v_mfma_f32_16x16x32_bf16 v[44:47], v[128:131], v[194:197], v[44:47]
	v_mfma_f32_16x16x32_bf16 v[40:43], v[136:139], v[194:197], v[40:43]
	v_mfma_f32_16x16x32_bf16 v[24:27], v[128:131], v[206:209], v[24:27]
	v_mfma_f32_16x16x32_bf16 v[16:19], v[136:139], v[206:209], v[16:19]
	v_mfma_f32_16x16x32_bf16 v[4:7], v[128:131], v[214:217], v[4:7]
	v_mfma_f32_16x16x32_bf16 v[0:3], v[136:139], v[214:217], v[0:3]
	v_mfma_f32_16x16x32_bf16 v[60:63], v[132:135], v[190:193], v[60:63]
	v_mfma_f32_16x16x32_bf16 v[56:59], v[140:143], v[190:193], v[56:59]
	v_mfma_f32_16x16x32_bf16 v[44:47], v[132:135], v[198:201], v[44:47]
	v_mfma_f32_16x16x32_bf16 v[40:43], v[140:143], v[198:201], v[40:43]
	v_mfma_f32_16x16x32_bf16 v[24:27], v[132:135], v[210:213], v[24:27]
	v_mfma_f32_16x16x32_bf16 v[16:19], v[140:143], v[210:213], v[16:19]
	v_mfma_f32_16x16x32_bf16 v[4:7], v[132:135], v[218:221], v[4:7]
	v_mfma_f32_16x16x32_bf16 v[0:3], v[140:143], v[218:221], v[0:3]
	v_mfma_f32_16x16x32_bf16 v[52:55], v[160:163], v[186:189], v[52:55]
	v_mfma_f32_16x16x32_bf16 v[48:51], v[178:181], v[186:189], v[48:51]
	v_mfma_f32_16x16x32_bf16 v[28:31], v[160:163], v[194:197], v[28:31]
	v_mfma_f32_16x16x32_bf16 v[20:23], v[178:181], v[194:197], v[20:23]
	v_mfma_f32_16x16x32_bf16 v[32:35], v[160:163], v[206:209], v[32:35]
	v_mfma_f32_16x16x32_bf16 v[36:39], v[178:181], v[206:209], v[36:39]
	v_mfma_f32_16x16x32_bf16 v[8:11], v[160:163], v[214:217], v[8:11]
	v_mfma_f32_16x16x32_bf16 v[12:15], v[178:181], v[214:217], v[12:15]
	v_mfma_f32_16x16x32_bf16 v[52:55], v[174:177], v[190:193], v[52:55]
	v_mfma_f32_16x16x32_bf16 v[48:51], v[182:185], v[190:193], v[48:51]
	v_mfma_f32_16x16x32_bf16 v[28:31], v[174:177], v[198:201], v[28:31]
	v_mfma_f32_16x16x32_bf16 v[20:23], v[182:185], v[198:201], v[20:23]
	v_mfma_f32_16x16x32_bf16 v[32:35], v[174:177], v[210:213], v[32:35]
	v_mfma_f32_16x16x32_bf16 v[36:39], v[182:185], v[210:213], v[36:39]
	v_mfma_f32_16x16x32_bf16 v[8:11], v[174:177], v[218:221], v[8:11]
	v_mfma_f32_16x16x32_bf16 v[12:15], v[182:185], v[218:221], v[12:15]
	s_barrier
	s_setprio 0
	s_cmp_gt_u32 s31, 29
	s_cbranch_scc1 .LBB0_3144
	s_mov_b32 s31, s40
	s_branch .LBB0_3130

.LBB0_3613:
	s_add_i32 s70, s26, 2
	s_add_u32 s71, s22, 0x80
	s_addc_u32 s27, s23, 0
	s_add_i32 s95, 0, 0x10000
	s_cmp_eq_u32 s67, s26
	s_cselect_b32 s27, s40, s27
	s_cselect_b32 s26, s53, s71
	v_add_u32_e32 v155, s95, v143
	s_cselect_b32 s97, s58, s69
	s_cselect_b32 s96, s59, s68
	s_add_i32 s71, 0, 0x14000
	ds_read_b128 v[138:141], v155
	ds_read_b128 v[156:159], v155 offset:1024
	ds_read_b128 v[160:163], v155 offset:2048
	ds_read_b128 v[168:171], v155 offset:3072
	v_add_u32_e32 v155, s71, v143
	ds_read_b128 v[172:175], v155
	ds_read_b128 v[176:179], v155 offset:1024
	ds_read_b128 v[180:183], v155 offset:2048
	ds_read_b128 v[184:187], v155 offset:3072
	v_lshl_add_u64 v[222:223], s[22:23], 0, v[136:137]
	s_add_i32 m0, s12, 0xc000
	ds_read_b128 v[188:191], v154
	ds_read_b128 v[192:195], v154 offset:1024
	ds_read_b128 v[196:199], v154 offset:2048
	ds_read_b128 v[200:203], v154 offset:3072
	ds_read_b128 v[206:209], v154 offset:4096
	ds_read_b128 v[210:213], v154 offset:5120
	ds_read_b128 v[214:217], v154 offset:6144
	ds_read_b128 v[218:221], v154 offset:7168
	global_load_lds_dwordx4 v[222:223], off
	v_lshl_add_u64 v[222:223], s[22:23], 0, v[134:135]
	s_add_i32 m0, s12, 0xe000
	s_nop 0
	global_load_lds_dwordx4 v[222:223], off
	s_waitcnt vmcnt(8)
	s_waitcnt lgkmcnt(0)
	s_setprio 1
	s_barrier
	v_mfma_f32_16x16x32_bf16 v[124:127], v[138:141], v[188:191], v[124:127]
	v_mfma_f32_16x16x32_bf16 v[120:123], v[160:163], v[188:191], v[120:123]
	v_mfma_f32_16x16x32_bf16 v[108:111], v[138:141], v[196:199], v[108:111]
	v_mfma_f32_16x16x32_bf16 v[104:107], v[160:163], v[196:199], v[104:107]
	v_mfma_f32_16x16x32_bf16 v[92:95], v[138:141], v[206:209], v[92:95]
	v_mfma_f32_16x16x32_bf16 v[88:91], v[160:163], v[206:209], v[88:91]
	v_mfma_f32_16x16x32_bf16 v[76:79], v[138:141], v[214:217], v[76:79]
	v_mfma_f32_16x16x32_bf16 v[72:75], v[160:163], v[214:217], v[72:75]
	v_mfma_f32_16x16x32_bf16 v[124:127], v[156:159], v[192:195], v[124:127]
	v_mfma_f32_16x16x32_bf16 v[120:123], v[168:171], v[192:195], v[120:123]
	v_mfma_f32_16x16x32_bf16 v[108:111], v[156:159], v[200:203], v[108:111]
	v_mfma_f32_16x16x32_bf16 v[104:107], v[168:171], v[200:203], v[104:107]
	v_mfma_f32_16x16x32_bf16 v[92:95], v[156:159], v[210:213], v[92:95]
	v_mfma_f32_16x16x32_bf16 v[88:91], v[168:171], v[210:213], v[88:91]
	v_mfma_f32_16x16x32_bf16 v[76:79], v[156:159], v[218:221], v[76:79]
	v_mfma_f32_16x16x32_bf16 v[72:75], v[168:171], v[218:221], v[72:75]
	v_mfma_f32_16x16x32_bf16 v[116:119], v[172:175], v[188:191], v[116:119]
	v_mfma_f32_16x16x32_bf16 v[112:115], v[180:183], v[188:191], v[112:115]
	v_mfma_f32_16x16x32_bf16 v[100:103], v[172:175], v[196:199], v[100:103]
	v_mfma_f32_16x16x32_bf16 v[96:99], v[180:183], v[196:199], v[96:99]
	v_mfma_f32_16x16x32_bf16 v[84:87], v[172:175], v[206:209], v[84:87]
	v_mfma_f32_16x16x32_bf16 v[80:83], v[180:183], v[206:209], v[80:83]
	v_mfma_f32_16x16x32_bf16 v[68:71], v[172:175], v[214:217], v[68:71]
	v_mfma_f32_16x16x32_bf16 v[64:67], v[180:183], v[214:217], v[64:67]
	v_mfma_f32_16x16x32_bf16 v[116:119], v[176:179], v[192:195], v[116:119]
	v_mfma_f32_16x16x32_bf16 v[112:115], v[184:187], v[192:195], v[112:115]
	v_mfma_f32_16x16x32_bf16 v[100:103], v[176:179], v[200:203], v[100:103]
	v_mfma_f32_16x16x32_bf16 v[96:99], v[184:187], v[200:203], v[96:99]
	v_mfma_f32_16x16x32_bf16 v[84:87], v[176:179], v[210:213], v[84:87]
	v_mfma_f32_16x16x32_bf16 v[80:83], v[184:187], v[210:213], v[80:83]
	v_mfma_f32_16x16x32_bf16 v[68:71], v[176:179], v[218:221], v[68:71]
	v_mfma_f32_16x16x32_bf16 v[64:67], v[184:187], v[218:221], v[64:67]
	s_barrier
	s_setprio 0
	s_add_i32 s95, s95, s11
	v_lshl_add_u64 v[222:223], s[96:97], 0, v[144:145]
	s_mov_b32 m0, s95
	ds_read_b128 v[188:191], v154 offset:16384
	ds_read_b128 v[192:195], v154 offset:17408
	ds_read_b128 v[196:199], v154 offset:18432
	ds_read_b128 v[200:203], v154 offset:19456
	ds_read_b128 v[206:209], v154 offset:20480
	ds_read_b128 v[210:213], v154 offset:21504
	ds_read_b128 v[214:217], v154 offset:22528
	ds_read_b128 v[218:221], v154 offset:23552
	global_load_lds_dwordx4 v[222:223], off
	s_add_i32 m0, s95, 0x2000
	v_lshl_add_u64 v[224:225], s[96:97], 0, v[132:133]
	s_add_u32 s96, s96, s20
	s_addc_u32 s97, s97, 0
	s_add_i32 s71, s71, s11
	global_load_lds_dwordx4 v[224:225], off
	v_lshl_add_u64 v[226:227], s[96:97], 0, v[144:145]
	s_mov_b32 m0, s71
	v_lshl_add_u64 v[228:229], s[96:97], 0, v[132:133]
	global_load_lds_dwordx4 v[226:227], off
	s_add_i32 m0, s71, 0x2000
	v_lshl_add_u64 v[230:231], s[26:27], 0, v[128:129]
	global_load_lds_dwordx4 v[228:229], off
	s_mov_b32 m0, s12
	v_lshl_add_u64 v[232:233], s[26:27], 0, v[130:131]
	global_load_lds_dwordx4 v[230:231], off
	s_mov_b32 m0, s13
	s_nop 0
	global_load_lds_dwordx4 v[232:233], off
	s_waitcnt vmcnt(8)
	s_waitcnt lgkmcnt(0)
	s_setprio 1
	s_barrier
	v_mfma_f32_16x16x32_bf16 v[60:63], v[138:141], v[188:191], v[60:63]
	v_mfma_f32_16x16x32_bf16 v[56:59], v[160:163], v[188:191], v[56:59]
	v_mfma_f32_16x16x32_bf16 v[44:47], v[138:141], v[196:199], v[44:47]
	v_mfma_f32_16x16x32_bf16 v[40:43], v[160:163], v[196:199], v[40:43]
	v_mfma_f32_16x16x32_bf16 v[28:31], v[138:141], v[206:209], v[28:31]
	v_mfma_f32_16x16x32_bf16 v[24:27], v[160:163], v[206:209], v[24:27]
	v_mfma_f32_16x16x32_bf16 v[12:15], v[138:141], v[214:217], v[12:15]
	v_mfma_f32_16x16x32_bf16 v[8:11], v[160:163], v[214:217], v[8:11]
	v_mfma_f32_16x16x32_bf16 v[60:63], v[156:159], v[192:195], v[60:63]
	v_mfma_f32_16x16x32_bf16 v[56:59], v[168:171], v[192:195], v[56:59]
	v_mfma_f32_16x16x32_bf16 v[44:47], v[156:159], v[200:203], v[44:47]
	v_mfma_f32_16x16x32_bf16 v[40:43], v[168:171], v[200:203], v[40:43]
	v_mfma_f32_16x16x32_bf16 v[28:31], v[156:159], v[210:213], v[28:31]
	v_mfma_f32_16x16x32_bf16 v[24:27], v[168:171], v[210:213], v[24:27]
	v_mfma_f32_16x16x32_bf16 v[12:15], v[156:159], v[218:221], v[12:15]
	v_mfma_f32_16x16x32_bf16 v[8:11], v[168:171], v[218:221], v[8:11]
	v_mfma_f32_16x16x32_bf16 v[52:55], v[172:175], v[188:191], v[52:55]
	v_mfma_f32_16x16x32_bf16 v[48:51], v[180:183], v[188:191], v[48:51]
	v_mfma_f32_16x16x32_bf16 v[36:39], v[172:175], v[196:199], v[36:39]
	v_mfma_f32_16x16x32_bf16 v[32:35], v[180:183], v[196:199], v[32:35]
	v_mfma_f32_16x16x32_bf16 v[20:23], v[172:175], v[206:209], v[20:23]
	v_mfma_f32_16x16x32_bf16 v[16:19], v[180:183], v[206:209], v[16:19]
	v_mfma_f32_16x16x32_bf16 v[4:7], v[172:175], v[214:217], v[4:7]
	v_mfma_f32_16x16x32_bf16 v[0:3], v[180:183], v[214:217], v[0:3]
	v_mfma_f32_16x16x32_bf16 v[52:55], v[176:179], v[192:195], v[52:55]
	v_mfma_f32_16x16x32_bf16 v[48:51], v[184:187], v[192:195], v[48:51]
	v_mfma_f32_16x16x32_bf16 v[36:39], v[176:179], v[200:203], v[36:39]
	v_mfma_f32_16x16x32_bf16 v[32:35], v[184:187], v[200:203], v[32:35]
	v_mfma_f32_16x16x32_bf16 v[20:23], v[176:179], v[210:213], v[20:23]
	v_mfma_f32_16x16x32_bf16 v[16:19], v[184:187], v[210:213], v[16:19]
	v_mfma_f32_16x16x32_bf16 v[4:7], v[176:179], v[218:221], v[4:7]
	v_mfma_f32_16x16x32_bf16 v[0:3], v[184:187], v[218:221], v[0:3]
	s_barrier
	s_setprio 0
	s_add_i32 s71, 0, 0x18000
	v_add_u32_e32 v155, s71, v143
	s_add_i32 s95, 0, 0x1c000
	ds_read_b128 v[138:141], v155
	ds_read_b128 v[156:159], v155 offset:1024
	ds_read_b128 v[160:163], v155 offset:2048
	ds_read_b128 v[168:171], v155 offset:3072
	v_add_u32_e32 v155, s95, v143
	ds_read_b128 v[172:175], v155
	ds_read_b128 v[176:179], v155 offset:1024
	ds_read_b128 v[180:183], v155 offset:2048
	ds_read_b128 v[184:187], v155 offset:3072
	s_add_u32 s26, s26, s20
	s_addc_u32 s27, s27, 0
	s_mov_b32 m0, s28
	v_lshl_add_u64 v[234:235], s[26:27], 0, v[128:129]
	ds_read_b128 v[188:191], v154 offset:32768
	ds_read_b128 v[192:195], v154 offset:33792
	ds_read_b128 v[196:199], v154 offset:34816
	ds_read_b128 v[200:203], v154 offset:35840
	ds_read_b128 v[206:209], v154 offset:36864
	ds_read_b128 v[210:213], v154 offset:37888
	ds_read_b128 v[214:217], v154 offset:38912
	ds_read_b128 v[218:221], v154 offset:39936
	global_load_lds_dwordx4 v[234:235], off
	v_lshl_add_u64 v[234:235], s[26:27], 0, v[130:131]
	s_mov_b32 m0, s29
	s_nop 0
	global_load_lds_dwordx4 v[234:235], off
	s_waitcnt vmcnt(8)
	s_waitcnt lgkmcnt(0)
	s_setprio 1
	s_barrier
	v_mfma_f32_16x16x32_bf16 v[124:127], v[138:141], v[188:191], v[124:127]
	v_mfma_f32_16x16x32_bf16 v[120:123], v[160:163], v[188:191], v[120:123]
	v_mfma_f32_16x16x32_bf16 v[108:111], v[138:141], v[196:199], v[108:111]
	v_mfma_f32_16x16x32_bf16 v[104:107], v[160:163], v[196:199], v[104:107]
	v_mfma_f32_16x16x32_bf16 v[92:95], v[138:141], v[206:209], v[92:95]
	v_mfma_f32_16x16x32_bf16 v[88:91], v[160:163], v[206:209], v[88:91]
	v_mfma_f32_16x16x32_bf16 v[76:79], v[138:141], v[214:217], v[76:79]
	v_mfma_f32_16x16x32_bf16 v[72:75], v[160:163], v[214:217], v[72:75]
	v_mfma_f32_16x16x32_bf16 v[124:127], v[156:159], v[192:195], v[124:127]
	v_mfma_f32_16x16x32_bf16 v[120:123], v[168:171], v[192:195], v[120:123]
	v_mfma_f32_16x16x32_bf16 v[108:111], v[156:159], v[200:203], v[108:111]
	v_mfma_f32_16x16x32_bf16 v[104:107], v[168:171], v[200:203], v[104:107]
	v_mfma_f32_16x16x32_bf16 v[92:95], v[156:159], v[210:213], v[92:95]
	v_mfma_f32_16x16x32_bf16 v[88:91], v[168:171], v[210:213], v[88:91]
	v_mfma_f32_16x16x32_bf16 v[76:79], v[156:159], v[218:221], v[76:79]
	v_mfma_f32_16x16x32_bf16 v[72:75], v[168:171], v[218:221], v[72:75]
	v_mfma_f32_16x16x32_bf16 v[116:119], v[172:175], v[188:191], v[116:119]
	v_mfma_f32_16x16x32_bf16 v[112:115], v[180:183], v[188:191], v[112:115]
	v_mfma_f32_16x16x32_bf16 v[100:103], v[172:175], v[196:199], v[100:103]
	v_mfma_f32_16x16x32_bf16 v[96:99], v[180:183], v[196:199], v[96:99]
	v_mfma_f32_16x16x32_bf16 v[84:87], v[172:175], v[206:209], v[84:87]
	v_mfma_f32_16x16x32_bf16 v[80:83], v[180:183], v[206:209], v[80:83]
	v_mfma_f32_16x16x32_bf16 v[68:71], v[172:175], v[214:217], v[68:71]
	v_mfma_f32_16x16x32_bf16 v[64:67], v[180:183], v[214:217], v[64:67]
	v_mfma_f32_16x16x32_bf16 v[116:119], v[176:179], v[192:195], v[116:119]
	v_mfma_f32_16x16x32_bf16 v[112:115], v[184:187], v[192:195], v[112:115]
	v_mfma_f32_16x16x32_bf16 v[100:103], v[176:179], v[200:203], v[100:103]
	v_mfma_f32_16x16x32_bf16 v[96:99], v[184:187], v[200:203], v[96:99]
	v_mfma_f32_16x16x32_bf16 v[84:87], v[176:179], v[210:213], v[84:87]
	v_mfma_f32_16x16x32_bf16 v[80:83], v[184:187], v[210:213], v[80:83]
	v_mfma_f32_16x16x32_bf16 v[68:71], v[176:179], v[218:221], v[68:71]
	v_mfma_f32_16x16x32_bf16 v[64:67], v[184:187], v[218:221], v[64:67]
	s_barrier
	s_setprio 0
	s_add_i32 s26, s71, s11
	v_lshl_add_u64 v[222:223], v[222:223], 0, s[42:43]
	s_mov_b32 m0, s26
	ds_read_b128 v[188:191], v154 offset:49152
	ds_read_b128 v[192:195], v154 offset:50176
	ds_read_b128 v[196:199], v154 offset:51200
	ds_read_b128 v[200:203], v154 offset:52224
	ds_read_b128 v[206:209], v154 offset:53248
	ds_read_b128 v[210:213], v154 offset:54272
	ds_read_b128 v[214:217], v154 offset:55296
	ds_read_b128 v[218:221], v154 offset:56320
	global_load_lds_dwordx4 v[222:223], off
	v_lshl_add_u64 v[222:223], v[224:225], 0, s[42:43]
	s_add_i32 m0, s26, 0x2000
	s_add_i32 s26, s95, s11
	global_load_lds_dwordx4 v[222:223], off
	v_lshl_add_u64 v[222:223], v[226:227], 0, s[42:43]
	s_mov_b32 m0, s26
	s_nop 0
	global_load_lds_dwordx4 v[222:223], off
	v_lshl_add_u64 v[222:223], v[228:229], 0, s[42:43]
	s_add_i32 m0, s26, 0x2000
	s_nop 0
	global_load_lds_dwordx4 v[222:223], off
	v_lshl_add_u64 v[222:223], v[230:231], 0, s[42:43]
	s_mov_b32 m0, s62
	s_nop 0
	global_load_lds_dwordx4 v[222:223], off
	v_lshl_add_u64 v[222:223], v[232:233], 0, s[42:43]
	s_mov_b32 m0, s63
	s_nop 0
	global_load_lds_dwordx4 v[222:223], off
	s_waitcnt vmcnt(8)
	s_waitcnt lgkmcnt(0)
	s_setprio 1
	s_barrier
	v_mfma_f32_16x16x32_bf16 v[60:63], v[138:141], v[188:191], v[60:63]
	v_mfma_f32_16x16x32_bf16 v[56:59], v[160:163], v[188:191], v[56:59]
	v_mfma_f32_16x16x32_bf16 v[44:47], v[138:141], v[196:199], v[44:47]
	v_mfma_f32_16x16x32_bf16 v[40:43], v[160:163], v[196:199], v[40:43]
	v_mfma_f32_16x16x32_bf16 v[28:31], v[138:141], v[206:209], v[28:31]
	v_mfma_f32_16x16x32_bf16 v[24:27], v[160:163], v[206:209], v[24:27]
	v_mfma_f32_16x16x32_bf16 v[12:15], v[138:141], v[214:217], v[12:15]
	v_mfma_f32_16x16x32_bf16 v[8:11], v[160:163], v[214:217], v[8:11]
	v_mfma_f32_16x16x32_bf16 v[60:63], v[156:159], v[192:195], v[60:63]
	v_mfma_f32_16x16x32_bf16 v[56:59], v[168:171], v[192:195], v[56:59]
	v_mfma_f32_16x16x32_bf16 v[44:47], v[156:159], v[200:203], v[44:47]
	v_mfma_f32_16x16x32_bf16 v[40:43], v[168:171], v[200:203], v[40:43]
	v_mfma_f32_16x16x32_bf16 v[28:31], v[156:159], v[210:213], v[28:31]
	v_mfma_f32_16x16x32_bf16 v[24:27], v[168:171], v[210:213], v[24:27]
	v_mfma_f32_16x16x32_bf16 v[12:15], v[156:159], v[218:221], v[12:15]
	v_mfma_f32_16x16x32_bf16 v[8:11], v[168:171], v[218:221], v[8:11]
	v_mfma_f32_16x16x32_bf16 v[52:55], v[172:175], v[188:191], v[52:55]
	v_mfma_f32_16x16x32_bf16 v[48:51], v[180:183], v[188:191], v[48:51]
	v_mfma_f32_16x16x32_bf16 v[36:39], v[172:175], v[196:199], v[36:39]
	v_mfma_f32_16x16x32_bf16 v[32:35], v[180:183], v[196:199], v[32:35]
	v_mfma_f32_16x16x32_bf16 v[20:23], v[172:175], v[206:209], v[20:23]
	v_mfma_f32_16x16x32_bf16 v[16:19], v[180:183], v[206:209], v[16:19]
	v_mfma_f32_16x16x32_bf16 v[4:7], v[172:175], v[214:217], v[4:7]
	v_mfma_f32_16x16x32_bf16 v[0:3], v[180:183], v[214:217], v[0:3]
	v_mfma_f32_16x16x32_bf16 v[52:55], v[176:179], v[192:195], v[52:55]
	v_mfma_f32_16x16x32_bf16 v[48:51], v[184:187], v[192:195], v[48:51]
	v_mfma_f32_16x16x32_bf16 v[36:39], v[176:179], v[200:203], v[36:39]
	v_mfma_f32_16x16x32_bf16 v[32:35], v[184:187], v[200:203], v[32:35]
	v_mfma_f32_16x16x32_bf16 v[20:23], v[176:179], v[210:213], v[20:23]
	v_mfma_f32_16x16x32_bf16 v[16:19], v[184:187], v[210:213], v[16:19]
	v_mfma_f32_16x16x32_bf16 v[4:7], v[176:179], v[218:221], v[4:7]
	v_mfma_f32_16x16x32_bf16 v[0:3], v[184:187], v[218:221], v[0:3]
	s_barrier
	s_setprio 0
	s_add_u32 s68, s68, 0x100
	s_addc_u32 s69, s69, 0
	s_add_u32 s22, s22, 0x100
	s_addc_u32 s23, s23, 0
	s_cmp_ge_i32 s70, s1
	s_mov_b32 s26, s70
	s_cbranch_scc0 .LBB0_3613
	s_and_b64 vcc, exec, s[46:47]
	s_cbranch_vccz .LBB0_3616
	s_barrier

.LBB0_3760:
	s_or_b32 s40, s63, 1
	s_lshl_b64 s[80:81], s[40:41], 7
	s_add_i32 s40, s63, 2
	s_lshl_b64 s[82:83], s[40:41], 7
	v_add_u32_e32 v140, s30, v177
	v_add_u32_e32 v180, s31, v177
	s_add_u32 s79, s58, s82
	ds_read_b128 v[128:131], v140
	ds_read_b128 v[132:135], v140 offset:1024
	ds_read_b128 v[136:139], v140 offset:2048
	ds_read_b128 v[140:143], v140 offset:3072
	ds_read_b128 v[162:165], v180
	ds_read_b128 v[166:169], v180 offset:1024
	ds_read_b128 v[170:173], v180 offset:2048
	ds_read_b128 v[180:183], v180 offset:3072
	s_addc_u32 s84, s59, s83
	s_and_b64 s[70:71], s[68:69], exec
	s_cselect_b32 s71, s84, s51
	s_cselect_b32 s70, s79, s50
	s_add_u32 s79, s60, s82
	s_addc_u32 s82, s61, s83
	s_and_b64 s[68:69], s[68:69], exec
	s_cselect_b32 s69, s82, s53
	s_cselect_b32 s68, s79, s52
	s_add_u32 s79, s58, s80
	s_addc_u32 s81, s59, s81
	s_add_u32 s80, s79, 0x80000
	s_addc_u32 s81, s81, 0
	v_lshl_add_u64 v[218:219], s[80:81], 0, v[144:145]
	s_add_i32 m0, s7, 0xc000
	ds_read_b128 v[184:187], v152
	ds_read_b128 v[188:191], v152 offset:1024
	ds_read_b128 v[192:195], v152 offset:2048
	ds_read_b128 v[196:199], v152 offset:3072
	ds_read_b128 v[200:203], v152 offset:4096
	ds_read_b128 v[206:209], v152 offset:5120
	ds_read_b128 v[210:213], v152 offset:6144
	ds_read_b128 v[214:217], v152 offset:7168
	global_load_lds_dwordx4 v[218:219], off
	v_lshl_add_u64 v[218:219], s[80:81], 0, v[148:149]
	s_add_i32 m0, s7, 0xe000
	s_nop 0
	global_load_lds_dwordx4 v[218:219], off
	s_waitcnt vmcnt(8)
	s_waitcnt lgkmcnt(0)
	s_setprio 1
	s_barrier
	v_mfma_f32_16x16x32_bf16 v[124:127], v[128:131], v[184:187], v[124:127]
	v_mfma_f32_16x16x32_bf16 v[120:123], v[136:139], v[184:187], v[120:123]
	v_mfma_f32_16x16x32_bf16 v[112:115], v[128:131], v[192:195], v[112:115]
	v_mfma_f32_16x16x32_bf16 v[104:107], v[136:139], v[192:195], v[104:107]
	v_mfma_f32_16x16x32_bf16 v[96:99], v[128:131], v[200:203], v[96:99]
	v_mfma_f32_16x16x32_bf16 v[88:91], v[136:139], v[200:203], v[88:91]
	v_mfma_f32_16x16x32_bf16 v[80:83], v[128:131], v[210:213], v[80:83]
	v_mfma_f32_16x16x32_bf16 v[72:75], v[136:139], v[210:213], v[72:75]
	v_mfma_f32_16x16x32_bf16 v[124:127], v[132:135], v[188:191], v[124:127]
	v_mfma_f32_16x16x32_bf16 v[120:123], v[140:143], v[188:191], v[120:123]
	v_mfma_f32_16x16x32_bf16 v[112:115], v[132:135], v[196:199], v[112:115]
	v_mfma_f32_16x16x32_bf16 v[104:107], v[140:143], v[196:199], v[104:107]
	v_mfma_f32_16x16x32_bf16 v[96:99], v[132:135], v[206:209], v[96:99]
	v_mfma_f32_16x16x32_bf16 v[88:91], v[140:143], v[206:209], v[88:91]
	v_mfma_f32_16x16x32_bf16 v[80:83], v[132:135], v[214:217], v[80:83]
	v_mfma_f32_16x16x32_bf16 v[72:75], v[140:143], v[214:217], v[72:75]
	v_mfma_f32_16x16x32_bf16 v[116:119], v[162:165], v[184:187], v[116:119]
	v_mfma_f32_16x16x32_bf16 v[108:111], v[170:173], v[184:187], v[108:111]
	v_mfma_f32_16x16x32_bf16 v[100:103], v[162:165], v[192:195], v[100:103]
	v_mfma_f32_16x16x32_bf16 v[92:95], v[170:173], v[192:195], v[92:95]
	v_mfma_f32_16x16x32_bf16 v[84:87], v[162:165], v[200:203], v[84:87]
	v_mfma_f32_16x16x32_bf16 v[76:79], v[170:173], v[200:203], v[76:79]
	v_mfma_f32_16x16x32_bf16 v[68:71], v[162:165], v[210:213], v[68:71]
	v_mfma_f32_16x16x32_bf16 v[64:67], v[170:173], v[210:213], v[64:67]
	v_mfma_f32_16x16x32_bf16 v[116:119], v[166:169], v[188:191], v[116:119]
	v_mfma_f32_16x16x32_bf16 v[108:111], v[180:183], v[188:191], v[108:111]
	v_mfma_f32_16x16x32_bf16 v[100:103], v[166:169], v[196:199], v[100:103]
	v_mfma_f32_16x16x32_bf16 v[92:95], v[180:183], v[196:199], v[92:95]
	v_mfma_f32_16x16x32_bf16 v[84:87], v[166:169], v[206:209], v[84:87]
	v_mfma_f32_16x16x32_bf16 v[76:79], v[180:183], v[206:209], v[76:79]
	v_mfma_f32_16x16x32_bf16 v[68:71], v[166:169], v[214:217], v[68:71]
	v_mfma_f32_16x16x32_bf16 v[64:67], v[180:183], v[214:217], v[64:67]
	s_barrier
	s_setprio 0
	s_add_i32 s79, s30, s6
	v_lshl_add_u64 v[218:219], s[68:69], 0, v[146:147]
	s_mov_b32 m0, s79
	ds_read_b128 v[184:187], v152 offset:16384
	ds_read_b128 v[188:191], v152 offset:17408
	ds_read_b128 v[192:195], v152 offset:18432
	ds_read_b128 v[196:199], v152 offset:19456
	ds_read_b128 v[200:203], v152 offset:20480
	ds_read_b128 v[206:209], v152 offset:21504
	ds_read_b128 v[210:213], v152 offset:22528
	ds_read_b128 v[214:217], v152 offset:23552
	global_load_lds_dwordx4 v[218:219], off
	s_add_i32 m0, s79, 0x2000
	s_add_u32 s80, s68, 0x80000
	v_lshl_add_u64 v[220:221], s[68:69], 0, v[150:151]
	s_addc_u32 s81, s69, 0
	s_add_i32 s79, s31, s6
	global_load_lds_dwordx4 v[220:221], off
	v_lshl_add_u64 v[222:223], s[80:81], 0, v[146:147]
	s_mov_b32 m0, s79
	v_lshl_add_u64 v[224:225], s[70:71], 0, v[148:149]
	global_load_lds_dwordx4 v[222:223], off
	v_lshl_add_u64 v[222:223], s[80:81], 0, v[150:151]
	s_add_i32 m0, s79, 0x2000
	s_nop 0
	global_load_lds_dwordx4 v[222:223], off
	v_lshl_add_u64 v[222:223], s[70:71], 0, v[144:145]
	s_mov_b32 m0, s7
	s_nop 0
	global_load_lds_dwordx4 v[222:223], off
	s_mov_b32 m0, s8
	s_nop 0
	global_load_lds_dwordx4 v[224:225], off
	s_waitcnt vmcnt(8)
	s_waitcnt lgkmcnt(0)
	s_setprio 1
	s_barrier
	v_mfma_f32_16x16x32_bf16 v[60:63], v[128:131], v[184:187], v[60:63]
	v_mfma_f32_16x16x32_bf16 v[56:59], v[136:139], v[184:187], v[56:59]
	v_mfma_f32_16x16x32_bf16 v[48:51], v[128:131], v[192:195], v[48:51]
	v_mfma_f32_16x16x32_bf16 v[32:35], v[136:139], v[192:195], v[32:35]
	v_mfma_f32_16x16x32_bf16 v[16:19], v[128:131], v[200:203], v[16:19]
	v_mfma_f32_16x16x32_bf16 v[12:15], v[136:139], v[200:203], v[12:15]
	v_mfma_f32_16x16x32_bf16 v[4:7], v[128:131], v[210:213], v[4:7]
	v_mfma_f32_16x16x32_bf16 v[0:3], v[136:139], v[210:213], v[0:3]
	v_mfma_f32_16x16x32_bf16 v[60:63], v[132:135], v[188:191], v[60:63]
	v_mfma_f32_16x16x32_bf16 v[56:59], v[140:143], v[188:191], v[56:59]
	v_mfma_f32_16x16x32_bf16 v[48:51], v[132:135], v[196:199], v[48:51]
	v_mfma_f32_16x16x32_bf16 v[32:35], v[140:143], v[196:199], v[32:35]
	v_mfma_f32_16x16x32_bf16 v[16:19], v[132:135], v[206:209], v[16:19]
	v_mfma_f32_16x16x32_bf16 v[12:15], v[140:143], v[206:209], v[12:15]
	v_mfma_f32_16x16x32_bf16 v[4:7], v[132:135], v[214:217], v[4:7]
	v_mfma_f32_16x16x32_bf16 v[0:3], v[140:143], v[214:217], v[0:3]
	v_mfma_f32_16x16x32_bf16 v[52:55], v[162:165], v[184:187], v[52:55]
	v_mfma_f32_16x16x32_bf16 v[36:39], v[170:173], v[184:187], v[36:39]
	v_mfma_f32_16x16x32_bf16 v[20:23], v[162:165], v[192:195], v[20:23]
	v_mfma_f32_16x16x32_bf16 v[8:11], v[170:173], v[192:195], v[8:11]
	v_mfma_f32_16x16x32_bf16 v[40:43], v[162:165], v[200:203], v[40:43]
	v_mfma_f32_16x16x32_bf16 v[44:47], v[170:173], v[200:203], v[44:47]
	v_mfma_f32_16x16x32_bf16 v[24:27], v[162:165], v[210:213], v[24:27]
	v_mfma_f32_16x16x32_bf16 v[28:31], v[170:173], v[210:213], v[28:31]
	v_mfma_f32_16x16x32_bf16 v[52:55], v[166:169], v[188:191], v[52:55]
	v_mfma_f32_16x16x32_bf16 v[36:39], v[180:183], v[188:191], v[36:39]
	v_mfma_f32_16x16x32_bf16 v[20:23], v[166:169], v[196:199], v[20:23]
	v_mfma_f32_16x16x32_bf16 v[8:11], v[180:183], v[196:199], v[8:11]
	v_mfma_f32_16x16x32_bf16 v[40:43], v[166:169], v[206:209], v[40:43]
	v_mfma_f32_16x16x32_bf16 v[44:47], v[180:183], v[206:209], v[44:47]
	v_mfma_f32_16x16x32_bf16 v[24:27], v[166:169], v[214:217], v[24:27]
	v_mfma_f32_16x16x32_bf16 v[28:31], v[180:183], v[214:217], v[28:31]
	s_barrier
	s_setprio 0
	v_add_u32_e32 v140, s55, v177
	v_add_u32_e32 v180, s57, v177
	ds_read_b128 v[128:131], v140
	ds_read_b128 v[132:135], v140 offset:1024
	ds_read_b128 v[136:139], v140 offset:2048
	ds_read_b128 v[140:143], v140 offset:3072
	ds_read_b128 v[162:165], v180
	ds_read_b128 v[166:169], v180 offset:1024
	ds_read_b128 v[170:173], v180 offset:2048
	ds_read_b128 v[180:183], v180 offset:3072
	s_add_u32 s70, s70, 0x80000
	s_addc_u32 s71, s71, 0
	s_mov_b32 m0, s9
	v_lshl_add_u64 v[226:227], s[70:71], 0, v[144:145]
	ds_read_b128 v[184:187], v152 offset:32768
	ds_read_b128 v[188:191], v152 offset:33792
	ds_read_b128 v[192:195], v152 offset:34816
	ds_read_b128 v[196:199], v152 offset:35840
	ds_read_b128 v[200:203], v152 offset:36864
	ds_read_b128 v[206:209], v152 offset:37888
	ds_read_b128 v[210:213], v152 offset:38912
	ds_read_b128 v[214:217], v152 offset:39936
	global_load_lds_dwordx4 v[226:227], off
	v_lshl_add_u64 v[226:227], s[70:71], 0, v[148:149]
	s_mov_b32 m0, s10
	s_nop 0
	global_load_lds_dwordx4 v[226:227], off
	s_waitcnt vmcnt(8)
	s_waitcnt lgkmcnt(0)
	s_setprio 1
	s_barrier
	v_mfma_f32_16x16x32_bf16 v[124:127], v[128:131], v[184:187], v[124:127]
	v_mfma_f32_16x16x32_bf16 v[120:123], v[136:139], v[184:187], v[120:123]
	v_mfma_f32_16x16x32_bf16 v[112:115], v[128:131], v[192:195], v[112:115]
	v_mfma_f32_16x16x32_bf16 v[104:107], v[136:139], v[192:195], v[104:107]
	v_mfma_f32_16x16x32_bf16 v[96:99], v[128:131], v[200:203], v[96:99]
	v_mfma_f32_16x16x32_bf16 v[88:91], v[136:139], v[200:203], v[88:91]
	v_mfma_f32_16x16x32_bf16 v[80:83], v[128:131], v[210:213], v[80:83]
	v_mfma_f32_16x16x32_bf16 v[72:75], v[136:139], v[210:213], v[72:75]
	v_mfma_f32_16x16x32_bf16 v[124:127], v[132:135], v[188:191], v[124:127]
	v_mfma_f32_16x16x32_bf16 v[120:123], v[140:143], v[188:191], v[120:123]
	v_mfma_f32_16x16x32_bf16 v[112:115], v[132:135], v[196:199], v[112:115]
	v_mfma_f32_16x16x32_bf16 v[104:107], v[140:143], v[196:199], v[104:107]
	v_mfma_f32_16x16x32_bf16 v[96:99], v[132:135], v[206:209], v[96:99]
	v_mfma_f32_16x16x32_bf16 v[88:91], v[140:143], v[206:209], v[88:91]
	v_mfma_f32_16x16x32_bf16 v[80:83], v[132:135], v[214:217], v[80:83]
	v_mfma_f32_16x16x32_bf16 v[72:75], v[140:143], v[214:217], v[72:75]
	v_mfma_f32_16x16x32_bf16 v[116:119], v[162:165], v[184:187], v[116:119]
	v_mfma_f32_16x16x32_bf16 v[108:111], v[170:173], v[184:187], v[108:111]
	v_mfma_f32_16x16x32_bf16 v[100:103], v[162:165], v[192:195], v[100:103]
	v_mfma_f32_16x16x32_bf16 v[92:95], v[170:173], v[192:195], v[92:95]
	v_mfma_f32_16x16x32_bf16 v[84:87], v[162:165], v[200:203], v[84:87]
	v_mfma_f32_16x16x32_bf16 v[76:79], v[170:173], v[200:203], v[76:79]
	v_mfma_f32_16x16x32_bf16 v[68:71], v[162:165], v[210:213], v[68:71]
	v_mfma_f32_16x16x32_bf16 v[64:67], v[170:173], v[210:213], v[64:67]
	v_mfma_f32_16x16x32_bf16 v[116:119], v[166:169], v[188:191], v[116:119]
	v_mfma_f32_16x16x32_bf16 v[108:111], v[180:183], v[188:191], v[108:111]
	v_mfma_f32_16x16x32_bf16 v[100:103], v[166:169], v[196:199], v[100:103]
	v_mfma_f32_16x16x32_bf16 v[92:95], v[180:183], v[196:199], v[92:95]
	v_mfma_f32_16x16x32_bf16 v[84:87], v[166:169], v[206:209], v[84:87]
	v_mfma_f32_16x16x32_bf16 v[76:79], v[180:183], v[206:209], v[76:79]
	v_mfma_f32_16x16x32_bf16 v[68:71], v[166:169], v[214:217], v[68:71]
	v_mfma_f32_16x16x32_bf16 v[64:67], v[180:183], v[214:217], v[64:67]
	s_barrier
	s_setprio 0
	s_add_i32 s70, s55, s6
	v_lshl_add_u64 v[218:219], v[218:219], 0, s[26:27]
	s_mov_b32 m0, s70
	ds_read_b128 v[184:187], v152 offset:49152
	ds_read_b128 v[188:191], v152 offset:50176
	ds_read_b128 v[192:195], v152 offset:51200
	ds_read_b128 v[196:199], v152 offset:52224
	ds_read_b128 v[200:203], v152 offset:53248
	ds_read_b128 v[206:209], v152 offset:54272
	ds_read_b128 v[210:213], v152 offset:55296
	ds_read_b128 v[214:217], v152 offset:56320
	global_load_lds_dwordx4 v[218:219], off
	s_add_i32 m0, s70, 0x2000
	s_add_u32 s68, s68, 0x80080
	v_lshl_add_u64 v[218:219], v[220:221], 0, s[26:27]
	s_addc_u32 s69, s69, 0
	s_add_i32 s70, s57, s6
	global_load_lds_dwordx4 v[218:219], off
	v_lshl_add_u64 v[218:219], s[68:69], 0, v[146:147]
	s_mov_b32 m0, s70
	s_nop 0
	global_load_lds_dwordx4 v[218:219], off
	v_lshl_add_u64 v[218:219], s[68:69], 0, v[150:151]
	s_add_i32 m0, s70, 0x2000
	s_nop 0
	global_load_lds_dwordx4 v[218:219], off
	v_lshl_add_u64 v[218:219], v[222:223], 0, s[26:27]
	s_mov_b32 m0, s11
	s_nop 0
	global_load_lds_dwordx4 v[218:219], off
	v_lshl_add_u64 v[218:219], v[224:225], 0, s[26:27]
	s_mov_b32 m0, s12
	s_nop 0
	global_load_lds_dwordx4 v[218:219], off
	s_waitcnt vmcnt(8)
	s_waitcnt lgkmcnt(0)
	s_setprio 1
	s_barrier
	v_mfma_f32_16x16x32_bf16 v[60:63], v[128:131], v[184:187], v[60:63]
	v_mfma_f32_16x16x32_bf16 v[56:59], v[136:139], v[184:187], v[56:59]
	v_mfma_f32_16x16x32_bf16 v[48:51], v[128:131], v[192:195], v[48:51]
	v_mfma_f32_16x16x32_bf16 v[32:35], v[136:139], v[192:195], v[32:35]
	v_mfma_f32_16x16x32_bf16 v[16:19], v[128:131], v[200:203], v[16:19]
	v_mfma_f32_16x16x32_bf16 v[12:15], v[136:139], v[200:203], v[12:15]
	v_mfma_f32_16x16x32_bf16 v[4:7], v[128:131], v[210:213], v[4:7]
	v_mfma_f32_16x16x32_bf16 v[0:3], v[136:139], v[210:213], v[0:3]
	v_mfma_f32_16x16x32_bf16 v[60:63], v[132:135], v[188:191], v[60:63]
	v_mfma_f32_16x16x32_bf16 v[56:59], v[140:143], v[188:191], v[56:59]
	v_mfma_f32_16x16x32_bf16 v[48:51], v[132:135], v[196:199], v[48:51]
	v_mfma_f32_16x16x32_bf16 v[32:35], v[140:143], v[196:199], v[32:35]
	v_mfma_f32_16x16x32_bf16 v[16:19], v[132:135], v[206:209], v[16:19]
	v_mfma_f32_16x16x32_bf16 v[12:15], v[140:143], v[206:209], v[12:15]
	v_mfma_f32_16x16x32_bf16 v[4:7], v[132:135], v[214:217], v[4:7]
	v_mfma_f32_16x16x32_bf16 v[0:3], v[140:143], v[214:217], v[0:3]
	v_mfma_f32_16x16x32_bf16 v[52:55], v[162:165], v[184:187], v[52:55]
	v_mfma_f32_16x16x32_bf16 v[36:39], v[170:173], v[184:187], v[36:39]
	v_mfma_f32_16x16x32_bf16 v[20:23], v[162:165], v[192:195], v[20:23]
	v_mfma_f32_16x16x32_bf16 v[8:11], v[170:173], v[192:195], v[8:11]
	v_mfma_f32_16x16x32_bf16 v[40:43], v[162:165], v[200:203], v[40:43]
	v_mfma_f32_16x16x32_bf16 v[44:47], v[170:173], v[200:203], v[44:47]
	v_mfma_f32_16x16x32_bf16 v[24:27], v[162:165], v[210:213], v[24:27]
	v_mfma_f32_16x16x32_bf16 v[28:31], v[170:173], v[210:213], v[28:31]
	v_mfma_f32_16x16x32_bf16 v[52:55], v[166:169], v[188:191], v[52:55]
	v_mfma_f32_16x16x32_bf16 v[36:39], v[180:183], v[188:191], v[36:39]
	v_mfma_f32_16x16x32_bf16 v[20:23], v[166:169], v[196:199], v[20:23]
	v_mfma_f32_16x16x32_bf16 v[8:11], v[180:183], v[196:199], v[8:11]
	v_mfma_f32_16x16x32_bf16 v[40:43], v[166:169], v[206:209], v[40:43]
	v_mfma_f32_16x16x32_bf16 v[44:47], v[180:183], v[206:209], v[44:47]
	v_mfma_f32_16x16x32_bf16 v[24:27], v[166:169], v[214:217], v[24:27]
	v_mfma_f32_16x16x32_bf16 v[28:31], v[180:183], v[214:217], v[28:31]
	s_barrier
	s_setprio 0
	s_cmp_gt_u32 s63, 29
	s_cbranch_scc1 .LBB0_3762
	s_mov_b32 s63, s40
	s_branch .LBB0_3748

.LBB0_6333:
	s_or_b32 s62, s23, 1
	s_lshl_b64 vcc, s[62:63], 7
	s_add_i32 s62, s23, 2
	s_lshl_b64 s[76:77], s[62:63], 7
	v_add_u32_e32 v12, s53, v201
	v_add_u32_e32 v157, s57, v201
	s_add_u32 s28, s0, s76
	ds_read_b128 v[0:3], v12
	ds_read_b128 v[4:7], v12 offset:1024
	ds_read_b128 v[8:11], v12 offset:2048
	ds_read_b128 v[12:15], v12 offset:3072
	ds_read_b128 v[144:147], v157
	ds_read_b128 v[166:169], v157 offset:1024
	ds_read_b128 v[170:173], v157 offset:2048
	ds_read_b128 v[174:177], v157 offset:3072
	s_addc_u32 s93, s1, s77
	s_and_b64 s[44:45], s[42:43], exec
	s_cselect_b32 s45, s93, s81
	s_cselect_b32 s44, s28, s80
	s_add_u32 s28, s20, s76
	s_addc_u32 s76, s21, s77
	s_and_b64 s[42:43], s[42:43], exec
	s_cselect_b32 s43, s76, s83
	s_cselect_b32 s42, s28, s82
	s_add_u32 s28, s0, vcc_lo
	s_addc_u32 s77, s1, vcc_hi
	s_add_u32 s76, s28, 0x80000
	s_addc_u32 s77, s77, 0
	v_lshl_add_u64 v[224:225], s[76:77], 0, v[148:149]
	s_add_i32 m0, s5, 0xc000
	ds_read_b128 v[178:181], v209
	ds_read_b128 v[182:185], v209 offset:1024
	ds_read_b128 v[186:189], v209 offset:2048
	ds_read_b128 v[190:193], v209 offset:3072
	ds_read_b128 v[194:197], v209 offset:4096
	ds_read_b128 v[212:215], v209 offset:5120
	ds_read_b128 v[216:219], v209 offset:6144
	ds_read_b128 v[220:223], v209 offset:7168
	global_load_lds_dwordx4 v[224:225], off
	v_lshl_add_u64 v[224:225], s[76:77], 0, v[152:153]
	s_add_i32 m0, s5, 0xe000
	s_nop 0
	global_load_lds_dwordx4 v[224:225], off
	s_waitcnt vmcnt(8)
	s_waitcnt lgkmcnt(0)
	s_setprio 1
	s_barrier
	v_mfma_f32_16x16x32_bf16 v[108:111], v[0:3], v[178:181], v[108:111]
	v_mfma_f32_16x16x32_bf16 v[104:107], v[8:11], v[178:181], v[104:107]
	v_mfma_f32_16x16x32_bf16 v[124:127], v[0:3], v[186:189], v[124:127]
	v_mfma_f32_16x16x32_bf16 v[116:119], v[8:11], v[186:189], v[116:119]
	v_mfma_f32_16x16x32_bf16 v[120:123], v[0:3], v[194:197], v[120:123]
	v_mfma_f32_16x16x32_bf16 v[112:115], v[8:11], v[194:197], v[112:115]
	v_mfma_f32_16x16x32_bf16 v[92:95], v[0:3], v[216:219], v[92:95]
	v_mfma_f32_16x16x32_bf16 v[88:91], v[8:11], v[216:219], v[88:91]
	v_mfma_f32_16x16x32_bf16 v[108:111], v[4:7], v[182:185], v[108:111]
	v_mfma_f32_16x16x32_bf16 v[104:107], v[12:15], v[182:185], v[104:107]
	v_mfma_f32_16x16x32_bf16 v[124:127], v[4:7], v[190:193], v[124:127]
	v_mfma_f32_16x16x32_bf16 v[116:119], v[12:15], v[190:193], v[116:119]
	v_mfma_f32_16x16x32_bf16 v[120:123], v[4:7], v[212:215], v[120:123]
	v_mfma_f32_16x16x32_bf16 v[112:115], v[12:15], v[212:215], v[112:115]
	v_mfma_f32_16x16x32_bf16 v[92:95], v[4:7], v[220:223], v[92:95]
	v_mfma_f32_16x16x32_bf16 v[88:91], v[12:15], v[220:223], v[88:91]
	v_mfma_f32_16x16x32_bf16 v[140:143], v[144:147], v[178:181], v[140:143]
	v_mfma_f32_16x16x32_bf16 v[136:139], v[170:173], v[178:181], v[136:139]
	v_mfma_f32_16x16x32_bf16 v[132:135], v[144:147], v[186:189], v[132:135]
	v_mfma_f32_16x16x32_bf16 v[128:131], v[170:173], v[186:189], v[128:131]
	v_mfma_f32_16x16x32_bf16 v[100:103], v[144:147], v[194:197], v[100:103]
	v_mfma_f32_16x16x32_bf16 v[96:99], v[170:173], v[194:197], v[96:99]
	v_mfma_f32_16x16x32_bf16 v[84:87], v[144:147], v[216:219], v[84:87]
	v_mfma_f32_16x16x32_bf16 v[80:83], v[170:173], v[216:219], v[80:83]
	v_mfma_f32_16x16x32_bf16 v[140:143], v[166:169], v[182:185], v[140:143]
	v_mfma_f32_16x16x32_bf16 v[136:139], v[174:177], v[182:185], v[136:139]
	v_mfma_f32_16x16x32_bf16 v[132:135], v[166:169], v[190:193], v[132:135]
	v_mfma_f32_16x16x32_bf16 v[128:131], v[174:177], v[190:193], v[128:131]
	v_mfma_f32_16x16x32_bf16 v[100:103], v[166:169], v[212:215], v[100:103]
	v_mfma_f32_16x16x32_bf16 v[96:99], v[174:177], v[212:215], v[96:99]
	v_mfma_f32_16x16x32_bf16 v[84:87], v[166:169], v[220:223], v[84:87]
	v_mfma_f32_16x16x32_bf16 v[80:83], v[174:177], v[220:223], v[80:83]
	s_barrier
	s_setprio 0
	s_add_i32 s28, s53, s4
	v_lshl_add_u64 v[224:225], s[42:43], 0, v[150:151]
	s_mov_b32 m0, s28
	ds_read_b128 v[178:181], v209 offset:16384
	ds_read_b128 v[182:185], v209 offset:17408
	ds_read_b128 v[186:189], v209 offset:18432
	ds_read_b128 v[190:193], v209 offset:19456
	ds_read_b128 v[194:197], v209 offset:20480
	ds_read_b128 v[212:215], v209 offset:21504
	ds_read_b128 v[216:219], v209 offset:22528
	ds_read_b128 v[220:223], v209 offset:23552
	global_load_lds_dwordx4 v[224:225], off
	s_add_i32 m0, s28, 0x2000
	s_add_u32 s76, s42, 0x80000
	v_lshl_add_u64 v[226:227], s[42:43], 0, v[154:155]
	s_addc_u32 s77, s43, 0
	s_add_i32 s28, s57, s4
	global_load_lds_dwordx4 v[226:227], off
	v_lshl_add_u64 v[228:229], s[76:77], 0, v[150:151]
	s_mov_b32 m0, s28
	v_lshl_add_u64 v[230:231], s[44:45], 0, v[152:153]
	global_load_lds_dwordx4 v[228:229], off
	v_lshl_add_u64 v[228:229], s[76:77], 0, v[154:155]
	s_add_i32 m0, s28, 0x2000
	s_nop 0
	global_load_lds_dwordx4 v[228:229], off
	v_lshl_add_u64 v[228:229], s[44:45], 0, v[148:149]
	s_mov_b32 m0, s5
	s_nop 0
	global_load_lds_dwordx4 v[228:229], off
	s_mov_b32 m0, s6
	s_nop 0
	global_load_lds_dwordx4 v[230:231], off
	s_waitcnt vmcnt(8)
	s_waitcnt lgkmcnt(0)
	s_setprio 1
	s_barrier
	v_mfma_f32_16x16x32_bf16 v[76:79], v[0:3], v[178:181], v[76:79]
	v_mfma_f32_16x16x32_bf16 v[72:75], v[8:11], v[178:181], v[72:75]
	v_mfma_f32_16x16x32_bf16 v[60:63], v[0:3], v[186:189], v[60:63]
	v_mfma_f32_16x16x32_bf16 v[56:59], v[8:11], v[186:189], v[56:59]
	v_mfma_f32_16x16x32_bf16 v[44:47], v[0:3], v[194:197], v[44:47]
	v_mfma_f32_16x16x32_bf16 v[40:43], v[8:11], v[194:197], v[40:43]
	v_mfma_f32_16x16x32_bf16 v[0:3], v[0:3], v[216:219], v[28:31]
	v_mfma_f32_16x16x32_bf16 v[76:79], v[4:7], v[182:185], v[76:79]
	v_mfma_f32_16x16x32_bf16 v[72:75], v[12:15], v[182:185], v[72:75]
	v_mfma_f32_16x16x32_bf16 v[60:63], v[4:7], v[190:193], v[60:63]
	v_mfma_f32_16x16x32_bf16 v[56:59], v[12:15], v[190:193], v[56:59]
	v_mfma_f32_16x16x32_bf16 v[44:47], v[4:7], v[212:215], v[44:47]
	v_mfma_f32_16x16x32_bf16 v[40:43], v[12:15], v[212:215], v[40:43]
	v_mfma_f32_16x16x32_bf16 v[0:3], v[4:7], v[220:223], v[0:3]
	v_mfma_f32_16x16x32_bf16 v[4:7], v[8:11], v[216:219], v[20:23]
	v_mfma_f32_16x16x32_bf16 v[4:7], v[12:15], v[220:223], v[4:7]
	v_mfma_f32_16x16x32_bf16 v[20:23], v[144:147], v[186:189], v[52:55]
	v_mfma_f32_16x16x32_bf16 v[52:55], v[166:169], v[190:193], v[20:23]
	v_mfma_f32_16x16x32_bf16 v[20:23], v[170:173], v[186:189], v[48:51]
	v_mfma_f32_16x16x32_bf16 v[48:51], v[174:177], v[190:193], v[20:23]
	v_mfma_f32_16x16x32_bf16 v[20:23], v[144:147], v[194:197], v[36:39]
	v_mfma_f32_16x16x32_bf16 v[36:39], v[166:169], v[212:215], v[20:23]
	v_mfma_f32_16x16x32_bf16 v[20:23], v[170:173], v[194:197], v[32:35]
	v_mfma_f32_16x16x32_bf16 v[32:35], v[174:177], v[212:215], v[20:23]
	v_mfma_f32_16x16x32_bf16 v[20:23], v[144:147], v[216:219], v[24:27]
	v_mfma_f32_16x16x32_bf16 v[16:19], v[170:173], v[216:219], v[16:19]
	v_mfma_f32_16x16x32_bf16 v[8:11], v[144:147], v[178:181], v[68:71]
	v_mfma_f32_16x16x32_bf16 v[12:15], v[170:173], v[178:181], v[64:67]
	v_mfma_f32_16x16x32_bf16 v[24:27], v[166:169], v[220:223], v[20:23]
	v_mfma_f32_16x16x32_bf16 v[16:19], v[174:177], v[220:223], v[16:19]
	v_mfma_f32_16x16x32_bf16 v[8:11], v[166:169], v[182:185], v[8:11]
	v_mfma_f32_16x16x32_bf16 v[12:15], v[174:177], v[182:185], v[12:15]
	s_barrier
	s_setprio 0
	v_add_u32_e32 v68, s86, v201
	v_add_u32_e32 v157, s87, v201
	ds_read_b128 v[20:23], v68
	ds_read_b128 v[28:31], v68 offset:1024
	ds_read_b128 v[64:67], v68 offset:2048
	ds_read_b128 v[68:71], v68 offset:3072
	ds_read_b128 v[144:147], v157
	ds_read_b128 v[166:169], v157 offset:1024
	ds_read_b128 v[170:173], v157 offset:2048
	ds_read_b128 v[174:177], v157 offset:3072
	s_add_u32 s44, s44, 0x80000
	s_addc_u32 s45, s45, 0
	s_mov_b32 m0, s7
	v_lshl_add_u64 v[232:233], s[44:45], 0, v[148:149]
	ds_read_b128 v[178:181], v209 offset:32768
	ds_read_b128 v[182:185], v209 offset:33792
	ds_read_b128 v[186:189], v209 offset:34816
	ds_read_b128 v[190:193], v209 offset:35840
	ds_read_b128 v[194:197], v209 offset:36864
	ds_read_b128 v[212:215], v209 offset:37888
	ds_read_b128 v[216:219], v209 offset:38912
	ds_read_b128 v[220:223], v209 offset:39936
	global_load_lds_dwordx4 v[232:233], off
	v_lshl_add_u64 v[232:233], s[44:45], 0, v[152:153]
	s_mov_b32 m0, s8
	s_nop 0
	global_load_lds_dwordx4 v[232:233], off
	s_waitcnt vmcnt(8)
	s_waitcnt lgkmcnt(0)
	s_setprio 1
	s_barrier
	v_mfma_f32_16x16x32_bf16 v[108:111], v[20:23], v[178:181], v[108:111]
	v_mfma_f32_16x16x32_bf16 v[104:107], v[64:67], v[178:181], v[104:107]
	v_mfma_f32_16x16x32_bf16 v[124:127], v[20:23], v[186:189], v[124:127]
	v_mfma_f32_16x16x32_bf16 v[116:119], v[64:67], v[186:189], v[116:119]
	v_mfma_f32_16x16x32_bf16 v[120:123], v[20:23], v[194:197], v[120:123]
	v_mfma_f32_16x16x32_bf16 v[112:115], v[64:67], v[194:197], v[112:115]
	v_mfma_f32_16x16x32_bf16 v[92:95], v[20:23], v[216:219], v[92:95]
	v_mfma_f32_16x16x32_bf16 v[88:91], v[64:67], v[216:219], v[88:91]
	v_mfma_f32_16x16x32_bf16 v[108:111], v[28:31], v[182:185], v[108:111]
	v_mfma_f32_16x16x32_bf16 v[104:107], v[68:71], v[182:185], v[104:107]
	v_mfma_f32_16x16x32_bf16 v[124:127], v[28:31], v[190:193], v[124:127]
	v_mfma_f32_16x16x32_bf16 v[116:119], v[68:71], v[190:193], v[116:119]
	v_mfma_f32_16x16x32_bf16 v[120:123], v[28:31], v[212:215], v[120:123]
	v_mfma_f32_16x16x32_bf16 v[112:115], v[68:71], v[212:215], v[112:115]
	v_mfma_f32_16x16x32_bf16 v[92:95], v[28:31], v[220:223], v[92:95]
	v_mfma_f32_16x16x32_bf16 v[88:91], v[68:71], v[220:223], v[88:91]
	v_mfma_f32_16x16x32_bf16 v[140:143], v[144:147], v[178:181], v[140:143]
	v_mfma_f32_16x16x32_bf16 v[136:139], v[170:173], v[178:181], v[136:139]
	v_mfma_f32_16x16x32_bf16 v[132:135], v[144:147], v[186:189], v[132:135]
	v_mfma_f32_16x16x32_bf16 v[128:131], v[170:173], v[186:189], v[128:131]
	v_mfma_f32_16x16x32_bf16 v[100:103], v[144:147], v[194:197], v[100:103]
	v_mfma_f32_16x16x32_bf16 v[96:99], v[170:173], v[194:197], v[96:99]
	v_mfma_f32_16x16x32_bf16 v[84:87], v[144:147], v[216:219], v[84:87]
	v_mfma_f32_16x16x32_bf16 v[80:83], v[170:173], v[216:219], v[80:83]
	v_mfma_f32_16x16x32_bf16 v[140:143], v[166:169], v[182:185], v[140:143]
	v_mfma_f32_16x16x32_bf16 v[136:139], v[174:177], v[182:185], v[136:139]
	v_mfma_f32_16x16x32_bf16 v[132:135], v[166:169], v[190:193], v[132:135]
	v_mfma_f32_16x16x32_bf16 v[128:131], v[174:177], v[190:193], v[128:131]
	v_mfma_f32_16x16x32_bf16 v[100:103], v[166:169], v[212:215], v[100:103]
	v_mfma_f32_16x16x32_bf16 v[96:99], v[174:177], v[212:215], v[96:99]
	v_mfma_f32_16x16x32_bf16 v[84:87], v[166:169], v[220:223], v[84:87]
	v_mfma_f32_16x16x32_bf16 v[80:83], v[174:177], v[220:223], v[80:83]
	s_barrier
	s_setprio 0
	s_add_i32 s28, s86, s4
	v_lshl_add_u64 v[224:225], v[224:225], 0, s[60:61]
	s_mov_b32 m0, s28
	ds_read_b128 v[178:181], v209 offset:49152
	ds_read_b128 v[182:185], v209 offset:50176
	ds_read_b128 v[186:189], v209 offset:51200
	ds_read_b128 v[190:193], v209 offset:52224
	ds_read_b128 v[194:197], v209 offset:53248
	ds_read_b128 v[212:215], v209 offset:54272
	ds_read_b128 v[216:219], v209 offset:55296
	ds_read_b128 v[220:223], v209 offset:56320
	global_load_lds_dwordx4 v[224:225], off
	s_add_i32 m0, s28, 0x2000
	s_add_u32 s42, s42, 0x80080
	v_lshl_add_u64 v[224:225], v[226:227], 0, s[60:61]
	s_addc_u32 s43, s43, 0
	s_add_i32 s28, s87, s4
	global_load_lds_dwordx4 v[224:225], off
	v_lshl_add_u64 v[224:225], s[42:43], 0, v[150:151]
	s_mov_b32 m0, s28
	s_nop 0
	global_load_lds_dwordx4 v[224:225], off
	v_lshl_add_u64 v[224:225], s[42:43], 0, v[154:155]
	s_add_i32 m0, s28, 0x2000
	s_nop 0
	global_load_lds_dwordx4 v[224:225], off
	v_lshl_add_u64 v[224:225], v[228:229], 0, s[60:61]
	s_mov_b32 m0, s9
	s_nop 0
	global_load_lds_dwordx4 v[224:225], off
	v_lshl_add_u64 v[224:225], v[230:231], 0, s[60:61]
	s_mov_b32 m0, s10
	s_nop 0
	global_load_lds_dwordx4 v[224:225], off
	s_waitcnt vmcnt(8)
	s_waitcnt lgkmcnt(0)
	s_setprio 1
	s_barrier
	v_mfma_f32_16x16x32_bf16 v[76:79], v[20:23], v[178:181], v[76:79]
	v_mfma_f32_16x16x32_bf16 v[60:63], v[20:23], v[186:189], v[60:63]
	v_mfma_f32_16x16x32_bf16 v[44:47], v[20:23], v[194:197], v[44:47]
	v_mfma_f32_16x16x32_bf16 v[0:3], v[20:23], v[216:219], v[0:3]
	v_mfma_f32_16x16x32_bf16 v[76:79], v[28:31], v[182:185], v[76:79]
	v_mfma_f32_16x16x32_bf16 v[72:75], v[64:67], v[178:181], v[72:75]
	v_mfma_f32_16x16x32_bf16 v[60:63], v[28:31], v[190:193], v[60:63]
	v_mfma_f32_16x16x32_bf16 v[56:59], v[64:67], v[186:189], v[56:59]
	v_mfma_f32_16x16x32_bf16 v[44:47], v[28:31], v[212:215], v[44:47]
	v_mfma_f32_16x16x32_bf16 v[40:43], v[64:67], v[194:197], v[40:43]
	v_mfma_f32_16x16x32_bf16 v[28:31], v[28:31], v[220:223], v[0:3]
	v_mfma_f32_16x16x32_bf16 v[0:3], v[64:67], v[216:219], v[4:7]
	v_mfma_f32_16x16x32_bf16 v[72:75], v[68:71], v[182:185], v[72:75]
	v_mfma_f32_16x16x32_bf16 v[56:59], v[68:71], v[190:193], v[56:59]
	v_mfma_f32_16x16x32_bf16 v[40:43], v[68:71], v[212:215], v[40:43]
	v_mfma_f32_16x16x32_bf16 v[20:23], v[68:71], v[220:223], v[0:3]
	v_mfma_f32_16x16x32_bf16 v[0:3], v[144:147], v[178:181], v[8:11]
	v_mfma_f32_16x16x32_bf16 v[68:71], v[166:169], v[182:185], v[0:3]
	v_mfma_f32_16x16x32_bf16 v[0:3], v[170:173], v[178:181], v[12:15]
	v_mfma_f32_16x16x32_bf16 v[64:67], v[174:177], v[182:185], v[0:3]
	v_mfma_f32_16x16x32_bf16 v[0:3], v[144:147], v[186:189], v[52:55]
	v_mfma_f32_16x16x32_bf16 v[52:55], v[166:169], v[190:193], v[0:3]
	v_mfma_f32_16x16x32_bf16 v[0:3], v[170:173], v[186:189], v[48:51]
	v_mfma_f32_16x16x32_bf16 v[48:51], v[174:177], v[190:193], v[0:3]
	v_mfma_f32_16x16x32_bf16 v[0:3], v[144:147], v[194:197], v[36:39]
	v_mfma_f32_16x16x32_bf16 v[36:39], v[166:169], v[212:215], v[0:3]
	v_mfma_f32_16x16x32_bf16 v[0:3], v[170:173], v[194:197], v[32:35]
	v_mfma_f32_16x16x32_bf16 v[32:35], v[174:177], v[212:215], v[0:3]
	v_mfma_f32_16x16x32_bf16 v[0:3], v[144:147], v[216:219], v[24:27]
	v_mfma_f32_16x16x32_bf16 v[24:27], v[166:169], v[220:223], v[0:3]
	v_mfma_f32_16x16x32_bf16 v[0:3], v[170:173], v[216:219], v[16:19]
	v_mfma_f32_16x16x32_bf16 v[16:19], v[174:177], v[220:223], v[0:3]
	s_barrier
	s_setprio 0
	s_cmp_gt_u32 s23, 29
	s_cbranch_scc1 .LBB0_6335
	s_mov_b32 s23, s62
	s_branch .LBB0_6321

.LBB0_7545:
	s_or_b32 s44, s69, 1
	s_lshl_b64 s[94:95], s[44:45], 7
	s_add_i32 s44, s69, 2
	s_lshl_b64 vcc, s[44:45], 7
	s_add_u32 s42, s64, vcc_lo
	s_addc_u32 s93, s65, vcc_hi
	s_and_b64 s[74:75], s[72:73], exec
	s_cselect_b32 s75, s93, s59
	s_cselect_b32 s74, s42, s58
	s_add_u32 s42, s66, vcc_lo
	s_addc_u32 s93, s67, vcc_hi
	s_add_i32 vcc_lo, 0, 0x10000
	s_and_b64 s[72:73], s[72:73], exec
	s_cselect_b32 s73, s93, s61
	s_cselect_b32 s72, s42, s60
	s_add_i32 s42, 0, 0x14000
	v_add_u32_e32 v140, vcc_lo, v168
	v_add_u32_e32 v173, s42, v168
	ds_read_b128 v[128:131], v140
	ds_read_b128 v[132:135], v140 offset:1024
	ds_read_b128 v[136:139], v140 offset:2048
	ds_read_b128 v[140:143], v140 offset:3072
	ds_read_b128 v[160:163], v173
	ds_read_b128 v[174:177], v173 offset:1024
	ds_read_b128 v[178:181], v173 offset:2048
	ds_read_b128 v[182:185], v173 offset:3072
	s_add_u32 s93, s64, s94
	s_addc_u32 s95, s65, s95
	s_add_u32 s94, s93, 0x80000
	s_addc_u32 s95, s95, 0
	v_lshl_add_u64 v[202:203], s[94:95], 0, v[152:153]
	s_add_i32 m0, s63, 0xc000
	ds_read_b128 v[186:189], v172
	ds_read_b128 v[190:193], v172 offset:1024
	ds_read_b128 v[194:197], v172 offset:2048
	ds_read_b128 v[198:201], v172 offset:3072
	ds_read_b128 v[206:209], v172 offset:4096
	ds_read_b128 v[210:213], v172 offset:5120
	ds_read_b128 v[214:217], v172 offset:6144
	ds_read_b128 v[218:221], v172 offset:7168
	global_load_lds_dwordx4 v[202:203], off
	v_lshl_add_u64 v[202:203], s[94:95], 0, v[154:155]
	s_add_i32 m0, s63, 0xe000
	s_nop 0
	global_load_lds_dwordx4 v[202:203], off
	s_waitcnt vmcnt(8)
	s_waitcnt lgkmcnt(0)
	s_setprio 1
	s_barrier
	v_mfma_f32_16x16x32_bf16 v[124:127], v[128:131], v[186:189], v[124:127]
	v_mfma_f32_16x16x32_bf16 v[120:123], v[136:139], v[186:189], v[120:123]
	v_mfma_f32_16x16x32_bf16 v[108:111], v[128:131], v[194:197], v[108:111]
	v_mfma_f32_16x16x32_bf16 v[104:107], v[136:139], v[194:197], v[104:107]
	v_mfma_f32_16x16x32_bf16 v[92:95], v[128:131], v[206:209], v[92:95]
	v_mfma_f32_16x16x32_bf16 v[88:91], v[136:139], v[206:209], v[88:91]
	v_mfma_f32_16x16x32_bf16 v[76:79], v[128:131], v[214:217], v[76:79]
	v_mfma_f32_16x16x32_bf16 v[72:75], v[136:139], v[214:217], v[72:75]
	v_mfma_f32_16x16x32_bf16 v[124:127], v[132:135], v[190:193], v[124:127]
	v_mfma_f32_16x16x32_bf16 v[120:123], v[140:143], v[190:193], v[120:123]
	v_mfma_f32_16x16x32_bf16 v[108:111], v[132:135], v[198:201], v[108:111]
	v_mfma_f32_16x16x32_bf16 v[104:107], v[140:143], v[198:201], v[104:107]
	v_mfma_f32_16x16x32_bf16 v[92:95], v[132:135], v[210:213], v[92:95]
	v_mfma_f32_16x16x32_bf16 v[88:91], v[140:143], v[210:213], v[88:91]
	v_mfma_f32_16x16x32_bf16 v[76:79], v[132:135], v[218:221], v[76:79]
	v_mfma_f32_16x16x32_bf16 v[72:75], v[140:143], v[218:221], v[72:75]
	v_mfma_f32_16x16x32_bf16 v[116:119], v[160:163], v[186:189], v[116:119]
	v_mfma_f32_16x16x32_bf16 v[112:115], v[178:181], v[186:189], v[112:115]
	v_mfma_f32_16x16x32_bf16 v[100:103], v[160:163], v[194:197], v[100:103]
	v_mfma_f32_16x16x32_bf16 v[96:99], v[178:181], v[194:197], v[96:99]
	v_mfma_f32_16x16x32_bf16 v[84:87], v[160:163], v[206:209], v[84:87]
	v_mfma_f32_16x16x32_bf16 v[80:83], v[178:181], v[206:209], v[80:83]
	v_mfma_f32_16x16x32_bf16 v[68:71], v[160:163], v[214:217], v[68:71]
	v_mfma_f32_16x16x32_bf16 v[64:67], v[178:181], v[214:217], v[64:67]
	v_mfma_f32_16x16x32_bf16 v[116:119], v[174:177], v[190:193], v[116:119]
	v_mfma_f32_16x16x32_bf16 v[112:115], v[182:185], v[190:193], v[112:115]
	v_mfma_f32_16x16x32_bf16 v[100:103], v[174:177], v[198:201], v[100:103]
	v_mfma_f32_16x16x32_bf16 v[96:99], v[182:185], v[198:201], v[96:99]
	v_mfma_f32_16x16x32_bf16 v[84:87], v[174:177], v[210:213], v[84:87]
	v_mfma_f32_16x16x32_bf16 v[80:83], v[182:185], v[210:213], v[80:83]
	v_mfma_f32_16x16x32_bf16 v[68:71], v[174:177], v[218:221], v[68:71]
	v_mfma_f32_16x16x32_bf16 v[64:67], v[182:185], v[218:221], v[64:67]
	s_barrier
	s_setprio 0
	s_add_i32 s93, vcc_lo, s83
	v_lshl_add_u64 v[202:203], s[72:73], 0, v[144:145]
	s_mov_b32 m0, s93
	ds_read_b128 v[186:189], v172 offset:16384
	ds_read_b128 v[190:193], v172 offset:17408
	ds_read_b128 v[194:197], v172 offset:18432
	ds_read_b128 v[198:201], v172 offset:19456
	ds_read_b128 v[206:209], v172 offset:20480
	ds_read_b128 v[210:213], v172 offset:21504
	ds_read_b128 v[214:217], v172 offset:22528
	ds_read_b128 v[218:221], v172 offset:23552
	global_load_lds_dwordx4 v[202:203], off
	s_add_i32 m0, s93, 0x2000
	s_add_u32 s94, s72, 0x80000
	v_lshl_add_u64 v[222:223], s[72:73], 0, v[156:157]
	s_addc_u32 s95, s73, 0
	s_add_i32 s42, s42, s83
	global_load_lds_dwordx4 v[222:223], off
	v_lshl_add_u64 v[224:225], s[94:95], 0, v[144:145]
	s_mov_b32 m0, s42
	v_lshl_add_u64 v[226:227], s[74:75], 0, v[154:155]
	global_load_lds_dwordx4 v[224:225], off
	v_lshl_add_u64 v[224:225], s[94:95], 0, v[156:157]
	s_add_i32 m0, s42, 0x2000
	s_nop 0
	global_load_lds_dwordx4 v[224:225], off
	v_lshl_add_u64 v[224:225], s[74:75], 0, v[152:153]
	s_mov_b32 m0, s63
	s_nop 0
	global_load_lds_dwordx4 v[224:225], off
	s_mov_b32 m0, s84
	s_nop 0
	global_load_lds_dwordx4 v[226:227], off
	s_waitcnt vmcnt(8)
	s_waitcnt lgkmcnt(0)
	s_setprio 1
	s_barrier
	v_mfma_f32_16x16x32_bf16 v[60:63], v[128:131], v[186:189], v[60:63]
	v_mfma_f32_16x16x32_bf16 v[56:59], v[136:139], v[186:189], v[56:59]
	v_mfma_f32_16x16x32_bf16 v[44:47], v[128:131], v[194:197], v[44:47]
	v_mfma_f32_16x16x32_bf16 v[40:43], v[136:139], v[194:197], v[40:43]
	v_mfma_f32_16x16x32_bf16 v[24:27], v[128:131], v[206:209], v[24:27]
	v_mfma_f32_16x16x32_bf16 v[16:19], v[136:139], v[206:209], v[16:19]
	v_mfma_f32_16x16x32_bf16 v[4:7], v[128:131], v[214:217], v[4:7]
	v_mfma_f32_16x16x32_bf16 v[0:3], v[136:139], v[214:217], v[0:3]
	v_mfma_f32_16x16x32_bf16 v[60:63], v[132:135], v[190:193], v[60:63]
	v_mfma_f32_16x16x32_bf16 v[56:59], v[140:143], v[190:193], v[56:59]
	v_mfma_f32_16x16x32_bf16 v[44:47], v[132:135], v[198:201], v[44:47]
	v_mfma_f32_16x16x32_bf16 v[40:43], v[140:143], v[198:201], v[40:43]
	v_mfma_f32_16x16x32_bf16 v[24:27], v[132:135], v[210:213], v[24:27]
	v_mfma_f32_16x16x32_bf16 v[16:19], v[140:143], v[210:213], v[16:19]
	v_mfma_f32_16x16x32_bf16 v[4:7], v[132:135], v[218:221], v[4:7]
	v_mfma_f32_16x16x32_bf16 v[0:3], v[140:143], v[218:221], v[0:3]
	v_mfma_f32_16x16x32_bf16 v[52:55], v[160:163], v[186:189], v[52:55]
	v_mfma_f32_16x16x32_bf16 v[48:51], v[178:181], v[186:189], v[48:51]
	v_mfma_f32_16x16x32_bf16 v[28:31], v[160:163], v[194:197], v[28:31]
	v_mfma_f32_16x16x32_bf16 v[20:23], v[178:181], v[194:197], v[20:23]
	v_mfma_f32_16x16x32_bf16 v[32:35], v[160:163], v[206:209], v[32:35]
	v_mfma_f32_16x16x32_bf16 v[36:39], v[178:181], v[206:209], v[36:39]
	v_mfma_f32_16x16x32_bf16 v[8:11], v[160:163], v[214:217], v[8:11]
	v_mfma_f32_16x16x32_bf16 v[12:15], v[178:181], v[214:217], v[12:15]
	v_mfma_f32_16x16x32_bf16 v[52:55], v[174:177], v[190:193], v[52:55]
	v_mfma_f32_16x16x32_bf16 v[48:51], v[182:185], v[190:193], v[48:51]
	v_mfma_f32_16x16x32_bf16 v[28:31], v[174:177], v[198:201], v[28:31]
	v_mfma_f32_16x16x32_bf16 v[20:23], v[182:185], v[198:201], v[20:23]
	v_mfma_f32_16x16x32_bf16 v[32:35], v[174:177], v[210:213], v[32:35]
	v_mfma_f32_16x16x32_bf16 v[36:39], v[182:185], v[210:213], v[36:39]
	v_mfma_f32_16x16x32_bf16 v[8:11], v[174:177], v[218:221], v[8:11]
	v_mfma_f32_16x16x32_bf16 v[12:15], v[182:185], v[218:221], v[12:15]
	s_barrier
	s_setprio 0
	s_add_i32 s42, 0, 0x18000
	s_add_i32 s93, 0, 0x1c000
	v_add_u32_e32 v140, s42, v168
	v_add_u32_e32 v173, s93, v168
	ds_read_b128 v[128:131], v140
	ds_read_b128 v[132:135], v140 offset:1024
	ds_read_b128 v[136:139], v140 offset:2048
	ds_read_b128 v[140:143], v140 offset:3072
	ds_read_b128 v[160:163], v173
	ds_read_b128 v[174:177], v173 offset:1024
	ds_read_b128 v[178:181], v173 offset:2048
	ds_read_b128 v[182:185], v173 offset:3072
	s_add_u32 s74, s74, 0x80000
	s_addc_u32 s75, s75, 0
	s_mov_b32 m0, s85
	v_lshl_add_u64 v[228:229], s[74:75], 0, v[152:153]
	ds_read_b128 v[186:189], v172 offset:32768
	ds_read_b128 v[190:193], v172 offset:33792
	ds_read_b128 v[194:197], v172 offset:34816
	ds_read_b128 v[198:201], v172 offset:35840
	ds_read_b128 v[206:209], v172 offset:36864
	ds_read_b128 v[210:213], v172 offset:37888
	ds_read_b128 v[214:217], v172 offset:38912
	ds_read_b128 v[218:221], v172 offset:39936
	global_load_lds_dwordx4 v[228:229], off
	v_lshl_add_u64 v[228:229], s[74:75], 0, v[154:155]
	s_mov_b32 m0, s86
	s_nop 0
	global_load_lds_dwordx4 v[228:229], off
	s_waitcnt vmcnt(8)
	s_waitcnt lgkmcnt(0)
	s_setprio 1
	s_barrier
	v_mfma_f32_16x16x32_bf16 v[124:127], v[128:131], v[186:189], v[124:127]
	v_mfma_f32_16x16x32_bf16 v[120:123], v[136:139], v[186:189], v[120:123]
	v_mfma_f32_16x16x32_bf16 v[108:111], v[128:131], v[194:197], v[108:111]
	v_mfma_f32_16x16x32_bf16 v[104:107], v[136:139], v[194:197], v[104:107]
	v_mfma_f32_16x16x32_bf16 v[92:95], v[128:131], v[206:209], v[92:95]
	v_mfma_f32_16x16x32_bf16 v[88:91], v[136:139], v[206:209], v[88:91]
	v_mfma_f32_16x16x32_bf16 v[76:79], v[128:131], v[214:217], v[76:79]
	v_mfma_f32_16x16x32_bf16 v[72:75], v[136:139], v[214:217], v[72:75]
	v_mfma_f32_16x16x32_bf16 v[124:127], v[132:135], v[190:193], v[124:127]
	v_mfma_f32_16x16x32_bf16 v[120:123], v[140:143], v[190:193], v[120:123]
	v_mfma_f32_16x16x32_bf16 v[108:111], v[132:135], v[198:201], v[108:111]
	v_mfma_f32_16x16x32_bf16 v[104:107], v[140:143], v[198:201], v[104:107]
	v_mfma_f32_16x16x32_bf16 v[92:95], v[132:135], v[210:213], v[92:95]
	v_mfma_f32_16x16x32_bf16 v[88:91], v[140:143], v[210:213], v[88:91]
	v_mfma_f32_16x16x32_bf16 v[76:79], v[132:135], v[218:221], v[76:79]
	v_mfma_f32_16x16x32_bf16 v[72:75], v[140:143], v[218:221], v[72:75]
	v_mfma_f32_16x16x32_bf16 v[116:119], v[160:163], v[186:189], v[116:119]
	v_mfma_f32_16x16x32_bf16 v[112:115], v[178:181], v[186:189], v[112:115]
	v_mfma_f32_16x16x32_bf16 v[100:103], v[160:163], v[194:197], v[100:103]
	v_mfma_f32_16x16x32_bf16 v[96:99], v[178:181], v[194:197], v[96:99]
	v_mfma_f32_16x16x32_bf16 v[84:87], v[160:163], v[206:209], v[84:87]
	v_mfma_f32_16x16x32_bf16 v[80:83], v[178:181], v[206:209], v[80:83]
	v_mfma_f32_16x16x32_bf16 v[68:71], v[160:163], v[214:217], v[68:71]
	v_mfma_f32_16x16x32_bf16 v[64:67], v[178:181], v[214:217], v[64:67]
	v_mfma_f32_16x16x32_bf16 v[116:119], v[174:177], v[190:193], v[116:119]
	v_mfma_f32_16x16x32_bf16 v[112:115], v[182:185], v[190:193], v[112:115]
	v_mfma_f32_16x16x32_bf16 v[100:103], v[174:177], v[198:201], v[100:103]
	v_mfma_f32_16x16x32_bf16 v[96:99], v[182:185], v[198:201], v[96:99]
	v_mfma_f32_16x16x32_bf16 v[84:87], v[174:177], v[210:213], v[84:87]
	v_mfma_f32_16x16x32_bf16 v[80:83], v[182:185], v[210:213], v[80:83]
	v_mfma_f32_16x16x32_bf16 v[68:71], v[174:177], v[218:221], v[68:71]
	v_mfma_f32_16x16x32_bf16 v[64:67], v[182:185], v[218:221], v[64:67]
	s_barrier
	s_setprio 0
	s_add_i32 s42, s42, s83
	v_lshl_add_u64 v[202:203], v[202:203], 0, s[46:47]
	s_mov_b32 m0, s42
	ds_read_b128 v[186:189], v172 offset:49152
	ds_read_b128 v[190:193], v172 offset:50176
	ds_read_b128 v[194:197], v172 offset:51200
	ds_read_b128 v[198:201], v172 offset:52224
	ds_read_b128 v[206:209], v172 offset:53248
	ds_read_b128 v[210:213], v172 offset:54272
	ds_read_b128 v[214:217], v172 offset:55296
	ds_read_b128 v[218:221], v172 offset:56320
	global_load_lds_dwordx4 v[202:203], off
	s_add_i32 m0, s42, 0x2000
	s_add_u32 s72, s72, 0x80080
	v_lshl_add_u64 v[202:203], v[222:223], 0, s[46:47]
	s_addc_u32 s73, s73, 0
	s_add_i32 s42, s93, s83
	global_load_lds_dwordx4 v[202:203], off
	v_lshl_add_u64 v[202:203], s[72:73], 0, v[144:145]
	s_mov_b32 m0, s42
	s_nop 0
	global_load_lds_dwordx4 v[202:203], off
	v_lshl_add_u64 v[202:203], s[72:73], 0, v[156:157]
	s_add_i32 m0, s42, 0x2000
	s_nop 0
	global_load_lds_dwordx4 v[202:203], off
	v_lshl_add_u64 v[202:203], v[224:225], 0, s[46:47]
	s_mov_b32 m0, s87
	s_nop 0
	global_load_lds_dwordx4 v[202:203], off
	v_lshl_add_u64 v[202:203], v[226:227], 0, s[46:47]
	s_mov_b32 m0, s88
	s_nop 0
	global_load_lds_dwordx4 v[202:203], off
	s_waitcnt vmcnt(8)
	s_waitcnt lgkmcnt(0)
	s_setprio 1
	s_barrier
	v_mfma_f32_16x16x32_bf16 v[60:63], v[128:131], v[186:189], v[60:63]
	v_mfma_f32_16x16x32_bf16 v[56:59], v[136:139], v[186:189], v[56:59]
	v_mfma_f32_16x16x32_bf16 v[44:47], v[128:131], v[194:197], v[44:47]
	v_mfma_f32_16x16x32_bf16 v[40:43], v[136:139], v[194:197], v[40:43]
	v_mfma_f32_16x16x32_bf16 v[24:27], v[128:131], v[206:209], v[24:27]
	v_mfma_f32_16x16x32_bf16 v[16:19], v[136:139], v[206:209], v[16:19]
	v_mfma_f32_16x16x32_bf16 v[4:7], v[128:131], v[214:217], v[4:7]
	v_mfma_f32_16x16x32_bf16 v[0:3], v[136:139], v[214:217], v[0:3]
	v_mfma_f32_16x16x32_bf16 v[60:63], v[132:135], v[190:193], v[60:63]
	v_mfma_f32_16x16x32_bf16 v[56:59], v[140:143], v[190:193], v[56:59]
	v_mfma_f32_16x16x32_bf16 v[44:47], v[132:135], v[198:201], v[44:47]
	v_mfma_f32_16x16x32_bf16 v[40:43], v[140:143], v[198:201], v[40:43]
	v_mfma_f32_16x16x32_bf16 v[24:27], v[132:135], v[210:213], v[24:27]
	v_mfma_f32_16x16x32_bf16 v[16:19], v[140:143], v[210:213], v[16:19]
	v_mfma_f32_16x16x32_bf16 v[4:7], v[132:135], v[218:221], v[4:7]
	v_mfma_f32_16x16x32_bf16 v[0:3], v[140:143], v[218:221], v[0:3]
	v_mfma_f32_16x16x32_bf16 v[52:55], v[160:163], v[186:189], v[52:55]
	v_mfma_f32_16x16x32_bf16 v[48:51], v[178:181], v[186:189], v[48:51]
	v_mfma_f32_16x16x32_bf16 v[28:31], v[160:163], v[194:197], v[28:31]
	v_mfma_f32_16x16x32_bf16 v[20:23], v[178:181], v[194:197], v[20:23]
	v_mfma_f32_16x16x32_bf16 v[32:35], v[160:163], v[206:209], v[32:35]
	v_mfma_f32_16x16x32_bf16 v[36:39], v[178:181], v[206:209], v[36:39]
	v_mfma_f32_16x16x32_bf16 v[8:11], v[160:163], v[214:217], v[8:11]
	v_mfma_f32_16x16x32_bf16 v[12:15], v[178:181], v[214:217], v[12:15]
	v_mfma_f32_16x16x32_bf16 v[52:55], v[174:177], v[190:193], v[52:55]
	v_mfma_f32_16x16x32_bf16 v[48:51], v[182:185], v[190:193], v[48:51]
	v_mfma_f32_16x16x32_bf16 v[28:31], v[174:177], v[198:201], v[28:31]
	v_mfma_f32_16x16x32_bf16 v[20:23], v[182:185], v[198:201], v[20:23]
	v_mfma_f32_16x16x32_bf16 v[32:35], v[174:177], v[210:213], v[32:35]
	v_mfma_f32_16x16x32_bf16 v[36:39], v[182:185], v[210:213], v[36:39]
	v_mfma_f32_16x16x32_bf16 v[8:11], v[174:177], v[218:221], v[8:11]
	v_mfma_f32_16x16x32_bf16 v[12:15], v[182:185], v[218:221], v[12:15]
	s_barrier
	s_setprio 0
	s_cmp_gt_u32 s69, 29
	s_cbranch_scc1 .LBB0_7547
	s_mov_b32 s69, s44
	s_branch .LBB0_7533

.LBB0_7633:
	s_add_i32 vcc_hi, s26, 2
	s_add_u32 s94, s22, 0x80
	s_addc_u32 s27, s23, 0
	s_add_i32 s93, 0, 0x10000
	s_cmp_eq_u32 s90, s26
	s_cselect_b32 s27, s44, s27
	s_cselect_b32 s26, s57, s94
	v_add_u32_e32 v155, s93, v143
	s_cselect_b32 s95, s62, vcc_lo
	s_cselect_b32 s94, s63, s91
	s_add_i32 s42, 0, 0x14000
	ds_read_b128 v[138:141], v155
	ds_read_b128 v[156:159], v155 offset:1024
	ds_read_b128 v[160:163], v155 offset:2048
	ds_read_b128 v[166:169], v155 offset:3072
	v_add_u32_e32 v155, s42, v143
	ds_read_b128 v[170:173], v155
	ds_read_b128 v[174:177], v155 offset:1024
	ds_read_b128 v[178:181], v155 offset:2048
	ds_read_b128 v[182:185], v155 offset:3072
	v_lshl_add_u64 v[202:203], s[22:23], 0, v[136:137]
	s_add_i32 m0, s73, 0xc000
	ds_read_b128 v[186:189], v154
	ds_read_b128 v[190:193], v154 offset:1024
	ds_read_b128 v[194:197], v154 offset:2048
	ds_read_b128 v[198:201], v154 offset:3072
	ds_read_b128 v[206:209], v154 offset:4096
	ds_read_b128 v[210:213], v154 offset:5120
	ds_read_b128 v[214:217], v154 offset:6144
	ds_read_b128 v[218:221], v154 offset:7168
	global_load_lds_dwordx4 v[202:203], off
	v_lshl_add_u64 v[202:203], s[22:23], 0, v[134:135]
	s_add_i32 m0, s73, 0xe000
	s_nop 0
	global_load_lds_dwordx4 v[202:203], off
	s_waitcnt vmcnt(8)
	s_waitcnt lgkmcnt(0)
	s_setprio 1
	s_barrier
	v_mfma_f32_16x16x32_bf16 v[124:127], v[138:141], v[186:189], v[124:127]
	v_mfma_f32_16x16x32_bf16 v[120:123], v[160:163], v[186:189], v[120:123]
	v_mfma_f32_16x16x32_bf16 v[108:111], v[138:141], v[194:197], v[108:111]
	v_mfma_f32_16x16x32_bf16 v[104:107], v[160:163], v[194:197], v[104:107]
	v_mfma_f32_16x16x32_bf16 v[92:95], v[138:141], v[206:209], v[92:95]
	v_mfma_f32_16x16x32_bf16 v[88:91], v[160:163], v[206:209], v[88:91]
	v_mfma_f32_16x16x32_bf16 v[76:79], v[138:141], v[214:217], v[76:79]
	v_mfma_f32_16x16x32_bf16 v[72:75], v[160:163], v[214:217], v[72:75]
	v_mfma_f32_16x16x32_bf16 v[124:127], v[156:159], v[190:193], v[124:127]
	v_mfma_f32_16x16x32_bf16 v[120:123], v[166:169], v[190:193], v[120:123]
	v_mfma_f32_16x16x32_bf16 v[108:111], v[156:159], v[198:201], v[108:111]
	v_mfma_f32_16x16x32_bf16 v[104:107], v[166:169], v[198:201], v[104:107]
	v_mfma_f32_16x16x32_bf16 v[92:95], v[156:159], v[210:213], v[92:95]
	v_mfma_f32_16x16x32_bf16 v[88:91], v[166:169], v[210:213], v[88:91]
	v_mfma_f32_16x16x32_bf16 v[76:79], v[156:159], v[218:221], v[76:79]
	v_mfma_f32_16x16x32_bf16 v[72:75], v[166:169], v[218:221], v[72:75]
	v_mfma_f32_16x16x32_bf16 v[116:119], v[170:173], v[186:189], v[116:119]
	v_mfma_f32_16x16x32_bf16 v[112:115], v[178:181], v[186:189], v[112:115]
	v_mfma_f32_16x16x32_bf16 v[100:103], v[170:173], v[194:197], v[100:103]
	v_mfma_f32_16x16x32_bf16 v[96:99], v[178:181], v[194:197], v[96:99]
	v_mfma_f32_16x16x32_bf16 v[84:87], v[170:173], v[206:209], v[84:87]
	v_mfma_f32_16x16x32_bf16 v[80:83], v[178:181], v[206:209], v[80:83]
	v_mfma_f32_16x16x32_bf16 v[68:71], v[170:173], v[214:217], v[68:71]
	v_mfma_f32_16x16x32_bf16 v[64:67], v[178:181], v[214:217], v[64:67]
	v_mfma_f32_16x16x32_bf16 v[116:119], v[174:177], v[190:193], v[116:119]
	v_mfma_f32_16x16x32_bf16 v[112:115], v[182:185], v[190:193], v[112:115]
	v_mfma_f32_16x16x32_bf16 v[100:103], v[174:177], v[198:201], v[100:103]
	v_mfma_f32_16x16x32_bf16 v[96:99], v[182:185], v[198:201], v[96:99]
	v_mfma_f32_16x16x32_bf16 v[84:87], v[174:177], v[210:213], v[84:87]
	v_mfma_f32_16x16x32_bf16 v[80:83], v[182:185], v[210:213], v[80:83]
	v_mfma_f32_16x16x32_bf16 v[68:71], v[174:177], v[218:221], v[68:71]
	v_mfma_f32_16x16x32_bf16 v[64:67], v[182:185], v[218:221], v[64:67]
	s_barrier
	s_setprio 0
	s_add_i32 s93, s93, s72
	v_lshl_add_u64 v[202:203], s[94:95], 0, v[144:145]
	s_mov_b32 m0, s93
	ds_read_b128 v[186:189], v154 offset:16384
	ds_read_b128 v[190:193], v154 offset:17408
	ds_read_b128 v[194:197], v154 offset:18432
	ds_read_b128 v[198:201], v154 offset:19456
	ds_read_b128 v[206:209], v154 offset:20480
	ds_read_b128 v[210:213], v154 offset:21504
	ds_read_b128 v[214:217], v154 offset:22528
	ds_read_b128 v[218:221], v154 offset:23552
	global_load_lds_dwordx4 v[202:203], off
	s_add_i32 m0, s93, 0x2000
	v_lshl_add_u64 v[222:223], s[94:95], 0, v[132:133]
	s_add_u32 s94, s94, s20
	s_addc_u32 s95, s95, 0
	s_add_i32 s42, s42, s72
	global_load_lds_dwordx4 v[222:223], off
	v_lshl_add_u64 v[224:225], s[94:95], 0, v[144:145]
	s_mov_b32 m0, s42
	v_lshl_add_u64 v[226:227], s[94:95], 0, v[132:133]
	global_load_lds_dwordx4 v[224:225], off
	s_add_i32 m0, s42, 0x2000
	v_lshl_add_u64 v[228:229], s[26:27], 0, v[128:129]
	global_load_lds_dwordx4 v[226:227], off
	s_mov_b32 m0, s73
	v_lshl_add_u64 v[230:231], s[26:27], 0, v[130:131]
	global_load_lds_dwordx4 v[228:229], off
	s_mov_b32 m0, s74
	s_nop 0
	global_load_lds_dwordx4 v[230:231], off
	s_waitcnt vmcnt(8)
	s_waitcnt lgkmcnt(0)
	s_setprio 1
	s_barrier
	v_mfma_f32_16x16x32_bf16 v[60:63], v[138:141], v[186:189], v[60:63]
	v_mfma_f32_16x16x32_bf16 v[56:59], v[160:163], v[186:189], v[56:59]
	v_mfma_f32_16x16x32_bf16 v[44:47], v[138:141], v[194:197], v[44:47]
	v_mfma_f32_16x16x32_bf16 v[40:43], v[160:163], v[194:197], v[40:43]
	v_mfma_f32_16x16x32_bf16 v[28:31], v[138:141], v[206:209], v[28:31]
	v_mfma_f32_16x16x32_bf16 v[24:27], v[160:163], v[206:209], v[24:27]
	v_mfma_f32_16x16x32_bf16 v[12:15], v[138:141], v[214:217], v[12:15]
	v_mfma_f32_16x16x32_bf16 v[8:11], v[160:163], v[214:217], v[8:11]
	v_mfma_f32_16x16x32_bf16 v[60:63], v[156:159], v[190:193], v[60:63]
	v_mfma_f32_16x16x32_bf16 v[56:59], v[166:169], v[190:193], v[56:59]
	v_mfma_f32_16x16x32_bf16 v[44:47], v[156:159], v[198:201], v[44:47]
	v_mfma_f32_16x16x32_bf16 v[40:43], v[166:169], v[198:201], v[40:43]
	v_mfma_f32_16x16x32_bf16 v[28:31], v[156:159], v[210:213], v[28:31]
	v_mfma_f32_16x16x32_bf16 v[24:27], v[166:169], v[210:213], v[24:27]
	v_mfma_f32_16x16x32_bf16 v[12:15], v[156:159], v[218:221], v[12:15]
	v_mfma_f32_16x16x32_bf16 v[8:11], v[166:169], v[218:221], v[8:11]
	v_mfma_f32_16x16x32_bf16 v[52:55], v[170:173], v[186:189], v[52:55]
	v_mfma_f32_16x16x32_bf16 v[48:51], v[178:181], v[186:189], v[48:51]
	v_mfma_f32_16x16x32_bf16 v[36:39], v[170:173], v[194:197], v[36:39]
	v_mfma_f32_16x16x32_bf16 v[32:35], v[178:181], v[194:197], v[32:35]
	v_mfma_f32_16x16x32_bf16 v[20:23], v[170:173], v[206:209], v[20:23]
	v_mfma_f32_16x16x32_bf16 v[16:19], v[178:181], v[206:209], v[16:19]
	v_mfma_f32_16x16x32_bf16 v[4:7], v[170:173], v[214:217], v[4:7]
	v_mfma_f32_16x16x32_bf16 v[0:3], v[178:181], v[214:217], v[0:3]
	v_mfma_f32_16x16x32_bf16 v[52:55], v[174:177], v[190:193], v[52:55]
	v_mfma_f32_16x16x32_bf16 v[48:51], v[182:185], v[190:193], v[48:51]
	v_mfma_f32_16x16x32_bf16 v[36:39], v[174:177], v[198:201], v[36:39]
	v_mfma_f32_16x16x32_bf16 v[32:35], v[182:185], v[198:201], v[32:35]
	v_mfma_f32_16x16x32_bf16 v[20:23], v[174:177], v[210:213], v[20:23]
	v_mfma_f32_16x16x32_bf16 v[16:19], v[182:185], v[210:213], v[16:19]
	v_mfma_f32_16x16x32_bf16 v[4:7], v[174:177], v[218:221], v[4:7]
	v_mfma_f32_16x16x32_bf16 v[0:3], v[182:185], v[218:221], v[0:3]
	s_barrier
	s_setprio 0
	s_add_i32 s42, 0, 0x18000
	v_add_u32_e32 v155, s42, v143
	s_add_i32 s93, 0, 0x1c000
	ds_read_b128 v[138:141], v155
	ds_read_b128 v[156:159], v155 offset:1024
	ds_read_b128 v[160:163], v155 offset:2048
	ds_read_b128 v[166:169], v155 offset:3072
	v_add_u32_e32 v155, s93, v143
	ds_read_b128 v[170:173], v155
	ds_read_b128 v[174:177], v155 offset:1024
	ds_read_b128 v[178:181], v155 offset:2048
	ds_read_b128 v[182:185], v155 offset:3072
	s_add_u32 s26, s26, s20
	s_addc_u32 s27, s27, 0
	s_mov_b32 m0, s75
	v_lshl_add_u64 v[232:233], s[26:27], 0, v[128:129]
	ds_read_b128 v[186:189], v154 offset:32768
	ds_read_b128 v[190:193], v154 offset:33792
	ds_read_b128 v[194:197], v154 offset:34816
	ds_read_b128 v[198:201], v154 offset:35840
	ds_read_b128 v[206:209], v154 offset:36864
	ds_read_b128 v[210:213], v154 offset:37888
	ds_read_b128 v[214:217], v154 offset:38912
	ds_read_b128 v[218:221], v154 offset:39936
	global_load_lds_dwordx4 v[232:233], off
	v_lshl_add_u64 v[232:233], s[26:27], 0, v[130:131]
	s_mov_b32 m0, s80
	s_nop 0
	global_load_lds_dwordx4 v[232:233], off
	s_waitcnt vmcnt(8)
	s_waitcnt lgkmcnt(0)
	s_setprio 1
	s_barrier
	v_mfma_f32_16x16x32_bf16 v[124:127], v[138:141], v[186:189], v[124:127]
	v_mfma_f32_16x16x32_bf16 v[120:123], v[160:163], v[186:189], v[120:123]
	v_mfma_f32_16x16x32_bf16 v[108:111], v[138:141], v[194:197], v[108:111]
	v_mfma_f32_16x16x32_bf16 v[104:107], v[160:163], v[194:197], v[104:107]
	v_mfma_f32_16x16x32_bf16 v[92:95], v[138:141], v[206:209], v[92:95]
	v_mfma_f32_16x16x32_bf16 v[88:91], v[160:163], v[206:209], v[88:91]
	v_mfma_f32_16x16x32_bf16 v[76:79], v[138:141], v[214:217], v[76:79]
	v_mfma_f32_16x16x32_bf16 v[72:75], v[160:163], v[214:217], v[72:75]
	v_mfma_f32_16x16x32_bf16 v[124:127], v[156:159], v[190:193], v[124:127]
	v_mfma_f32_16x16x32_bf16 v[120:123], v[166:169], v[190:193], v[120:123]
	v_mfma_f32_16x16x32_bf16 v[108:111], v[156:159], v[198:201], v[108:111]
	v_mfma_f32_16x16x32_bf16 v[104:107], v[166:169], v[198:201], v[104:107]
	v_mfma_f32_16x16x32_bf16 v[92:95], v[156:159], v[210:213], v[92:95]
	v_mfma_f32_16x16x32_bf16 v[88:91], v[166:169], v[210:213], v[88:91]
	v_mfma_f32_16x16x32_bf16 v[76:79], v[156:159], v[218:221], v[76:79]
	v_mfma_f32_16x16x32_bf16 v[72:75], v[166:169], v[218:221], v[72:75]
	v_mfma_f32_16x16x32_bf16 v[116:119], v[170:173], v[186:189], v[116:119]
	v_mfma_f32_16x16x32_bf16 v[112:115], v[178:181], v[186:189], v[112:115]
	v_mfma_f32_16x16x32_bf16 v[100:103], v[170:173], v[194:197], v[100:103]
	v_mfma_f32_16x16x32_bf16 v[96:99], v[178:181], v[194:197], v[96:99]
	v_mfma_f32_16x16x32_bf16 v[84:87], v[170:173], v[206:209], v[84:87]
	v_mfma_f32_16x16x32_bf16 v[80:83], v[178:181], v[206:209], v[80:83]
	v_mfma_f32_16x16x32_bf16 v[68:71], v[170:173], v[214:217], v[68:71]
	v_mfma_f32_16x16x32_bf16 v[64:67], v[178:181], v[214:217], v[64:67]
	v_mfma_f32_16x16x32_bf16 v[116:119], v[174:177], v[190:193], v[116:119]
	v_mfma_f32_16x16x32_bf16 v[112:115], v[182:185], v[190:193], v[112:115]
	v_mfma_f32_16x16x32_bf16 v[100:103], v[174:177], v[198:201], v[100:103]
	v_mfma_f32_16x16x32_bf16 v[96:99], v[182:185], v[198:201], v[96:99]
	v_mfma_f32_16x16x32_bf16 v[84:87], v[174:177], v[210:213], v[84:87]
	v_mfma_f32_16x16x32_bf16 v[80:83], v[182:185], v[210:213], v[80:83]
	v_mfma_f32_16x16x32_bf16 v[68:71], v[174:177], v[218:221], v[68:71]
	v_mfma_f32_16x16x32_bf16 v[64:67], v[182:185], v[218:221], v[64:67]
	s_barrier
	s_setprio 0
	s_add_i32 s26, s42, s72
	v_lshl_add_u64 v[202:203], v[202:203], 0, s[46:47]
	s_mov_b32 m0, s26
	ds_read_b128 v[186:189], v154 offset:49152
	ds_read_b128 v[190:193], v154 offset:50176
	ds_read_b128 v[194:197], v154 offset:51200
	ds_read_b128 v[198:201], v154 offset:52224
	ds_read_b128 v[206:209], v154 offset:53248
	ds_read_b128 v[210:213], v154 offset:54272
	ds_read_b128 v[214:217], v154 offset:55296
	ds_read_b128 v[218:221], v154 offset:56320
	global_load_lds_dwordx4 v[202:203], off
	v_lshl_add_u64 v[202:203], v[222:223], 0, s[46:47]
	s_add_i32 m0, s26, 0x2000
	s_add_i32 s26, s93, s72
	global_load_lds_dwordx4 v[202:203], off
	v_lshl_add_u64 v[202:203], v[224:225], 0, s[46:47]
	s_mov_b32 m0, s26
	s_nop 0
	global_load_lds_dwordx4 v[202:203], off
	v_lshl_add_u64 v[202:203], v[226:227], 0, s[46:47]
	s_add_i32 m0, s26, 0x2000
	s_nop 0
	global_load_lds_dwordx4 v[202:203], off
	v_lshl_add_u64 v[202:203], v[228:229], 0, s[46:47]
	s_mov_b32 m0, s85
	s_nop 0
	global_load_lds_dwordx4 v[202:203], off
	v_lshl_add_u64 v[202:203], v[230:231], 0, s[46:47]
	s_mov_b32 m0, s86
	s_nop 0
	global_load_lds_dwordx4 v[202:203], off
	s_waitcnt vmcnt(8)
	s_waitcnt lgkmcnt(0)
	s_setprio 1
	s_barrier
	v_mfma_f32_16x16x32_bf16 v[60:63], v[138:141], v[186:189], v[60:63]
	v_mfma_f32_16x16x32_bf16 v[56:59], v[160:163], v[186:189], v[56:59]
	v_mfma_f32_16x16x32_bf16 v[44:47], v[138:141], v[194:197], v[44:47]
	v_mfma_f32_16x16x32_bf16 v[40:43], v[160:163], v[194:197], v[40:43]
	v_mfma_f32_16x16x32_bf16 v[28:31], v[138:141], v[206:209], v[28:31]
	v_mfma_f32_16x16x32_bf16 v[24:27], v[160:163], v[206:209], v[24:27]
	v_mfma_f32_16x16x32_bf16 v[12:15], v[138:141], v[214:217], v[12:15]
	v_mfma_f32_16x16x32_bf16 v[8:11], v[160:163], v[214:217], v[8:11]
	v_mfma_f32_16x16x32_bf16 v[60:63], v[156:159], v[190:193], v[60:63]
	v_mfma_f32_16x16x32_bf16 v[56:59], v[166:169], v[190:193], v[56:59]
	v_mfma_f32_16x16x32_bf16 v[44:47], v[156:159], v[198:201], v[44:47]
	v_mfma_f32_16x16x32_bf16 v[40:43], v[166:169], v[198:201], v[40:43]
	v_mfma_f32_16x16x32_bf16 v[28:31], v[156:159], v[210:213], v[28:31]
	v_mfma_f32_16x16x32_bf16 v[24:27], v[166:169], v[210:213], v[24:27]
	v_mfma_f32_16x16x32_bf16 v[12:15], v[156:159], v[218:221], v[12:15]
	v_mfma_f32_16x16x32_bf16 v[8:11], v[166:169], v[218:221], v[8:11]
	v_mfma_f32_16x16x32_bf16 v[52:55], v[170:173], v[186:189], v[52:55]
	v_mfma_f32_16x16x32_bf16 v[48:51], v[178:181], v[186:189], v[48:51]
	v_mfma_f32_16x16x32_bf16 v[36:39], v[170:173], v[194:197], v[36:39]
	v_mfma_f32_16x16x32_bf16 v[32:35], v[178:181], v[194:197], v[32:35]
	v_mfma_f32_16x16x32_bf16 v[20:23], v[170:173], v[206:209], v[20:23]
	v_mfma_f32_16x16x32_bf16 v[16:19], v[178:181], v[206:209], v[16:19]
	v_mfma_f32_16x16x32_bf16 v[4:7], v[170:173], v[214:217], v[4:7]
	v_mfma_f32_16x16x32_bf16 v[0:3], v[178:181], v[214:217], v[0:3]
	v_mfma_f32_16x16x32_bf16 v[52:55], v[174:177], v[190:193], v[52:55]
	v_mfma_f32_16x16x32_bf16 v[48:51], v[182:185], v[190:193], v[48:51]
	v_mfma_f32_16x16x32_bf16 v[36:39], v[174:177], v[198:201], v[36:39]
	v_mfma_f32_16x16x32_bf16 v[32:35], v[182:185], v[198:201], v[32:35]
	v_mfma_f32_16x16x32_bf16 v[20:23], v[174:177], v[210:213], v[20:23]
	v_mfma_f32_16x16x32_bf16 v[16:19], v[182:185], v[210:213], v[16:19]
	v_mfma_f32_16x16x32_bf16 v[4:7], v[174:177], v[218:221], v[4:7]
	v_mfma_f32_16x16x32_bf16 v[0:3], v[182:185], v[218:221], v[0:3]
	s_barrier
	s_setprio 0
	s_add_u32 s91, s91, 0x100
	s_addc_u32 vcc_lo, vcc_lo, 0
	s_add_u32 s22, s22, 0x100
	s_addc_u32 s23, s23, 0
	s_cmp_ge_i32 vcc_hi, s1
	s_mov_b32 s26, vcc_hi
	s_cbranch_scc0 .LBB0_7633
	s_and_b64 vcc, exec, s[50:51]
	s_cbranch_vccz .LBB0_7636
	s_barrier
